# weight-tile DMA loads bypass L1 (sc1) so the co-resident blocks' shared activation tile stays L1-resident
# speedup vs baseline: 1.0001x; 1.0001x over previous
.LBB0_208:
	s_and_b32 s8, s66, 0xffffff80
	s_ashr_i32 s9, s8, 31
	s_lshl_b32 s7, s68, 11
	s_lshl_b64 s[8:9], s[8:9], 11
	s_and_b32 s20, s7, 0xfc0000
	s_add_i32 s2, s2, s3
	s_cmpk_gt_i32 s2, 0xbff
	s_cselect_b64 s[54:55], -1, 0
	s_lshl_b32 s7, s2, 18
	s_and_b32 s7, s7, 0xfc0000
	s_add_u32 s7, s18, s7
	v_lshl_add_u64 v[126:127], v[114:115], 0, s[8:9]
	s_addc_u32 s10, s19, 0
	s_ashr_i32 s8, s2, 6
	s_ashr_i32 s9, s8, 31
	s_lshl_b64 s[8:9], s[8:9], 18
	v_lshl_add_u64 v[128:129], v[116:117], 0, s[20:21]
	s_add_u32 s20, s16, s8
	s_addc_u32 s11, s17, s9
	s_cmpk_lt_i32 s2, 0xc00
	s_cselect_b64 vcc, -1, 0
	s_and_b64 s[8:9], vcc, exec
	s_cselect_b32 s9, s10, 0
	s_cselect_b32 s8, s7, 0
	v_lshl_add_u64 v[2:3], s[8:9], 0, v[118:119]
	v_lshl_add_u64 v[0:1], v[122:123], 0, s[44:45]
	s_cselect_b32 s11, s11, 0
	s_cselect_b32 s10, s20, 0
	v_lshl_add_u64 v[2:3], v[2:3], 0, v[120:121]
	v_cndmask_b32_e32 v97, v1, v3, vcc
	v_cndmask_b32_e32 v98, v0, v2, vcc
	v_lshl_add_u64 v[0:1], s[10:11], 0, v[118:119]
	v_lshl_add_u64 v[0:1], v[0:1], 0, v[120:121]
	v_lshl_add_u64 v[2:3], v[124:125], 0, s[44:45]
	v_cndmask_b32_e32 v142, v2, v0, vcc
	v_mov_b32_e32 v0, 0
	v_lshl_add_u64 v[144:145], v[122:123], 0, s[28:29]
	v_lshl_add_u64 v[130:131], v[122:123], 0, s[30:31]
	v_lshl_add_u64 v[148:149], v[122:123], 0, s[34:35]
	v_lshl_add_u64 v[132:133], v[122:123], 0, s[36:37]
	v_lshl_add_u64 v[150:151], v[122:123], 0, s[38:39]
	v_lshl_add_u64 v[134:135], v[122:123], 0, s[40:41]
	v_lshl_add_u64 v[152:153], v[122:123], 0, s[42:43]
	v_lshl_add_u64 v[146:147], v[124:125], 0, s[28:29]
	v_lshl_add_u64 v[136:137], v[124:125], 0, s[30:31]
	v_lshl_add_u64 v[154:155], v[124:125], 0, s[34:35]
	v_lshl_add_u64 v[138:139], v[124:125], 0, s[36:37]
	v_lshl_add_u64 v[156:157], v[124:125], 0, s[38:39]
	v_lshl_add_u64 v[140:141], v[124:125], 0, s[40:41]
	v_lshl_add_u64 v[158:159], v[124:125], 0, s[42:43]
	v_cndmask_b32_e32 v143, v3, v1, vcc
	s_mov_b32 s7, -2
	v_mov_b32_e32 v1, v0
	v_mov_b32_e32 v2, v0
	v_mov_b32_e32 v3, v0
	v_mov_b32_e32 v20, v0
	v_mov_b32_e32 v21, v0
	v_mov_b32_e32 v22, v0
	v_mov_b32_e32 v23, v0
	v_mov_b32_e32 v24, v0
	v_mov_b32_e32 v25, v0
	v_mov_b32_e32 v26, v0
	v_mov_b32_e32 v27, v0
	v_mov_b32_e32 v32, v0
	v_mov_b32_e32 v33, v0
	v_mov_b32_e32 v34, v0
	v_mov_b32_e32 v35, v0
	v_mov_b32_e32 v8, v0
	v_mov_b32_e32 v9, v0
	v_mov_b32_e32 v10, v0
	v_mov_b32_e32 v11, v0
	v_mov_b32_e32 v4, v0
	v_mov_b32_e32 v5, v0
	v_mov_b32_e32 v6, v0
	v_mov_b32_e32 v7, v0
	v_mov_b32_e32 v12, v0
	v_mov_b32_e32 v13, v0
	v_mov_b32_e32 v14, v0
	v_mov_b32_e32 v15, v0
	v_mov_b32_e32 v16, v0
	v_mov_b32_e32 v17, v0
	v_mov_b32_e32 v18, v0
	v_mov_b32_e32 v19, v0
	v_mov_b32_e32 v28, v0
	v_mov_b32_e32 v29, v0
	v_mov_b32_e32 v30, v0
	v_mov_b32_e32 v31, v0
	v_mov_b32_e32 v36, v0
	v_mov_b32_e32 v37, v0
	v_mov_b32_e32 v38, v0
	v_mov_b32_e32 v39, v0
	v_mov_b32_e32 v40, v0
	v_mov_b32_e32 v41, v0
	v_mov_b32_e32 v42, v0
	v_mov_b32_e32 v43, v0
	v_mov_b32_e32 v44, v0
	v_mov_b32_e32 v45, v0
	v_mov_b32_e32 v46, v0
	v_mov_b32_e32 v47, v0
	v_mov_b32_e32 v48, v0
	v_mov_b32_e32 v49, v0
	v_mov_b32_e32 v50, v0
	v_mov_b32_e32 v51, v0
	v_mov_b32_e32 v52, v0
	v_mov_b32_e32 v53, v0
	v_mov_b32_e32 v54, v0
	v_mov_b32_e32 v55, v0
	v_mov_b32_e32 v56, v0
	v_mov_b32_e32 v57, v0
	v_mov_b32_e32 v58, v0
	v_mov_b32_e32 v59, v0
	v_mov_b32_e32 v60, v0
	v_mov_b32_e32 v61, v0
	v_mov_b32_e32 v62, v0
	v_mov_b32_e32 v63, v0
	v_readfirstlane_b32 s8, v122
	v_readfirstlane_b32 s9, v123
	v_readfirstlane_b32 s62, v124
	v_readfirstlane_b32 s63, v125
	v_readfirstlane_b32 s7, v247
	s_nop 3
	s_mul_i32 s64, s7, 0x4000
	s_sub_u32 s8, s8, s64
	s_subb_u32 s9, s9, 0
	s_sub_u32 s62, s62, s64
	s_subb_u32 s63, s63, 0
	s_lshl_b32 s7, s7, 12
	s_add_u32 m0, s7, 0x0
	v_mov_b32_e32 v60, 0
	global_load_lds_dwordx4 v248, s[8:9]
	v_mov_b32_e32 v61, 0
	s_add_u32 m0, s7, 0x400
	v_mov_b32_e32 v62, 0
	global_load_lds_dwordx4 v249, s[8:9]
	v_mov_b32_e32 v63, 0
	s_add_u32 m0, s7, 0x800
	v_mov_b32_e32 v56, 0
	global_load_lds_dwordx4 v250, s[8:9]
	v_mov_b32_e32 v57, 0
	s_add_u32 m0, s7, 0xc00
	v_mov_b32_e32 v58, 0
	global_load_lds_dwordx4 v251, s[8:9]
	v_mov_b32_e32 v59, 0
	s_add_u32 m0, s7, 0x8000
	v_mov_b32_e32 v52, 0
	global_load_lds_dwordx4 v248, s[62:63] sc1
	v_mov_b32_e32 v53, 0
	s_add_u32 m0, s7, 0x8400
	v_mov_b32_e32 v54, 0
	global_load_lds_dwordx4 v249, s[62:63] sc1
	v_mov_b32_e32 v55, 0
	s_add_u32 m0, s7, 0x8800
	v_mov_b32_e32 v48, 0
	global_load_lds_dwordx4 v250, s[62:63] sc1
	v_mov_b32_e32 v49, 0
	s_add_u32 m0, s7, 0x8c00
	v_mov_b32_e32 v50, 0
	global_load_lds_dwordx4 v251, s[62:63] sc1
	v_mov_b32_e32 v51, 0
	s_add_u32 s8, s8, 0x80
	s_addc_u32 s9, s9, 0
	s_add_u32 s62, s62, 0x80
	s_addc_u32 s63, s63, 0
	s_add_u32 m0, s7, 0x4000
	v_mov_b32_e32 v44, 0
	global_load_lds_dwordx4 v248, s[8:9]
	v_mov_b32_e32 v45, 0
	s_add_u32 m0, s7, 0x4400
	v_mov_b32_e32 v46, 0
	global_load_lds_dwordx4 v249, s[8:9]
	v_mov_b32_e32 v47, 0
	s_add_u32 m0, s7, 0x4800
	v_mov_b32_e32 v40, 0
	global_load_lds_dwordx4 v250, s[8:9]
	v_mov_b32_e32 v41, 0
	s_add_u32 m0, s7, 0x4c00
	v_mov_b32_e32 v42, 0
	global_load_lds_dwordx4 v251, s[8:9]
	v_mov_b32_e32 v43, 0
	s_add_u32 m0, s7, 0xc000
	v_mov_b32_e32 v36, 0
	global_load_lds_dwordx4 v248, s[62:63] sc1
	v_mov_b32_e32 v37, 0
	s_add_u32 m0, s7, 0xc400
	v_mov_b32_e32 v38, 0
	global_load_lds_dwordx4 v249, s[62:63] sc1
	v_mov_b32_e32 v39, 0
	s_add_u32 m0, s7, 0xc800
	v_mov_b32_e32 v28, 0
	global_load_lds_dwordx4 v250, s[62:63] sc1
	v_mov_b32_e32 v29, 0
	s_add_u32 m0, s7, 0xcc00
	v_mov_b32_e32 v30, 0
	global_load_lds_dwordx4 v251, s[62:63] sc1
	v_mov_b32_e32 v31, 0
	s_add_u32 s8, s8, 0x80
	s_addc_u32 s9, s9, 0
	s_add_u32 s62, s62, 0x80
	s_addc_u32 s63, s63, 0
	v_mov_b32_e32 v16, 0
	v_mov_b32_e32 v17, 0
	v_mov_b32_e32 v18, 0
	v_mov_b32_e32 v19, 0
	v_mov_b32_e32 v12, 0
	v_mov_b32_e32 v13, 0
	v_mov_b32_e32 v14, 0
	v_mov_b32_e32 v15, 0
	v_mov_b32_e32 v4, 0
	v_mov_b32_e32 v5, 0
	v_mov_b32_e32 v6, 0
	v_mov_b32_e32 v7, 0
	v_mov_b32_e32 v8, 0
	v_mov_b32_e32 v9, 0
	v_mov_b32_e32 v10, 0
	v_mov_b32_e32 v11, 0
	v_mov_b32_e32 v32, 0
	v_mov_b32_e32 v33, 0
	v_mov_b32_e32 v34, 0
	v_mov_b32_e32 v35, 0
	v_mov_b32_e32 v24, 0
	v_mov_b32_e32 v25, 0
	v_mov_b32_e32 v26, 0
	v_mov_b32_e32 v27, 0
	v_mov_b32_e32 v20, 0
	v_mov_b32_e32 v21, 0
	v_mov_b32_e32 v22, 0
	v_mov_b32_e32 v23, 0
	v_mov_b32_e32 v0, 0
	v_mov_b32_e32 v1, 0
	v_mov_b32_e32 v2, 0
	v_mov_b32_e32 v3, 0
	s_waitcnt vmcnt(8)
	s_barrier
	ds_read_b128 v[80:83], v252 offset:0
	ds_read_b128 v[144:147], v254 offset:32768
	ds_read_b128 v[148:151], v254 offset:34816
	ds_read_b128 v[152:155], v254 offset:36864
	ds_read_b128 v[156:159], v254 offset:38912
	ds_read_b128 v[84:87], v252 offset:2048
	ds_read_b128 v[88:91], v252 offset:4096
	ds_read_b128 v[92:95], v252 offset:6144
	ds_read_b128 v[124:127], v253 offset:0
	ds_read_b128 v[172:175], v255 offset:32768
	ds_read_b128 v[176:179], v255 offset:34816
	ds_read_b128 v[180:183], v255 offset:36864
	ds_read_b128 v[184:187], v255 offset:38912
	s_waitcnt lgkmcnt(11)
	v_mfma_f32_16x16x32_bf16 v[60:63], v[80:83], v[144:147], v[60:63]
	s_waitcnt lgkmcnt(10)
	v_mfma_f32_16x16x32_bf16 v[56:59], v[80:83], v[148:151], v[56:59]
	s_waitcnt lgkmcnt(9)
	v_mfma_f32_16x16x32_bf16 v[52:55], v[80:83], v[152:155], v[52:55]
	s_waitcnt lgkmcnt(8)
	v_mfma_f32_16x16x32_bf16 v[48:51], v[80:83], v[156:159], v[48:51]
	ds_read_b128 v[132:135], v253 offset:2048
	ds_read_b128 v[136:139], v253 offset:4096
	ds_read_b128 v[140:143], v253 offset:6144
	s_waitcnt lgkmcnt(10)
	v_mfma_f32_16x16x32_bf16 v[44:47], v[84:87], v[144:147], v[44:47]
	v_mfma_f32_16x16x32_bf16 v[40:43], v[84:87], v[148:151], v[40:43]
	v_mfma_f32_16x16x32_bf16 v[36:39], v[84:87], v[152:155], v[36:39]
	v_mfma_f32_16x16x32_bf16 v[28:31], v[84:87], v[156:159], v[28:31]
	s_waitcnt lgkmcnt(0)
	s_barrier
	s_add_u32 m0, s7, 0x0
	v_mfma_f32_16x16x32_bf16 v[16:19], v[88:91], v[144:147], v[16:19]
	global_load_lds_dwordx4 v248, s[8:9]
	s_add_u32 m0, s7, 0x400
	v_mfma_f32_16x16x32_bf16 v[12:15], v[88:91], v[148:151], v[12:15]
	global_load_lds_dwordx4 v249, s[8:9]
	s_add_u32 m0, s7, 0x800
	v_mfma_f32_16x16x32_bf16 v[4:7], v[88:91], v[152:155], v[4:7]
	global_load_lds_dwordx4 v250, s[8:9]
	s_add_u32 m0, s7, 0xc00
	v_mfma_f32_16x16x32_bf16 v[8:11], v[88:91], v[156:159], v[8:11]
	global_load_lds_dwordx4 v251, s[8:9]
	s_add_u32 m0, s7, 0x8000
	v_mfma_f32_16x16x32_bf16 v[32:35], v[92:95], v[144:147], v[32:35]
	global_load_lds_dwordx4 v248, s[62:63] sc1
	s_add_u32 m0, s7, 0x8400
	v_mfma_f32_16x16x32_bf16 v[24:27], v[92:95], v[148:151], v[24:27]
	global_load_lds_dwordx4 v249, s[62:63] sc1
	s_add_u32 m0, s7, 0x8800
	v_mfma_f32_16x16x32_bf16 v[20:23], v[92:95], v[152:155], v[20:23]
	global_load_lds_dwordx4 v250, s[62:63] sc1
	s_add_u32 m0, s7, 0x8c00
	v_mfma_f32_16x16x32_bf16 v[0:3], v[92:95], v[156:159], v[0:3]
	global_load_lds_dwordx4 v251, s[62:63] sc1
	s_add_u32 s8, s8, 0x80
	s_addc_u32 s9, s9, 0
	s_add_u32 s62, s62, 0x80
	s_addc_u32 s63, s63, 0
	s_waitcnt vmcnt(8)
	s_barrier
	ds_read_b128 v[80:83], v252 offset:16384
	ds_read_b128 v[144:147], v254 offset:49152
	ds_read_b128 v[148:151], v254 offset:51200
	ds_read_b128 v[152:155], v254 offset:53248
	ds_read_b128 v[156:159], v254 offset:55296
	ds_read_b128 v[84:87], v252 offset:18432
	ds_read_b128 v[88:91], v252 offset:20480
	ds_read_b128 v[92:95], v252 offset:22528
	v_mfma_f32_16x16x32_bf16 v[60:63], v[124:127], v[172:175], v[60:63]
	v_mfma_f32_16x16x32_bf16 v[56:59], v[124:127], v[176:179], v[56:59]
	v_mfma_f32_16x16x32_bf16 v[52:55], v[124:127], v[180:183], v[52:55]
	v_mfma_f32_16x16x32_bf16 v[48:51], v[124:127], v[184:187], v[48:51]
	v_mfma_f32_16x16x32_bf16 v[44:47], v[132:135], v[172:175], v[44:47]
	v_mfma_f32_16x16x32_bf16 v[40:43], v[132:135], v[176:179], v[40:43]
	v_mfma_f32_16x16x32_bf16 v[36:39], v[132:135], v[180:183], v[36:39]
	v_mfma_f32_16x16x32_bf16 v[28:31], v[132:135], v[184:187], v[28:31]
	v_mfma_f32_16x16x32_bf16 v[16:19], v[136:139], v[172:175], v[16:19]
	v_mfma_f32_16x16x32_bf16 v[12:15], v[136:139], v[176:179], v[12:15]
	v_mfma_f32_16x16x32_bf16 v[4:7], v[136:139], v[180:183], v[4:7]
	v_mfma_f32_16x16x32_bf16 v[8:11], v[136:139], v[184:187], v[8:11]
	v_mfma_f32_16x16x32_bf16 v[32:35], v[140:143], v[172:175], v[32:35]
	v_mfma_f32_16x16x32_bf16 v[24:27], v[140:143], v[176:179], v[24:27]
	v_mfma_f32_16x16x32_bf16 v[20:23], v[140:143], v[180:183], v[20:23]
	v_mfma_f32_16x16x32_bf16 v[0:3], v[140:143], v[184:187], v[0:3]
	ds_read_b128 v[124:127], v253 offset:16384
	ds_read_b128 v[172:175], v255 offset:49152
	ds_read_b128 v[176:179], v255 offset:51200
	ds_read_b128 v[180:183], v255 offset:53248
	ds_read_b128 v[184:187], v255 offset:55296
	ds_read_b128 v[132:135], v253 offset:18432
	ds_read_b128 v[136:139], v253 offset:20480
	ds_read_b128 v[140:143], v253 offset:22528
	s_waitcnt lgkmcnt(14)
	v_mfma_f32_16x16x32_bf16 v[60:63], v[80:83], v[144:147], v[60:63]
	s_waitcnt lgkmcnt(13)
	v_mfma_f32_16x16x32_bf16 v[56:59], v[80:83], v[148:151], v[56:59]
	s_waitcnt lgkmcnt(12)
	v_mfma_f32_16x16x32_bf16 v[52:55], v[80:83], v[152:155], v[52:55]
	s_waitcnt lgkmcnt(11)
	v_mfma_f32_16x16x32_bf16 v[48:51], v[80:83], v[156:159], v[48:51]
	s_waitcnt lgkmcnt(10)
	v_mfma_f32_16x16x32_bf16 v[44:47], v[84:87], v[144:147], v[44:47]
	v_mfma_f32_16x16x32_bf16 v[40:43], v[84:87], v[148:151], v[40:43]
	v_mfma_f32_16x16x32_bf16 v[36:39], v[84:87], v[152:155], v[36:39]
	v_mfma_f32_16x16x32_bf16 v[28:31], v[84:87], v[156:159], v[28:31]
	s_waitcnt lgkmcnt(0)
	s_barrier
	s_add_u32 m0, s7, 0x4000
	v_mfma_f32_16x16x32_bf16 v[16:19], v[88:91], v[144:147], v[16:19]
	global_load_lds_dwordx4 v248, s[8:9]
	s_add_u32 m0, s7, 0x4400
	v_mfma_f32_16x16x32_bf16 v[12:15], v[88:91], v[148:151], v[12:15]
	global_load_lds_dwordx4 v249, s[8:9]
	s_add_u32 m0, s7, 0x4800
	v_mfma_f32_16x16x32_bf16 v[4:7], v[88:91], v[152:155], v[4:7]
	global_load_lds_dwordx4 v250, s[8:9]
	s_add_u32 m0, s7, 0x4c00
	v_mfma_f32_16x16x32_bf16 v[8:11], v[88:91], v[156:159], v[8:11]
	global_load_lds_dwordx4 v251, s[8:9]
	s_add_u32 m0, s7, 0xc000
	v_mfma_f32_16x16x32_bf16 v[32:35], v[92:95], v[144:147], v[32:35]
	global_load_lds_dwordx4 v248, s[62:63] sc1
	s_add_u32 m0, s7, 0xc400
	v_mfma_f32_16x16x32_bf16 v[24:27], v[92:95], v[148:151], v[24:27]
	global_load_lds_dwordx4 v249, s[62:63] sc1
	s_add_u32 m0, s7, 0xc800
	v_mfma_f32_16x16x32_bf16 v[20:23], v[92:95], v[152:155], v[20:23]
	global_load_lds_dwordx4 v250, s[62:63] sc1
	s_add_u32 m0, s7, 0xcc00
	v_mfma_f32_16x16x32_bf16 v[0:3], v[92:95], v[156:159], v[0:3]
	global_load_lds_dwordx4 v251, s[62:63] sc1
	s_add_u32 s8, s8, 0x80
	s_addc_u32 s9, s9, 0
	s_add_u32 s62, s62, 0x80
	s_addc_u32 s63, s63, 0
	s_mov_b32 s32, 6
.Lg2_loop:
	s_waitcnt vmcnt(8)
	s_barrier
	ds_read_b128 v[80:83], v252 offset:0
	ds_read_b128 v[144:147], v254 offset:32768
	ds_read_b128 v[148:151], v254 offset:34816
	ds_read_b128 v[152:155], v254 offset:36864
	ds_read_b128 v[156:159], v254 offset:38912
	ds_read_b128 v[84:87], v252 offset:2048
	ds_read_b128 v[88:91], v252 offset:4096
	ds_read_b128 v[92:95], v252 offset:6144
	v_mfma_f32_16x16x32_bf16 v[60:63], v[124:127], v[172:175], v[60:63]
	v_mfma_f32_16x16x32_bf16 v[56:59], v[124:127], v[176:179], v[56:59]
	v_mfma_f32_16x16x32_bf16 v[52:55], v[124:127], v[180:183], v[52:55]
	v_mfma_f32_16x16x32_bf16 v[48:51], v[124:127], v[184:187], v[48:51]
	v_mfma_f32_16x16x32_bf16 v[44:47], v[132:135], v[172:175], v[44:47]
	v_mfma_f32_16x16x32_bf16 v[40:43], v[132:135], v[176:179], v[40:43]
	v_mfma_f32_16x16x32_bf16 v[36:39], v[132:135], v[180:183], v[36:39]
	v_mfma_f32_16x16x32_bf16 v[28:31], v[132:135], v[184:187], v[28:31]
	v_mfma_f32_16x16x32_bf16 v[16:19], v[136:139], v[172:175], v[16:19]
	v_mfma_f32_16x16x32_bf16 v[12:15], v[136:139], v[176:179], v[12:15]
	v_mfma_f32_16x16x32_bf16 v[4:7], v[136:139], v[180:183], v[4:7]
	v_mfma_f32_16x16x32_bf16 v[8:11], v[136:139], v[184:187], v[8:11]
	v_mfma_f32_16x16x32_bf16 v[32:35], v[140:143], v[172:175], v[32:35]
	v_mfma_f32_16x16x32_bf16 v[24:27], v[140:143], v[176:179], v[24:27]
	v_mfma_f32_16x16x32_bf16 v[20:23], v[140:143], v[180:183], v[20:23]
	v_mfma_f32_16x16x32_bf16 v[0:3], v[140:143], v[184:187], v[0:3]
	ds_read_b128 v[124:127], v253 offset:0
	ds_read_b128 v[172:175], v255 offset:32768
	ds_read_b128 v[176:179], v255 offset:34816
	ds_read_b128 v[180:183], v255 offset:36864
	ds_read_b128 v[184:187], v255 offset:38912
	ds_read_b128 v[132:135], v253 offset:2048
	ds_read_b128 v[136:139], v253 offset:4096
	ds_read_b128 v[140:143], v253 offset:6144
	s_waitcnt lgkmcnt(14)
	v_mfma_f32_16x16x32_bf16 v[60:63], v[80:83], v[144:147], v[60:63]
	s_waitcnt lgkmcnt(13)
	v_mfma_f32_16x16x32_bf16 v[56:59], v[80:83], v[148:151], v[56:59]
	s_waitcnt lgkmcnt(12)
	v_mfma_f32_16x16x32_bf16 v[52:55], v[80:83], v[152:155], v[52:55]
	s_waitcnt lgkmcnt(11)
	v_mfma_f32_16x16x32_bf16 v[48:51], v[80:83], v[156:159], v[48:51]
	s_waitcnt lgkmcnt(10)
	v_mfma_f32_16x16x32_bf16 v[44:47], v[84:87], v[144:147], v[44:47]
	v_mfma_f32_16x16x32_bf16 v[40:43], v[84:87], v[148:151], v[40:43]
	v_mfma_f32_16x16x32_bf16 v[36:39], v[84:87], v[152:155], v[36:39]
	v_mfma_f32_16x16x32_bf16 v[28:31], v[84:87], v[156:159], v[28:31]
	s_waitcnt lgkmcnt(0)
	s_barrier
	s_add_u32 m0, s7, 0x0
	v_mfma_f32_16x16x32_bf16 v[16:19], v[88:91], v[144:147], v[16:19]
	global_load_lds_dwordx4 v248, s[8:9]
	s_add_u32 m0, s7, 0x400
	v_mfma_f32_16x16x32_bf16 v[12:15], v[88:91], v[148:151], v[12:15]
	global_load_lds_dwordx4 v249, s[8:9]
	s_add_u32 m0, s7, 0x800
	v_mfma_f32_16x16x32_bf16 v[4:7], v[88:91], v[152:155], v[4:7]
	global_load_lds_dwordx4 v250, s[8:9]
	s_add_u32 m0, s7, 0xc00
	v_mfma_f32_16x16x32_bf16 v[8:11], v[88:91], v[156:159], v[8:11]
	global_load_lds_dwordx4 v251, s[8:9]
	s_add_u32 m0, s7, 0x8000
	v_mfma_f32_16x16x32_bf16 v[32:35], v[92:95], v[144:147], v[32:35]
	global_load_lds_dwordx4 v248, s[62:63] sc1
	s_add_u32 m0, s7, 0x8400
	v_mfma_f32_16x16x32_bf16 v[24:27], v[92:95], v[148:151], v[24:27]
	global_load_lds_dwordx4 v249, s[62:63] sc1
	s_add_u32 m0, s7, 0x8800
	v_mfma_f32_16x16x32_bf16 v[20:23], v[92:95], v[152:155], v[20:23]
	global_load_lds_dwordx4 v250, s[62:63] sc1
	s_add_u32 m0, s7, 0x8c00
	v_mfma_f32_16x16x32_bf16 v[0:3], v[92:95], v[156:159], v[0:3]
	global_load_lds_dwordx4 v251, s[62:63] sc1
	s_add_u32 s8, s8, 0x80
	s_addc_u32 s9, s9, 0
	s_add_u32 s62, s62, 0x80
	s_addc_u32 s63, s63, 0
	s_waitcnt vmcnt(8)
	s_barrier
	ds_read_b128 v[80:83], v252 offset:16384
	ds_read_b128 v[144:147], v254 offset:49152
	ds_read_b128 v[148:151], v254 offset:51200
	ds_read_b128 v[152:155], v254 offset:53248
	ds_read_b128 v[156:159], v254 offset:55296
	ds_read_b128 v[84:87], v252 offset:18432
	ds_read_b128 v[88:91], v252 offset:20480
	ds_read_b128 v[92:95], v252 offset:22528
	v_mfma_f32_16x16x32_bf16 v[60:63], v[124:127], v[172:175], v[60:63]
	v_mfma_f32_16x16x32_bf16 v[56:59], v[124:127], v[176:179], v[56:59]
	v_mfma_f32_16x16x32_bf16 v[52:55], v[124:127], v[180:183], v[52:55]
	v_mfma_f32_16x16x32_bf16 v[48:51], v[124:127], v[184:187], v[48:51]
	v_mfma_f32_16x16x32_bf16 v[44:47], v[132:135], v[172:175], v[44:47]
	v_mfma_f32_16x16x32_bf16 v[40:43], v[132:135], v[176:179], v[40:43]
	v_mfma_f32_16x16x32_bf16 v[36:39], v[132:135], v[180:183], v[36:39]
	v_mfma_f32_16x16x32_bf16 v[28:31], v[132:135], v[184:187], v[28:31]
	v_mfma_f32_16x16x32_bf16 v[16:19], v[136:139], v[172:175], v[16:19]
	v_mfma_f32_16x16x32_bf16 v[12:15], v[136:139], v[176:179], v[12:15]
	v_mfma_f32_16x16x32_bf16 v[4:7], v[136:139], v[180:183], v[4:7]
	v_mfma_f32_16x16x32_bf16 v[8:11], v[136:139], v[184:187], v[8:11]
	v_mfma_f32_16x16x32_bf16 v[32:35], v[140:143], v[172:175], v[32:35]
	v_mfma_f32_16x16x32_bf16 v[24:27], v[140:143], v[176:179], v[24:27]
	v_mfma_f32_16x16x32_bf16 v[20:23], v[140:143], v[180:183], v[20:23]
	v_mfma_f32_16x16x32_bf16 v[0:3], v[140:143], v[184:187], v[0:3]
	ds_read_b128 v[124:127], v253 offset:16384
	ds_read_b128 v[172:175], v255 offset:49152
	ds_read_b128 v[176:179], v255 offset:51200
	ds_read_b128 v[180:183], v255 offset:53248
	ds_read_b128 v[184:187], v255 offset:55296
	ds_read_b128 v[132:135], v253 offset:18432
	ds_read_b128 v[136:139], v253 offset:20480
	ds_read_b128 v[140:143], v253 offset:22528
	s_waitcnt lgkmcnt(14)
	v_mfma_f32_16x16x32_bf16 v[60:63], v[80:83], v[144:147], v[60:63]
	s_waitcnt lgkmcnt(13)
	v_mfma_f32_16x16x32_bf16 v[56:59], v[80:83], v[148:151], v[56:59]
	s_waitcnt lgkmcnt(12)
	v_mfma_f32_16x16x32_bf16 v[52:55], v[80:83], v[152:155], v[52:55]
	s_waitcnt lgkmcnt(11)
	v_mfma_f32_16x16x32_bf16 v[48:51], v[80:83], v[156:159], v[48:51]
	s_waitcnt lgkmcnt(10)
	v_mfma_f32_16x16x32_bf16 v[44:47], v[84:87], v[144:147], v[44:47]
	v_mfma_f32_16x16x32_bf16 v[40:43], v[84:87], v[148:151], v[40:43]
	v_mfma_f32_16x16x32_bf16 v[36:39], v[84:87], v[152:155], v[36:39]
	v_mfma_f32_16x16x32_bf16 v[28:31], v[84:87], v[156:159], v[28:31]
	s_waitcnt lgkmcnt(0)
	s_barrier
	s_add_u32 m0, s7, 0x4000
	v_mfma_f32_16x16x32_bf16 v[16:19], v[88:91], v[144:147], v[16:19]
	global_load_lds_dwordx4 v248, s[8:9]
	s_add_u32 m0, s7, 0x4400
	v_mfma_f32_16x16x32_bf16 v[12:15], v[88:91], v[148:151], v[12:15]
	global_load_lds_dwordx4 v249, s[8:9]
	s_add_u32 m0, s7, 0x4800
	v_mfma_f32_16x16x32_bf16 v[4:7], v[88:91], v[152:155], v[4:7]
	global_load_lds_dwordx4 v250, s[8:9]
	s_add_u32 m0, s7, 0x4c00
	v_mfma_f32_16x16x32_bf16 v[8:11], v[88:91], v[156:159], v[8:11]
	global_load_lds_dwordx4 v251, s[8:9]
	s_add_u32 m0, s7, 0xc000
	v_mfma_f32_16x16x32_bf16 v[32:35], v[92:95], v[144:147], v[32:35]
	global_load_lds_dwordx4 v248, s[62:63] sc1
	s_add_u32 m0, s7, 0xc400
	v_mfma_f32_16x16x32_bf16 v[24:27], v[92:95], v[148:151], v[24:27]
	global_load_lds_dwordx4 v249, s[62:63] sc1
	s_add_u32 m0, s7, 0xc800
	v_mfma_f32_16x16x32_bf16 v[20:23], v[92:95], v[152:155], v[20:23]
	global_load_lds_dwordx4 v250, s[62:63] sc1
	s_add_u32 m0, s7, 0xcc00
	v_mfma_f32_16x16x32_bf16 v[0:3], v[92:95], v[156:159], v[0:3]
	global_load_lds_dwordx4 v251, s[62:63] sc1
	s_add_u32 s8, s8, 0x80
	s_addc_u32 s9, s9, 0
	s_add_u32 s62, s62, 0x80
	s_addc_u32 s63, s63, 0
	s_sub_u32 s32, s32, 1
	s_cmp_lg_u32 s32, 0
	s_cbranch_scc1 .Lg2_loop
	s_waitcnt vmcnt(8)
	s_barrier
	ds_read_b128 v[80:83], v252 offset:0
	ds_read_b128 v[144:147], v254 offset:32768
	ds_read_b128 v[148:151], v254 offset:34816
	ds_read_b128 v[152:155], v254 offset:36864
	ds_read_b128 v[156:159], v254 offset:38912
	ds_read_b128 v[84:87], v252 offset:2048
	ds_read_b128 v[88:91], v252 offset:4096
	ds_read_b128 v[92:95], v252 offset:6144
	v_mfma_f32_16x16x32_bf16 v[60:63], v[124:127], v[172:175], v[60:63]
	v_mfma_f32_16x16x32_bf16 v[56:59], v[124:127], v[176:179], v[56:59]
	v_mfma_f32_16x16x32_bf16 v[52:55], v[124:127], v[180:183], v[52:55]
	v_mfma_f32_16x16x32_bf16 v[48:51], v[124:127], v[184:187], v[48:51]
	v_mfma_f32_16x16x32_bf16 v[44:47], v[132:135], v[172:175], v[44:47]
	v_mfma_f32_16x16x32_bf16 v[40:43], v[132:135], v[176:179], v[40:43]
	v_mfma_f32_16x16x32_bf16 v[36:39], v[132:135], v[180:183], v[36:39]
	v_mfma_f32_16x16x32_bf16 v[28:31], v[132:135], v[184:187], v[28:31]
	v_mfma_f32_16x16x32_bf16 v[16:19], v[136:139], v[172:175], v[16:19]
	v_mfma_f32_16x16x32_bf16 v[12:15], v[136:139], v[176:179], v[12:15]
	v_mfma_f32_16x16x32_bf16 v[4:7], v[136:139], v[180:183], v[4:7]
	v_mfma_f32_16x16x32_bf16 v[8:11], v[136:139], v[184:187], v[8:11]
	v_mfma_f32_16x16x32_bf16 v[32:35], v[140:143], v[172:175], v[32:35]
	v_mfma_f32_16x16x32_bf16 v[24:27], v[140:143], v[176:179], v[24:27]
	v_mfma_f32_16x16x32_bf16 v[20:23], v[140:143], v[180:183], v[20:23]
	v_mfma_f32_16x16x32_bf16 v[0:3], v[140:143], v[184:187], v[0:3]
	ds_read_b128 v[124:127], v253 offset:0
	ds_read_b128 v[172:175], v255 offset:32768
	ds_read_b128 v[176:179], v255 offset:34816
	ds_read_b128 v[180:183], v255 offset:36864
	ds_read_b128 v[184:187], v255 offset:38912
	ds_read_b128 v[132:135], v253 offset:2048
	ds_read_b128 v[136:139], v253 offset:4096
	ds_read_b128 v[140:143], v253 offset:6144
	s_waitcnt lgkmcnt(14)
	v_mfma_f32_16x16x32_bf16 v[60:63], v[80:83], v[144:147], v[60:63]
	s_waitcnt lgkmcnt(13)
	v_mfma_f32_16x16x32_bf16 v[56:59], v[80:83], v[148:151], v[56:59]
	s_waitcnt lgkmcnt(12)
	v_mfma_f32_16x16x32_bf16 v[52:55], v[80:83], v[152:155], v[52:55]
	s_waitcnt lgkmcnt(11)
	v_mfma_f32_16x16x32_bf16 v[48:51], v[80:83], v[156:159], v[48:51]
	s_waitcnt lgkmcnt(10)
	v_mfma_f32_16x16x32_bf16 v[44:47], v[84:87], v[144:147], v[44:47]
	v_mfma_f32_16x16x32_bf16 v[40:43], v[84:87], v[148:151], v[40:43]
	v_mfma_f32_16x16x32_bf16 v[36:39], v[84:87], v[152:155], v[36:39]
	v_mfma_f32_16x16x32_bf16 v[28:31], v[84:87], v[156:159], v[28:31]
	s_waitcnt lgkmcnt(0)
	s_barrier
	v_mfma_f32_16x16x32_bf16 v[16:19], v[88:91], v[144:147], v[16:19]
	v_mfma_f32_16x16x32_bf16 v[12:15], v[88:91], v[148:151], v[12:15]
	v_mfma_f32_16x16x32_bf16 v[4:7], v[88:91], v[152:155], v[4:7]
	v_mfma_f32_16x16x32_bf16 v[8:11], v[88:91], v[156:159], v[8:11]
	v_mfma_f32_16x16x32_bf16 v[32:35], v[92:95], v[144:147], v[32:35]
	v_mfma_f32_16x16x32_bf16 v[24:27], v[92:95], v[148:151], v[24:27]
	v_mfma_f32_16x16x32_bf16 v[20:23], v[92:95], v[152:155], v[20:23]
	v_mfma_f32_16x16x32_bf16 v[0:3], v[92:95], v[156:159], v[0:3]
	s_waitcnt vmcnt(0)
	s_barrier
	ds_read_b128 v[80:83], v252 offset:16384
	ds_read_b128 v[144:147], v254 offset:49152
	ds_read_b128 v[148:151], v254 offset:51200
	ds_read_b128 v[152:155], v254 offset:53248
	ds_read_b128 v[156:159], v254 offset:55296
	ds_read_b128 v[84:87], v252 offset:18432
	ds_read_b128 v[88:91], v252 offset:20480
	ds_read_b128 v[92:95], v252 offset:22528
	v_mfma_f32_16x16x32_bf16 v[60:63], v[124:127], v[172:175], v[60:63]
	v_mfma_f32_16x16x32_bf16 v[56:59], v[124:127], v[176:179], v[56:59]
	v_mfma_f32_16x16x32_bf16 v[52:55], v[124:127], v[180:183], v[52:55]
	v_mfma_f32_16x16x32_bf16 v[48:51], v[124:127], v[184:187], v[48:51]
	v_mfma_f32_16x16x32_bf16 v[44:47], v[132:135], v[172:175], v[44:47]
	v_mfma_f32_16x16x32_bf16 v[40:43], v[132:135], v[176:179], v[40:43]
	v_mfma_f32_16x16x32_bf16 v[36:39], v[132:135], v[180:183], v[36:39]
	v_mfma_f32_16x16x32_bf16 v[28:31], v[132:135], v[184:187], v[28:31]
	v_mfma_f32_16x16x32_bf16 v[16:19], v[136:139], v[172:175], v[16:19]
	v_mfma_f32_16x16x32_bf16 v[12:15], v[136:139], v[176:179], v[12:15]
	v_mfma_f32_16x16x32_bf16 v[4:7], v[136:139], v[180:183], v[4:7]
	v_mfma_f32_16x16x32_bf16 v[8:11], v[136:139], v[184:187], v[8:11]
	v_mfma_f32_16x16x32_bf16 v[32:35], v[140:143], v[172:175], v[32:35]
	v_mfma_f32_16x16x32_bf16 v[24:27], v[140:143], v[176:179], v[24:27]
	v_mfma_f32_16x16x32_bf16 v[20:23], v[140:143], v[180:183], v[20:23]
	v_mfma_f32_16x16x32_bf16 v[0:3], v[140:143], v[184:187], v[0:3]
	ds_read_b128 v[124:127], v253 offset:16384
	ds_read_b128 v[172:175], v255 offset:49152
	ds_read_b128 v[176:179], v255 offset:51200
	ds_read_b128 v[180:183], v255 offset:53248
	ds_read_b128 v[184:187], v255 offset:55296
	ds_read_b128 v[132:135], v253 offset:18432
	ds_read_b128 v[136:139], v253 offset:20480
	ds_read_b128 v[140:143], v253 offset:22528
	s_waitcnt lgkmcnt(14)
	v_mfma_f32_16x16x32_bf16 v[60:63], v[80:83], v[144:147], v[60:63]
	s_waitcnt lgkmcnt(13)
	v_mfma_f32_16x16x32_bf16 v[56:59], v[80:83], v[148:151], v[56:59]
	s_waitcnt lgkmcnt(12)
	v_mfma_f32_16x16x32_bf16 v[52:55], v[80:83], v[152:155], v[52:55]
	s_waitcnt lgkmcnt(11)
	v_mfma_f32_16x16x32_bf16 v[48:51], v[80:83], v[156:159], v[48:51]
	s_waitcnt lgkmcnt(10)
	v_mfma_f32_16x16x32_bf16 v[44:47], v[84:87], v[144:147], v[44:47]
	v_mfma_f32_16x16x32_bf16 v[40:43], v[84:87], v[148:151], v[40:43]
	v_mfma_f32_16x16x32_bf16 v[36:39], v[84:87], v[152:155], v[36:39]
	v_mfma_f32_16x16x32_bf16 v[28:31], v[84:87], v[156:159], v[28:31]
	s_waitcnt lgkmcnt(0)
	s_barrier
	v_mfma_f32_16x16x32_bf16 v[16:19], v[88:91], v[144:147], v[16:19]
	v_mfma_f32_16x16x32_bf16 v[12:15], v[88:91], v[148:151], v[12:15]
	v_mfma_f32_16x16x32_bf16 v[4:7], v[88:91], v[152:155], v[4:7]
	v_mfma_f32_16x16x32_bf16 v[8:11], v[88:91], v[156:159], v[8:11]
	v_mfma_f32_16x16x32_bf16 v[32:35], v[92:95], v[144:147], v[32:35]
	v_mfma_f32_16x16x32_bf16 v[24:27], v[92:95], v[148:151], v[24:27]
	v_mfma_f32_16x16x32_bf16 v[20:23], v[92:95], v[152:155], v[20:23]
	v_mfma_f32_16x16x32_bf16 v[0:3], v[92:95], v[156:159], v[0:3]
	v_mfma_f32_16x16x32_bf16 v[60:63], v[124:127], v[172:175], v[60:63]
	v_mfma_f32_16x16x32_bf16 v[56:59], v[124:127], v[176:179], v[56:59]
	v_mfma_f32_16x16x32_bf16 v[52:55], v[124:127], v[180:183], v[52:55]
	v_mfma_f32_16x16x32_bf16 v[48:51], v[124:127], v[184:187], v[48:51]
	v_mfma_f32_16x16x32_bf16 v[44:47], v[132:135], v[172:175], v[44:47]
	v_mfma_f32_16x16x32_bf16 v[40:43], v[132:135], v[176:179], v[40:43]
	v_mfma_f32_16x16x32_bf16 v[36:39], v[132:135], v[180:183], v[36:39]
	v_mfma_f32_16x16x32_bf16 v[28:31], v[132:135], v[184:187], v[28:31]
	v_mfma_f32_16x16x32_bf16 v[16:19], v[136:139], v[172:175], v[16:19]
	v_mfma_f32_16x16x32_bf16 v[12:15], v[136:139], v[176:179], v[12:15]
	v_mfma_f32_16x16x32_bf16 v[4:7], v[136:139], v[180:183], v[4:7]
	v_mfma_f32_16x16x32_bf16 v[8:11], v[136:139], v[184:187], v[8:11]
	v_mfma_f32_16x16x32_bf16 v[32:35], v[140:143], v[172:175], v[32:35]
	v_mfma_f32_16x16x32_bf16 v[24:27], v[140:143], v[176:179], v[24:27]
	v_mfma_f32_16x16x32_bf16 v[20:23], v[140:143], v[180:183], v[20:23]
	v_mfma_f32_16x16x32_bf16 v[0:3], v[140:143], v[184:187], v[0:3]
	s_nop 7
	s_nop 1
	v_add_u32_e32 v80, s12, v168
	v_or_b32_e32 v64, s6, v169
	s_cmpk_gt_i32 s6, 0x3ff
	s_mov_b64 s[6:7], -1
	s_cbranch_scc0 .LBB0_416
	s_cmpk_gt_u32 s13, 0xbff
	s_cbranch_scc0 .LBB0_413
	s_cmpk_gt_u32 s13, 0x13ff
	s_cbranch_scc0 .LBB0_236
	s_cmpk_gt_u32 s13, 0x17ff
	s_cbranch_scc0 .LBB0_217
	s_and_saveexec_b64 s[6:7], s[4:5]
	s_cbranch_execz .LBB0_216
	v_lshlrev_b32_e32 v98, 7, v80
	v_lshl_add_u64 v[66:67], v[104:105], 0, v[98:99]
	global_store_dword v[66:67], v60, off
	global_store_dword v[66:67], v61, off offset:128
	global_store_dword v[66:67], v62, off offset:256
	global_store_dword v[66:67], v63, off offset:384
	global_store_dword v[66:67], v56, off offset:64
	global_store_dword v[66:67], v57, off offset:192
	global_store_dword v[66:67], v58, off offset:320
	global_store_dword v[66:67], v59, off offset:448
	global_store_dword v[66:67], v44, off offset:2048
	global_store_dword v[66:67], v45, off offset:2176
	global_store_dword v[66:67], v46, off offset:2304
	global_store_dword v[66:67], v47, off offset:2432
	global_store_dword v[66:67], v40, off offset:2112
	global_store_dword v[66:67], v41, off offset:2240
	global_store_dword v[66:67], v42, off offset:2368
	global_store_dword v[66:67], v43, off offset:2496
	v_or_b32_e32 v66, 0x1000, v98
	v_mov_b32_e32 v67, v99
	v_lshl_add_u64 v[68:69], v[104:105], 0, v[66:67]
	global_store_dword v[68:69], v16, off
	v_or_b32_e32 v68, 0x1080, v98
	v_mov_b32_e32 v69, v99
	v_lshl_add_u64 v[70:71], v[104:105], 0, v[68:69]
	global_store_dword v[70:71], v17, off
	v_or_b32_e32 v70, 0x1100, v98
	v_mov_b32_e32 v71, v99
	v_lshl_add_u64 v[66:67], v[106:107], 0, v[66:67]
	v_lshl_add_u64 v[72:73], v[104:105], 0, v[70:71]
	global_store_dword v[66:67], v12, off
	v_lshl_add_u64 v[66:67], v[106:107], 0, v[68:69]
	global_store_dword v[72:73], v18, off
	v_or_b32_e32 v72, 0x1180, v98
	v_mov_b32_e32 v73, v99
	global_store_dword v[66:67], v13, off
	v_lshl_add_u64 v[66:67], v[106:107], 0, v[70:71]
	global_store_dword v[66:67], v14, off
	v_lshl_add_u64 v[66:67], v[106:107], 0, v[72:73]
	global_store_dword v[66:67], v15, off
	v_or_b32_e32 v66, 0x1800, v98
	v_mov_b32_e32 v67, v99
	v_lshl_add_u64 v[68:69], v[104:105], 0, v[66:67]
	global_store_dword v[68:69], v32, off
	v_or_b32_e32 v68, 0x1880, v98
	v_mov_b32_e32 v69, v99
	v_lshl_add_u64 v[70:71], v[104:105], 0, v[68:69]
	v_lshl_add_u64 v[66:67], v[106:107], 0, v[66:67]
	global_store_dword v[70:71], v33, off
	v_or_b32_e32 v70, 0x1900, v98
	v_mov_b32_e32 v71, v99
	global_store_dword v[66:67], v24, off
	v_lshl_add_u64 v[66:67], v[106:107], 0, v[68:69]
	v_lshl_add_u64 v[74:75], v[104:105], 0, v[72:73]
	v_lshl_add_u64 v[72:73], v[104:105], 0, v[70:71]
	v_or_b32_e32 v98, 0x1980, v98
	global_store_dword v[66:67], v25, off
	v_lshl_add_u64 v[66:67], v[106:107], 0, v[70:71]
	global_store_dword v[72:73], v34, off
	v_lshl_add_u64 v[72:73], v[104:105], 0, v[98:99]
	global_store_dword v[66:67], v26, off
	v_lshl_add_u64 v[66:67], v[106:107], 0, v[98:99]
	global_store_dword v[74:75], v19, off
	global_store_dword v[72:73], v35, off
	global_store_dword v[66:67], v27, off

.Lr6_tile:
	s_cmp_lt_u32 s15, 0x200
	s_cbranch_scc0 .Lr6_end
	s_and_b32 s2, s15, 63
	s_lshr_b32 s3, s15, 6
	s_mul_i32 s14, s2, 0x80000
	s_add_u32 s8, s26, s14
	s_addc_u32 s9, s27, 0
	s_mul_i32 s14, s3, 0x80000
	s_add_u32 s10, s28, s14
	s_addc_u32 s11, s29, 0
	s_lshl_b32 s14, s2, 19
	s_lshl_b32 s6, s3, 9
	s_add_u32 s14, s14, s6
	s_add_u32 s20, s4, 0x6b7a100
	s_addc_u32 s21, s5, 0
	s_add_u32 s20, s20, s14
	s_addc_u32 s21, s21, 0
	s_sub_u32 s7, s2, 32
	s_lshr_b32 s7, s7, 3
	s_add_u32 s7, s7, 1
	s_cmp_lt_u32 s2, 32
	s_cselect_b32 s7, 0, s7
	s_mul_i32 s7, s7, 0x6000
	s_add_u32 s7, s7, s6
	s_add_u32 s22, s4, 0x6b04000
	s_addc_u32 s23, s5, 0
	s_add_u32 s22, s22, s7
	s_addc_u32 s23, s23, 0
	v_readfirstlane_b32 s12, v247
	s_lshl_b32 s12, s12, 12
	s_add_u32 m0, s12, 0x0
	v_mov_b32_e32 v0, 0
	global_load_lds_dwordx4 v248, s[8:9]
	v_mov_b32_e32 v1, 0
	s_add_u32 m0, s12, 0x400
	v_mov_b32_e32 v2, 0
	global_load_lds_dwordx4 v249, s[8:9]
	v_mov_b32_e32 v3, 0
	s_add_u32 m0, s12, 0x800
	v_mov_b32_e32 v4, 0
	global_load_lds_dwordx4 v250, s[8:9]
	v_mov_b32_e32 v5, 0
	s_add_u32 m0, s12, 0xc00
	v_mov_b32_e32 v6, 0
	global_load_lds_dwordx4 v251, s[8:9]
	v_mov_b32_e32 v7, 0
	s_add_u32 m0, s12, 0x8000
	v_mov_b32_e32 v8, 0
	global_load_lds_dwordx4 v248, s[10:11] sc1
	v_mov_b32_e32 v9, 0
	s_add_u32 m0, s12, 0x8400
	v_mov_b32_e32 v10, 0
	global_load_lds_dwordx4 v249, s[10:11] sc1
	v_mov_b32_e32 v11, 0
	s_add_u32 m0, s12, 0x8800
	v_mov_b32_e32 v12, 0
	global_load_lds_dwordx4 v250, s[10:11] sc1
	v_mov_b32_e32 v13, 0
	s_add_u32 m0, s12, 0x8c00
	v_mov_b32_e32 v14, 0
	global_load_lds_dwordx4 v251, s[10:11] sc1
	v_mov_b32_e32 v15, 0
	s_add_u32 s8, s8, 0x80
	s_addc_u32 s9, s9, 0
	s_add_u32 s10, s10, 0x80
	s_addc_u32 s11, s11, 0
	s_add_u32 m0, s12, 0x4000
	v_mov_b32_e32 v16, 0
	global_load_lds_dwordx4 v248, s[8:9]
	v_mov_b32_e32 v17, 0
	s_add_u32 m0, s12, 0x4400
	v_mov_b32_e32 v18, 0
	global_load_lds_dwordx4 v249, s[8:9]
	v_mov_b32_e32 v19, 0
	s_add_u32 m0, s12, 0x4800
	v_mov_b32_e32 v20, 0
	global_load_lds_dwordx4 v250, s[8:9]
	v_mov_b32_e32 v21, 0
	s_add_u32 m0, s12, 0x4c00
	v_mov_b32_e32 v22, 0
	global_load_lds_dwordx4 v251, s[8:9]
	v_mov_b32_e32 v23, 0
	s_add_u32 m0, s12, 0xc000
	v_mov_b32_e32 v24, 0
	global_load_lds_dwordx4 v248, s[10:11] sc1
	v_mov_b32_e32 v25, 0
	s_add_u32 m0, s12, 0xc400
	v_mov_b32_e32 v26, 0
	global_load_lds_dwordx4 v249, s[10:11] sc1
	v_mov_b32_e32 v27, 0
	s_add_u32 m0, s12, 0xc800
	v_mov_b32_e32 v28, 0
	global_load_lds_dwordx4 v250, s[10:11] sc1
	v_mov_b32_e32 v29, 0
	s_add_u32 m0, s12, 0xcc00
	v_mov_b32_e32 v30, 0
	global_load_lds_dwordx4 v251, s[10:11] sc1
	v_mov_b32_e32 v31, 0
	s_add_u32 s8, s8, 0x80
	s_addc_u32 s9, s9, 0
	s_add_u32 s10, s10, 0x80
	s_addc_u32 s11, s11, 0
	v_mov_b32_e32 v32, 0
	v_mov_b32_e32 v33, 0
	v_mov_b32_e32 v34, 0
	v_mov_b32_e32 v35, 0
	v_mov_b32_e32 v36, 0
	v_mov_b32_e32 v37, 0
	v_mov_b32_e32 v38, 0
	v_mov_b32_e32 v39, 0
	v_mov_b32_e32 v40, 0
	v_mov_b32_e32 v41, 0
	v_mov_b32_e32 v42, 0
	v_mov_b32_e32 v43, 0
	v_mov_b32_e32 v44, 0
	v_mov_b32_e32 v45, 0
	v_mov_b32_e32 v46, 0
	v_mov_b32_e32 v47, 0
	v_mov_b32_e32 v48, 0
	v_mov_b32_e32 v49, 0
	v_mov_b32_e32 v50, 0
	v_mov_b32_e32 v51, 0
	v_mov_b32_e32 v52, 0
	v_mov_b32_e32 v53, 0
	v_mov_b32_e32 v54, 0
	v_mov_b32_e32 v55, 0
	v_mov_b32_e32 v56, 0
	v_mov_b32_e32 v57, 0
	v_mov_b32_e32 v58, 0
	v_mov_b32_e32 v59, 0
	v_mov_b32_e32 v60, 0
	v_mov_b32_e32 v61, 0
	v_mov_b32_e32 v62, 0
	v_mov_b32_e32 v63, 0
	global_load_dword v201, v245, s[22:23] offset:0
	global_load_dword v202, v245, s[22:23] offset:64
	global_load_dword v203, v245, s[22:23] offset:128
	global_load_dword v204, v245, s[22:23] offset:192
	s_load_dwordx4 s[36:39], s[0:1], 0x0
	s_sub_u32 s7, s2, 32
	s_cmp_lt_u32 s2, 32
	s_cselect_b32 s7, s2, s7
	s_lshl_b32 s7, s7, 19
	s_add_u32 s7, s7, s6
	s_waitcnt lgkmcnt(0)
	s_cmp_lt_u32 s2, 32
	s_cselect_b32 s18, s36, s38
	s_cselect_b32 s19, s37, s39
	s_add_u32 s18, s18, s7
	s_addc_u32 s19, s19, 0
	global_load_dword v129, v246, s[18:19] offset:0
	global_load_dword v130, v246, s[18:19] offset:64
	global_load_dword v131, v246, s[18:19] offset:128
	global_load_dword v132, v246, s[18:19] offset:192
	s_add_u32 s18, s18, 0x1000
	s_addc_u32 s19, s19, 0
	global_load_dword v133, v246, s[18:19] offset:0
	global_load_dword v134, v246, s[18:19] offset:64
	global_load_dword v135, v246, s[18:19] offset:128
	global_load_dword v136, v246, s[18:19] offset:192
	s_add_u32 s18, s18, 0x1000
	s_addc_u32 s19, s19, 0
	global_load_dword v137, v246, s[18:19] offset:0
	global_load_dword v138, v246, s[18:19] offset:64
	global_load_dword v139, v246, s[18:19] offset:128
	global_load_dword v140, v246, s[18:19] offset:192
	s_add_u32 s18, s18, 0x1000
	s_addc_u32 s19, s19, 0
	global_load_dword v141, v246, s[18:19] offset:0
	global_load_dword v142, v246, s[18:19] offset:64
	global_load_dword v143, v246, s[18:19] offset:128
	global_load_dword v144, v246, s[18:19] offset:192
	s_add_u32 s18, s18, 0xd000
	s_addc_u32 s19, s19, 0
	global_load_dword v145, v246, s[18:19] offset:0
	global_load_dword v146, v246, s[18:19] offset:64
	global_load_dword v147, v246, s[18:19] offset:128
	global_load_dword v148, v246, s[18:19] offset:192
	s_add_u32 s18, s18, 0x1000
	s_addc_u32 s19, s19, 0
	global_load_dword v149, v246, s[18:19] offset:0
	global_load_dword v150, v246, s[18:19] offset:64
	global_load_dword v151, v246, s[18:19] offset:128
	global_load_dword v152, v246, s[18:19] offset:192
	s_add_u32 s18, s18, 0x1000
	s_addc_u32 s19, s19, 0
	global_load_dword v153, v246, s[18:19] offset:0
	global_load_dword v154, v246, s[18:19] offset:64
	global_load_dword v155, v246, s[18:19] offset:128
	global_load_dword v156, v246, s[18:19] offset:192
	s_add_u32 s18, s18, 0x1000
	s_addc_u32 s19, s19, 0
	global_load_dword v157, v246, s[18:19] offset:0
	global_load_dword v158, v246, s[18:19] offset:64
	global_load_dword v159, v246, s[18:19] offset:128
	global_load_dword v160, v246, s[18:19] offset:192
	s_add_u32 s18, s18, 0xd000
	s_addc_u32 s19, s19, 0
	global_load_dword v161, v246, s[18:19] offset:0
	global_load_dword v170, v246, s[18:19] offset:64
	global_load_dword v171, v246, s[18:19] offset:128
	global_load_dword v172, v246, s[18:19] offset:192
	s_add_u32 s18, s18, 0x1000
	s_addc_u32 s19, s19, 0
	global_load_dword v173, v246, s[18:19] offset:0
	global_load_dword v174, v246, s[18:19] offset:64
	global_load_dword v175, v246, s[18:19] offset:128
	global_load_dword v176, v246, s[18:19] offset:192
	s_add_u32 s18, s18, 0x1000
	s_addc_u32 s19, s19, 0
	global_load_dword v177, v246, s[18:19] offset:0
	global_load_dword v178, v246, s[18:19] offset:64
	global_load_dword v179, v246, s[18:19] offset:128
	global_load_dword v180, v246, s[18:19] offset:192
	s_add_u32 s18, s18, 0x1000
	s_addc_u32 s19, s19, 0
	global_load_dword v181, v246, s[18:19] offset:0
	global_load_dword v182, v246, s[18:19] offset:64
	global_load_dword v183, v246, s[18:19] offset:128
	global_load_dword v184, v246, s[18:19] offset:192
	s_add_u32 s18, s18, 0xd000
	s_addc_u32 s19, s19, 0
	global_load_dword v185, v246, s[18:19] offset:0
	global_load_dword v186, v246, s[18:19] offset:64
	global_load_dword v187, v246, s[18:19] offset:128
	global_load_dword v188, v246, s[18:19] offset:192
	s_add_u32 s18, s18, 0x1000
	s_addc_u32 s19, s19, 0
	global_load_dword v189, v246, s[18:19] offset:0
	global_load_dword v190, v246, s[18:19] offset:64
	global_load_dword v191, v246, s[18:19] offset:128
	global_load_dword v192, v246, s[18:19] offset:192
	s_add_u32 s18, s18, 0x1000
	s_addc_u32 s19, s19, 0
	global_load_dword v193, v246, s[18:19] offset:0
	global_load_dword v194, v246, s[18:19] offset:64
	global_load_dword v195, v246, s[18:19] offset:128
	global_load_dword v196, v246, s[18:19] offset:192
	s_add_u32 s18, s18, 0x1000
	s_addc_u32 s19, s19, 0
	global_load_dword v197, v246, s[18:19] offset:0
	global_load_dword v198, v246, s[18:19] offset:64
	global_load_dword v199, v246, s[18:19] offset:128
	global_load_dword v200, v246, s[18:19] offset:192
	s_waitcnt vmcnt(63)
	s_barrier
	ds_read_b128 v[64:67], v252 offset:0
	ds_read_b128 v[96:99], v254 offset:32768
	ds_read_b128 v[100:103], v254 offset:34816
	ds_read_b128 v[104:107], v254 offset:36864
	ds_read_b128 v[108:111], v254 offset:38912
	ds_read_b128 v[68:71], v252 offset:2048
	ds_read_b128 v[72:75], v252 offset:4096
	ds_read_b128 v[76:79], v252 offset:6144
	ds_read_b128 v[80:83], v253 offset:0
	ds_read_b128 v[112:115], v255 offset:32768
	ds_read_b128 v[116:119], v255 offset:34816
	ds_read_b128 v[120:123], v255 offset:36864
	ds_read_b128 v[124:127], v255 offset:38912
	s_waitcnt lgkmcnt(11)
	v_mfma_f32_16x16x32_bf16 v[0:3], v[64:67], v[96:99], v[0:3]
	s_waitcnt lgkmcnt(10)
	v_mfma_f32_16x16x32_bf16 v[4:7], v[64:67], v[100:103], v[4:7]
	s_waitcnt lgkmcnt(9)
	v_mfma_f32_16x16x32_bf16 v[8:11], v[64:67], v[104:107], v[8:11]
	s_waitcnt lgkmcnt(8)
	v_mfma_f32_16x16x32_bf16 v[12:15], v[64:67], v[108:111], v[12:15]
	ds_read_b128 v[84:87], v253 offset:2048
	ds_read_b128 v[88:91], v253 offset:4096
	ds_read_b128 v[92:95], v253 offset:6144
	s_waitcnt lgkmcnt(10)
	v_mfma_f32_16x16x32_bf16 v[16:19], v[68:71], v[96:99], v[16:19]
	v_mfma_f32_16x16x32_bf16 v[20:23], v[68:71], v[100:103], v[20:23]
	v_mfma_f32_16x16x32_bf16 v[24:27], v[68:71], v[104:107], v[24:27]
	v_mfma_f32_16x16x32_bf16 v[28:31], v[68:71], v[108:111], v[28:31]
	s_waitcnt lgkmcnt(0)
	s_barrier
	s_add_u32 m0, s12, 0x0
	v_mfma_f32_16x16x32_bf16 v[32:35], v[72:75], v[96:99], v[32:35]
	global_load_lds_dwordx4 v248, s[8:9]
	s_add_u32 m0, s12, 0x400
	v_mfma_f32_16x16x32_bf16 v[36:39], v[72:75], v[100:103], v[36:39]
	global_load_lds_dwordx4 v249, s[8:9]
	s_add_u32 m0, s12, 0x800
	v_mfma_f32_16x16x32_bf16 v[40:43], v[72:75], v[104:107], v[40:43]
	global_load_lds_dwordx4 v250, s[8:9]
	s_add_u32 m0, s12, 0xc00
	v_mfma_f32_16x16x32_bf16 v[44:47], v[72:75], v[108:111], v[44:47]
	global_load_lds_dwordx4 v251, s[8:9]
	s_add_u32 m0, s12, 0x8000
	v_mfma_f32_16x16x32_bf16 v[48:51], v[76:79], v[96:99], v[48:51]
	global_load_lds_dwordx4 v248, s[10:11] sc1
	s_add_u32 m0, s12, 0x8400
	v_mfma_f32_16x16x32_bf16 v[52:55], v[76:79], v[100:103], v[52:55]
	global_load_lds_dwordx4 v249, s[10:11] sc1
	s_add_u32 m0, s12, 0x8800
	v_mfma_f32_16x16x32_bf16 v[56:59], v[76:79], v[104:107], v[56:59]
	global_load_lds_dwordx4 v250, s[10:11] sc1
	s_add_u32 m0, s12, 0x8c00
	v_mfma_f32_16x16x32_bf16 v[60:63], v[76:79], v[108:111], v[60:63]
	global_load_lds_dwordx4 v251, s[10:11] sc1
	s_add_u32 s8, s8, 0x80
	s_addc_u32 s9, s9, 0
	s_add_u32 s10, s10, 0x80
	s_addc_u32 s11, s11, 0
	s_waitcnt vmcnt(63)
	s_barrier
	ds_read_b128 v[64:67], v252 offset:16384
	ds_read_b128 v[96:99], v254 offset:49152
	ds_read_b128 v[100:103], v254 offset:51200
	ds_read_b128 v[104:107], v254 offset:53248
	ds_read_b128 v[108:111], v254 offset:55296
	ds_read_b128 v[68:71], v252 offset:18432
	ds_read_b128 v[72:75], v252 offset:20480
	ds_read_b128 v[76:79], v252 offset:22528
	v_mfma_f32_16x16x32_bf16 v[0:3], v[80:83], v[112:115], v[0:3]
	v_mfma_f32_16x16x32_bf16 v[4:7], v[80:83], v[116:119], v[4:7]
	v_mfma_f32_16x16x32_bf16 v[8:11], v[80:83], v[120:123], v[8:11]
	v_mfma_f32_16x16x32_bf16 v[12:15], v[80:83], v[124:127], v[12:15]
	v_mfma_f32_16x16x32_bf16 v[16:19], v[84:87], v[112:115], v[16:19]
	v_mfma_f32_16x16x32_bf16 v[20:23], v[84:87], v[116:119], v[20:23]
	v_mfma_f32_16x16x32_bf16 v[24:27], v[84:87], v[120:123], v[24:27]
	v_mfma_f32_16x16x32_bf16 v[28:31], v[84:87], v[124:127], v[28:31]
	v_mfma_f32_16x16x32_bf16 v[32:35], v[88:91], v[112:115], v[32:35]
	v_mfma_f32_16x16x32_bf16 v[36:39], v[88:91], v[116:119], v[36:39]
	v_mfma_f32_16x16x32_bf16 v[40:43], v[88:91], v[120:123], v[40:43]
	v_mfma_f32_16x16x32_bf16 v[44:47], v[88:91], v[124:127], v[44:47]
	v_mfma_f32_16x16x32_bf16 v[48:51], v[92:95], v[112:115], v[48:51]
	v_mfma_f32_16x16x32_bf16 v[52:55], v[92:95], v[116:119], v[52:55]
	v_mfma_f32_16x16x32_bf16 v[56:59], v[92:95], v[120:123], v[56:59]
	v_mfma_f32_16x16x32_bf16 v[60:63], v[92:95], v[124:127], v[60:63]
	ds_read_b128 v[80:83], v253 offset:16384
	ds_read_b128 v[112:115], v255 offset:49152
	ds_read_b128 v[116:119], v255 offset:51200
	ds_read_b128 v[120:123], v255 offset:53248
	ds_read_b128 v[124:127], v255 offset:55296
	ds_read_b128 v[84:87], v253 offset:18432
	ds_read_b128 v[88:91], v253 offset:20480
	ds_read_b128 v[92:95], v253 offset:22528
	s_waitcnt lgkmcnt(14)
	v_mfma_f32_16x16x32_bf16 v[0:3], v[64:67], v[96:99], v[0:3]
	s_waitcnt lgkmcnt(13)
	v_mfma_f32_16x16x32_bf16 v[4:7], v[64:67], v[100:103], v[4:7]
	s_waitcnt lgkmcnt(12)
	v_mfma_f32_16x16x32_bf16 v[8:11], v[64:67], v[104:107], v[8:11]
	s_waitcnt lgkmcnt(11)
	v_mfma_f32_16x16x32_bf16 v[12:15], v[64:67], v[108:111], v[12:15]
	s_waitcnt lgkmcnt(10)
	v_mfma_f32_16x16x32_bf16 v[16:19], v[68:71], v[96:99], v[16:19]
	v_mfma_f32_16x16x32_bf16 v[20:23], v[68:71], v[100:103], v[20:23]
	v_mfma_f32_16x16x32_bf16 v[24:27], v[68:71], v[104:107], v[24:27]
	v_mfma_f32_16x16x32_bf16 v[28:31], v[68:71], v[108:111], v[28:31]
	s_waitcnt lgkmcnt(0)
	s_barrier
	s_add_u32 m0, s12, 0x4000
	v_mfma_f32_16x16x32_bf16 v[32:35], v[72:75], v[96:99], v[32:35]
	global_load_lds_dwordx4 v248, s[8:9]
	s_add_u32 m0, s12, 0x4400
	v_mfma_f32_16x16x32_bf16 v[36:39], v[72:75], v[100:103], v[36:39]
	global_load_lds_dwordx4 v249, s[8:9]
	s_add_u32 m0, s12, 0x4800
	v_mfma_f32_16x16x32_bf16 v[40:43], v[72:75], v[104:107], v[40:43]
	global_load_lds_dwordx4 v250, s[8:9]
	s_add_u32 m0, s12, 0x4c00
	v_mfma_f32_16x16x32_bf16 v[44:47], v[72:75], v[108:111], v[44:47]
	global_load_lds_dwordx4 v251, s[8:9]
	s_add_u32 m0, s12, 0xc000
	v_mfma_f32_16x16x32_bf16 v[48:51], v[76:79], v[96:99], v[48:51]
	global_load_lds_dwordx4 v248, s[10:11] sc1
	s_add_u32 m0, s12, 0xc400
	v_mfma_f32_16x16x32_bf16 v[52:55], v[76:79], v[100:103], v[52:55]
	global_load_lds_dwordx4 v249, s[10:11] sc1
	s_add_u32 m0, s12, 0xc800
	v_mfma_f32_16x16x32_bf16 v[56:59], v[76:79], v[104:107], v[56:59]
	global_load_lds_dwordx4 v250, s[10:11] sc1
	s_add_u32 m0, s12, 0xcc00
	v_mfma_f32_16x16x32_bf16 v[60:63], v[76:79], v[108:111], v[60:63]
	global_load_lds_dwordx4 v251, s[10:11] sc1
	s_add_u32 s8, s8, 0x80
	s_addc_u32 s9, s9, 0
	s_add_u32 s10, s10, 0x80
	s_addc_u32 s11, s11, 0
	s_mov_b32 s13, 14
.Lr6_loop:
	s_waitcnt vmcnt(8)
	s_barrier
	ds_read_b128 v[64:67], v252 offset:0
	ds_read_b128 v[96:99], v254 offset:32768
	ds_read_b128 v[100:103], v254 offset:34816
	ds_read_b128 v[104:107], v254 offset:36864
	ds_read_b128 v[108:111], v254 offset:38912
	ds_read_b128 v[68:71], v252 offset:2048
	ds_read_b128 v[72:75], v252 offset:4096
	ds_read_b128 v[76:79], v252 offset:6144
	v_mfma_f32_16x16x32_bf16 v[0:3], v[80:83], v[112:115], v[0:3]
	v_mfma_f32_16x16x32_bf16 v[4:7], v[80:83], v[116:119], v[4:7]
	v_mfma_f32_16x16x32_bf16 v[8:11], v[80:83], v[120:123], v[8:11]
	v_mfma_f32_16x16x32_bf16 v[12:15], v[80:83], v[124:127], v[12:15]
	v_mfma_f32_16x16x32_bf16 v[16:19], v[84:87], v[112:115], v[16:19]
	v_mfma_f32_16x16x32_bf16 v[20:23], v[84:87], v[116:119], v[20:23]
	v_mfma_f32_16x16x32_bf16 v[24:27], v[84:87], v[120:123], v[24:27]
	v_mfma_f32_16x16x32_bf16 v[28:31], v[84:87], v[124:127], v[28:31]
	v_mfma_f32_16x16x32_bf16 v[32:35], v[88:91], v[112:115], v[32:35]
	v_mfma_f32_16x16x32_bf16 v[36:39], v[88:91], v[116:119], v[36:39]
	v_mfma_f32_16x16x32_bf16 v[40:43], v[88:91], v[120:123], v[40:43]
	v_mfma_f32_16x16x32_bf16 v[44:47], v[88:91], v[124:127], v[44:47]
	v_mfma_f32_16x16x32_bf16 v[48:51], v[92:95], v[112:115], v[48:51]
	v_mfma_f32_16x16x32_bf16 v[52:55], v[92:95], v[116:119], v[52:55]
	v_mfma_f32_16x16x32_bf16 v[56:59], v[92:95], v[120:123], v[56:59]
	v_mfma_f32_16x16x32_bf16 v[60:63], v[92:95], v[124:127], v[60:63]
	ds_read_b128 v[80:83], v253 offset:0
	ds_read_b128 v[112:115], v255 offset:32768
	ds_read_b128 v[116:119], v255 offset:34816
	ds_read_b128 v[120:123], v255 offset:36864
	ds_read_b128 v[124:127], v255 offset:38912
	ds_read_b128 v[84:87], v253 offset:2048
	ds_read_b128 v[88:91], v253 offset:4096
	ds_read_b128 v[92:95], v253 offset:6144
	s_waitcnt lgkmcnt(14)
	v_mfma_f32_16x16x32_bf16 v[0:3], v[64:67], v[96:99], v[0:3]
	s_waitcnt lgkmcnt(13)
	v_mfma_f32_16x16x32_bf16 v[4:7], v[64:67], v[100:103], v[4:7]
	s_waitcnt lgkmcnt(12)
	v_mfma_f32_16x16x32_bf16 v[8:11], v[64:67], v[104:107], v[8:11]
	s_waitcnt lgkmcnt(11)
	v_mfma_f32_16x16x32_bf16 v[12:15], v[64:67], v[108:111], v[12:15]
	s_waitcnt lgkmcnt(10)
	v_mfma_f32_16x16x32_bf16 v[16:19], v[68:71], v[96:99], v[16:19]
	v_mfma_f32_16x16x32_bf16 v[20:23], v[68:71], v[100:103], v[20:23]
	v_mfma_f32_16x16x32_bf16 v[24:27], v[68:71], v[104:107], v[24:27]
	v_mfma_f32_16x16x32_bf16 v[28:31], v[68:71], v[108:111], v[28:31]
	s_waitcnt lgkmcnt(0)
	s_barrier
	s_add_u32 m0, s12, 0x0
	v_mfma_f32_16x16x32_bf16 v[32:35], v[72:75], v[96:99], v[32:35]
	global_load_lds_dwordx4 v248, s[8:9]
	s_add_u32 m0, s12, 0x400
	v_mfma_f32_16x16x32_bf16 v[36:39], v[72:75], v[100:103], v[36:39]
	global_load_lds_dwordx4 v249, s[8:9]
	s_add_u32 m0, s12, 0x800
	v_mfma_f32_16x16x32_bf16 v[40:43], v[72:75], v[104:107], v[40:43]
	global_load_lds_dwordx4 v250, s[8:9]
	s_add_u32 m0, s12, 0xc00
	v_mfma_f32_16x16x32_bf16 v[44:47], v[72:75], v[108:111], v[44:47]
	global_load_lds_dwordx4 v251, s[8:9]
	s_add_u32 m0, s12, 0x8000
	v_mfma_f32_16x16x32_bf16 v[48:51], v[76:79], v[96:99], v[48:51]
	global_load_lds_dwordx4 v248, s[10:11] sc1
	s_add_u32 m0, s12, 0x8400
	v_mfma_f32_16x16x32_bf16 v[52:55], v[76:79], v[100:103], v[52:55]
	global_load_lds_dwordx4 v249, s[10:11] sc1
	s_add_u32 m0, s12, 0x8800
	v_mfma_f32_16x16x32_bf16 v[56:59], v[76:79], v[104:107], v[56:59]
	global_load_lds_dwordx4 v250, s[10:11] sc1
	s_add_u32 m0, s12, 0x8c00
	v_mfma_f32_16x16x32_bf16 v[60:63], v[76:79], v[108:111], v[60:63]
	global_load_lds_dwordx4 v251, s[10:11] sc1
	s_add_u32 s8, s8, 0x80
	s_addc_u32 s9, s9, 0
	s_add_u32 s10, s10, 0x80
	s_addc_u32 s11, s11, 0
	s_waitcnt vmcnt(8)
	s_barrier
	ds_read_b128 v[64:67], v252 offset:16384
	ds_read_b128 v[96:99], v254 offset:49152
	ds_read_b128 v[100:103], v254 offset:51200
	ds_read_b128 v[104:107], v254 offset:53248
	ds_read_b128 v[108:111], v254 offset:55296
	ds_read_b128 v[68:71], v252 offset:18432
	ds_read_b128 v[72:75], v252 offset:20480
	ds_read_b128 v[76:79], v252 offset:22528
	v_mfma_f32_16x16x32_bf16 v[0:3], v[80:83], v[112:115], v[0:3]
	v_mfma_f32_16x16x32_bf16 v[4:7], v[80:83], v[116:119], v[4:7]
	v_mfma_f32_16x16x32_bf16 v[8:11], v[80:83], v[120:123], v[8:11]
	v_mfma_f32_16x16x32_bf16 v[12:15], v[80:83], v[124:127], v[12:15]
	v_mfma_f32_16x16x32_bf16 v[16:19], v[84:87], v[112:115], v[16:19]
	v_mfma_f32_16x16x32_bf16 v[20:23], v[84:87], v[116:119], v[20:23]
	v_mfma_f32_16x16x32_bf16 v[24:27], v[84:87], v[120:123], v[24:27]
	v_mfma_f32_16x16x32_bf16 v[28:31], v[84:87], v[124:127], v[28:31]
	v_mfma_f32_16x16x32_bf16 v[32:35], v[88:91], v[112:115], v[32:35]
	v_mfma_f32_16x16x32_bf16 v[36:39], v[88:91], v[116:119], v[36:39]
	v_mfma_f32_16x16x32_bf16 v[40:43], v[88:91], v[120:123], v[40:43]
	v_mfma_f32_16x16x32_bf16 v[44:47], v[88:91], v[124:127], v[44:47]
	v_mfma_f32_16x16x32_bf16 v[48:51], v[92:95], v[112:115], v[48:51]
	v_mfma_f32_16x16x32_bf16 v[52:55], v[92:95], v[116:119], v[52:55]
	v_mfma_f32_16x16x32_bf16 v[56:59], v[92:95], v[120:123], v[56:59]
	v_mfma_f32_16x16x32_bf16 v[60:63], v[92:95], v[124:127], v[60:63]
	ds_read_b128 v[80:83], v253 offset:16384
	ds_read_b128 v[112:115], v255 offset:49152
	ds_read_b128 v[116:119], v255 offset:51200
	ds_read_b128 v[120:123], v255 offset:53248
	ds_read_b128 v[124:127], v255 offset:55296
	ds_read_b128 v[84:87], v253 offset:18432
	ds_read_b128 v[88:91], v253 offset:20480
	ds_read_b128 v[92:95], v253 offset:22528
	s_waitcnt lgkmcnt(14)
	v_mfma_f32_16x16x32_bf16 v[0:3], v[64:67], v[96:99], v[0:3]
	s_waitcnt lgkmcnt(13)
	v_mfma_f32_16x16x32_bf16 v[4:7], v[64:67], v[100:103], v[4:7]
	s_waitcnt lgkmcnt(12)
	v_mfma_f32_16x16x32_bf16 v[8:11], v[64:67], v[104:107], v[8:11]
	s_waitcnt lgkmcnt(11)
	v_mfma_f32_16x16x32_bf16 v[12:15], v[64:67], v[108:111], v[12:15]
	s_waitcnt lgkmcnt(10)
	v_mfma_f32_16x16x32_bf16 v[16:19], v[68:71], v[96:99], v[16:19]
	v_mfma_f32_16x16x32_bf16 v[20:23], v[68:71], v[100:103], v[20:23]
	v_mfma_f32_16x16x32_bf16 v[24:27], v[68:71], v[104:107], v[24:27]
	v_mfma_f32_16x16x32_bf16 v[28:31], v[68:71], v[108:111], v[28:31]
	s_waitcnt lgkmcnt(0)
	s_barrier
	s_add_u32 m0, s12, 0x4000
	v_mfma_f32_16x16x32_bf16 v[32:35], v[72:75], v[96:99], v[32:35]
	global_load_lds_dwordx4 v248, s[8:9]
	s_add_u32 m0, s12, 0x4400
	v_mfma_f32_16x16x32_bf16 v[36:39], v[72:75], v[100:103], v[36:39]
	global_load_lds_dwordx4 v249, s[8:9]
	s_add_u32 m0, s12, 0x4800
	v_mfma_f32_16x16x32_bf16 v[40:43], v[72:75], v[104:107], v[40:43]
	global_load_lds_dwordx4 v250, s[8:9]
	s_add_u32 m0, s12, 0x4c00
	v_mfma_f32_16x16x32_bf16 v[44:47], v[72:75], v[108:111], v[44:47]
	global_load_lds_dwordx4 v251, s[8:9]
	s_add_u32 m0, s12, 0xc000
	v_mfma_f32_16x16x32_bf16 v[48:51], v[76:79], v[96:99], v[48:51]
	global_load_lds_dwordx4 v248, s[10:11] sc1
	s_add_u32 m0, s12, 0xc400
	v_mfma_f32_16x16x32_bf16 v[52:55], v[76:79], v[100:103], v[52:55]
	global_load_lds_dwordx4 v249, s[10:11] sc1
	s_add_u32 m0, s12, 0xc800
	v_mfma_f32_16x16x32_bf16 v[56:59], v[76:79], v[104:107], v[56:59]
	global_load_lds_dwordx4 v250, s[10:11] sc1
	s_add_u32 m0, s12, 0xcc00
	v_mfma_f32_16x16x32_bf16 v[60:63], v[76:79], v[108:111], v[60:63]
	global_load_lds_dwordx4 v251, s[10:11] sc1
	s_add_u32 s8, s8, 0x80
	s_addc_u32 s9, s9, 0
	s_add_u32 s10, s10, 0x80
	s_addc_u32 s11, s11, 0
	s_sub_u32 s13, s13, 1
	s_cmp_lg_u32 s13, 0
	s_cbranch_scc1 .Lr6_loop
	s_waitcnt vmcnt(8)
	s_barrier
	ds_read_b128 v[64:67], v252 offset:0
	ds_read_b128 v[96:99], v254 offset:32768
	ds_read_b128 v[100:103], v254 offset:34816
	ds_read_b128 v[104:107], v254 offset:36864
	ds_read_b128 v[108:111], v254 offset:38912
	ds_read_b128 v[68:71], v252 offset:2048
	ds_read_b128 v[72:75], v252 offset:4096
	ds_read_b128 v[76:79], v252 offset:6144
	v_mfma_f32_16x16x32_bf16 v[0:3], v[80:83], v[112:115], v[0:3]
	v_mfma_f32_16x16x32_bf16 v[4:7], v[80:83], v[116:119], v[4:7]
	v_mfma_f32_16x16x32_bf16 v[8:11], v[80:83], v[120:123], v[8:11]
	v_mfma_f32_16x16x32_bf16 v[12:15], v[80:83], v[124:127], v[12:15]
	v_mfma_f32_16x16x32_bf16 v[16:19], v[84:87], v[112:115], v[16:19]
	v_mfma_f32_16x16x32_bf16 v[20:23], v[84:87], v[116:119], v[20:23]
	v_mfma_f32_16x16x32_bf16 v[24:27], v[84:87], v[120:123], v[24:27]
	v_mfma_f32_16x16x32_bf16 v[28:31], v[84:87], v[124:127], v[28:31]
	v_mfma_f32_16x16x32_bf16 v[32:35], v[88:91], v[112:115], v[32:35]
	v_mfma_f32_16x16x32_bf16 v[36:39], v[88:91], v[116:119], v[36:39]
	v_mfma_f32_16x16x32_bf16 v[40:43], v[88:91], v[120:123], v[40:43]
	v_mfma_f32_16x16x32_bf16 v[44:47], v[88:91], v[124:127], v[44:47]
	v_mfma_f32_16x16x32_bf16 v[48:51], v[92:95], v[112:115], v[48:51]
	v_mfma_f32_16x16x32_bf16 v[52:55], v[92:95], v[116:119], v[52:55]
	v_mfma_f32_16x16x32_bf16 v[56:59], v[92:95], v[120:123], v[56:59]
	v_mfma_f32_16x16x32_bf16 v[60:63], v[92:95], v[124:127], v[60:63]
	ds_read_b128 v[80:83], v253 offset:0
	ds_read_b128 v[112:115], v255 offset:32768
	ds_read_b128 v[116:119], v255 offset:34816
	ds_read_b128 v[120:123], v255 offset:36864
	ds_read_b128 v[124:127], v255 offset:38912
	ds_read_b128 v[84:87], v253 offset:2048
	ds_read_b128 v[88:91], v253 offset:4096
	ds_read_b128 v[92:95], v253 offset:6144
	s_waitcnt lgkmcnt(14)
	v_mfma_f32_16x16x32_bf16 v[0:3], v[64:67], v[96:99], v[0:3]
	s_waitcnt lgkmcnt(13)
	v_mfma_f32_16x16x32_bf16 v[4:7], v[64:67], v[100:103], v[4:7]
	s_waitcnt lgkmcnt(12)
	v_mfma_f32_16x16x32_bf16 v[8:11], v[64:67], v[104:107], v[8:11]
	s_waitcnt lgkmcnt(11)
	v_mfma_f32_16x16x32_bf16 v[12:15], v[64:67], v[108:111], v[12:15]
	s_waitcnt lgkmcnt(10)
	v_mfma_f32_16x16x32_bf16 v[16:19], v[68:71], v[96:99], v[16:19]
	v_mfma_f32_16x16x32_bf16 v[20:23], v[68:71], v[100:103], v[20:23]
	v_mfma_f32_16x16x32_bf16 v[24:27], v[68:71], v[104:107], v[24:27]
	v_mfma_f32_16x16x32_bf16 v[28:31], v[68:71], v[108:111], v[28:31]
	s_waitcnt lgkmcnt(0)
	s_barrier
	v_mfma_f32_16x16x32_bf16 v[32:35], v[72:75], v[96:99], v[32:35]
	v_mfma_f32_16x16x32_bf16 v[36:39], v[72:75], v[100:103], v[36:39]
	v_mfma_f32_16x16x32_bf16 v[40:43], v[72:75], v[104:107], v[40:43]
	v_mfma_f32_16x16x32_bf16 v[44:47], v[72:75], v[108:111], v[44:47]
	v_mfma_f32_16x16x32_bf16 v[48:51], v[76:79], v[96:99], v[48:51]
	v_mfma_f32_16x16x32_bf16 v[52:55], v[76:79], v[100:103], v[52:55]
	v_mfma_f32_16x16x32_bf16 v[56:59], v[76:79], v[104:107], v[56:59]
	v_mfma_f32_16x16x32_bf16 v[60:63], v[76:79], v[108:111], v[60:63]
	s_waitcnt vmcnt(0)
	s_barrier
	ds_read_b128 v[64:67], v252 offset:16384
	ds_read_b128 v[96:99], v254 offset:49152
	ds_read_b128 v[100:103], v254 offset:51200
	ds_read_b128 v[104:107], v254 offset:53248
	ds_read_b128 v[108:111], v254 offset:55296
	ds_read_b128 v[68:71], v252 offset:18432
	ds_read_b128 v[72:75], v252 offset:20480
	ds_read_b128 v[76:79], v252 offset:22528
	v_mfma_f32_16x16x32_bf16 v[0:3], v[80:83], v[112:115], v[0:3]
	v_mfma_f32_16x16x32_bf16 v[4:7], v[80:83], v[116:119], v[4:7]
	v_mfma_f32_16x16x32_bf16 v[8:11], v[80:83], v[120:123], v[8:11]
	v_mfma_f32_16x16x32_bf16 v[12:15], v[80:83], v[124:127], v[12:15]
	v_mfma_f32_16x16x32_bf16 v[16:19], v[84:87], v[112:115], v[16:19]
	v_mfma_f32_16x16x32_bf16 v[20:23], v[84:87], v[116:119], v[20:23]
	v_mfma_f32_16x16x32_bf16 v[24:27], v[84:87], v[120:123], v[24:27]
	v_mfma_f32_16x16x32_bf16 v[28:31], v[84:87], v[124:127], v[28:31]
	v_mfma_f32_16x16x32_bf16 v[32:35], v[88:91], v[112:115], v[32:35]
	v_mfma_f32_16x16x32_bf16 v[36:39], v[88:91], v[116:119], v[36:39]
	v_mfma_f32_16x16x32_bf16 v[40:43], v[88:91], v[120:123], v[40:43]
	v_mfma_f32_16x16x32_bf16 v[44:47], v[88:91], v[124:127], v[44:47]
	v_mfma_f32_16x16x32_bf16 v[48:51], v[92:95], v[112:115], v[48:51]
	v_mfma_f32_16x16x32_bf16 v[52:55], v[92:95], v[116:119], v[52:55]
	v_mfma_f32_16x16x32_bf16 v[56:59], v[92:95], v[120:123], v[56:59]
	v_mfma_f32_16x16x32_bf16 v[60:63], v[92:95], v[124:127], v[60:63]
	ds_read_b128 v[80:83], v253 offset:16384
	ds_read_b128 v[112:115], v255 offset:49152
	ds_read_b128 v[116:119], v255 offset:51200
	ds_read_b128 v[120:123], v255 offset:53248
	ds_read_b128 v[124:127], v255 offset:55296
	ds_read_b128 v[84:87], v253 offset:18432
	ds_read_b128 v[88:91], v253 offset:20480
	ds_read_b128 v[92:95], v253 offset:22528
	s_waitcnt lgkmcnt(14)
	v_mfma_f32_16x16x32_bf16 v[0:3], v[64:67], v[96:99], v[0:3]
	s_waitcnt lgkmcnt(13)
	v_mfma_f32_16x16x32_bf16 v[4:7], v[64:67], v[100:103], v[4:7]
	s_waitcnt lgkmcnt(12)
	v_mfma_f32_16x16x32_bf16 v[8:11], v[64:67], v[104:107], v[8:11]
	s_waitcnt lgkmcnt(11)
	v_mfma_f32_16x16x32_bf16 v[12:15], v[64:67], v[108:111], v[12:15]
	s_waitcnt lgkmcnt(10)
	v_mfma_f32_16x16x32_bf16 v[16:19], v[68:71], v[96:99], v[16:19]
	v_mfma_f32_16x16x32_bf16 v[20:23], v[68:71], v[100:103], v[20:23]
	v_mfma_f32_16x16x32_bf16 v[24:27], v[68:71], v[104:107], v[24:27]
	v_mfma_f32_16x16x32_bf16 v[28:31], v[68:71], v[108:111], v[28:31]
	s_waitcnt lgkmcnt(0)
	s_barrier
	v_mfma_f32_16x16x32_bf16 v[32:35], v[72:75], v[96:99], v[32:35]
	v_mfma_f32_16x16x32_bf16 v[36:39], v[72:75], v[100:103], v[36:39]
	v_mfma_f32_16x16x32_bf16 v[40:43], v[72:75], v[104:107], v[40:43]
	v_mfma_f32_16x16x32_bf16 v[44:47], v[72:75], v[108:111], v[44:47]
	v_mfma_f32_16x16x32_bf16 v[48:51], v[76:79], v[96:99], v[48:51]
	v_mfma_f32_16x16x32_bf16 v[52:55], v[76:79], v[100:103], v[52:55]
	v_mfma_f32_16x16x32_bf16 v[56:59], v[76:79], v[104:107], v[56:59]
	v_mfma_f32_16x16x32_bf16 v[60:63], v[76:79], v[108:111], v[60:63]
	v_mfma_f32_16x16x32_bf16 v[0:3], v[80:83], v[112:115], v[0:3]
	v_mfma_f32_16x16x32_bf16 v[4:7], v[80:83], v[116:119], v[4:7]
	v_mfma_f32_16x16x32_bf16 v[8:11], v[80:83], v[120:123], v[8:11]
	v_mfma_f32_16x16x32_bf16 v[12:15], v[80:83], v[124:127], v[12:15]
	v_mfma_f32_16x16x32_bf16 v[16:19], v[84:87], v[112:115], v[16:19]
	v_mfma_f32_16x16x32_bf16 v[20:23], v[84:87], v[116:119], v[20:23]
	v_mfma_f32_16x16x32_bf16 v[24:27], v[84:87], v[120:123], v[24:27]
	v_mfma_f32_16x16x32_bf16 v[28:31], v[84:87], v[124:127], v[28:31]
	v_mfma_f32_16x16x32_bf16 v[32:35], v[88:91], v[112:115], v[32:35]
	v_mfma_f32_16x16x32_bf16 v[36:39], v[88:91], v[116:119], v[36:39]
	v_mfma_f32_16x16x32_bf16 v[40:43], v[88:91], v[120:123], v[40:43]
	v_mfma_f32_16x16x32_bf16 v[44:47], v[88:91], v[124:127], v[44:47]
	v_mfma_f32_16x16x32_bf16 v[48:51], v[92:95], v[112:115], v[48:51]
	v_mfma_f32_16x16x32_bf16 v[52:55], v[92:95], v[116:119], v[52:55]
	v_mfma_f32_16x16x32_bf16 v[56:59], v[92:95], v[120:123], v[56:59]
	v_mfma_f32_16x16x32_bf16 v[60:63], v[92:95], v[124:127], v[60:63]
	s_nop 7
	s_nop 1
	s_mov_b64 s[18:19], s[20:21]
	v_fma_f32 v129, v201, v0, v129
	v_fma_f32 v130, v202, v4, v130
	v_fma_f32 v131, v203, v8, v131
	v_fma_f32 v132, v204, v12, v132
	global_store_dword v246, v129, s[18:19] offset:0
	global_store_dword v246, v130, s[18:19] offset:64
	global_store_dword v246, v131, s[18:19] offset:128
	global_store_dword v246, v132, s[18:19] offset:192
	s_add_u32 s18, s18, 0x1000
	s_addc_u32 s19, s19, 0
	v_fma_f32 v133, v201, v1, v133
	v_fma_f32 v134, v202, v5, v134
	v_fma_f32 v135, v203, v9, v135
	v_fma_f32 v136, v204, v13, v136
	global_store_dword v246, v133, s[18:19] offset:0
	global_store_dword v246, v134, s[18:19] offset:64
	global_store_dword v246, v135, s[18:19] offset:128
	global_store_dword v246, v136, s[18:19] offset:192
	s_add_u32 s18, s18, 0x1000
	s_addc_u32 s19, s19, 0
	v_fma_f32 v137, v201, v2, v137
	v_fma_f32 v138, v202, v6, v138
	v_fma_f32 v139, v203, v10, v139
	v_fma_f32 v140, v204, v14, v140
	global_store_dword v246, v137, s[18:19] offset:0
	global_store_dword v246, v138, s[18:19] offset:64
	global_store_dword v246, v139, s[18:19] offset:128
	global_store_dword v246, v140, s[18:19] offset:192
	s_add_u32 s18, s18, 0x1000
	s_addc_u32 s19, s19, 0
	v_fma_f32 v141, v201, v3, v141
	v_fma_f32 v142, v202, v7, v142
	v_fma_f32 v143, v203, v11, v143
	v_fma_f32 v144, v204, v15, v144
	global_store_dword v246, v141, s[18:19] offset:0
	global_store_dword v246, v142, s[18:19] offset:64
	global_store_dword v246, v143, s[18:19] offset:128
	global_store_dword v246, v144, s[18:19] offset:192
	s_add_u32 s18, s18, 0xd000
	s_addc_u32 s19, s19, 0
	v_fma_f32 v145, v201, v16, v145
	v_fma_f32 v146, v202, v20, v146
	v_fma_f32 v147, v203, v24, v147
	v_fma_f32 v148, v204, v28, v148
	global_store_dword v246, v145, s[18:19] offset:0
	global_store_dword v246, v146, s[18:19] offset:64
	global_store_dword v246, v147, s[18:19] offset:128
	global_store_dword v246, v148, s[18:19] offset:192
	s_add_u32 s18, s18, 0x1000
	s_addc_u32 s19, s19, 0
	v_fma_f32 v149, v201, v17, v149
	v_fma_f32 v150, v202, v21, v150
	v_fma_f32 v151, v203, v25, v151
	v_fma_f32 v152, v204, v29, v152
	global_store_dword v246, v149, s[18:19] offset:0
	global_store_dword v246, v150, s[18:19] offset:64
	global_store_dword v246, v151, s[18:19] offset:128
	global_store_dword v246, v152, s[18:19] offset:192
	s_add_u32 s18, s18, 0x1000
	s_addc_u32 s19, s19, 0
	v_fma_f32 v153, v201, v18, v153
	v_fma_f32 v154, v202, v22, v154
	v_fma_f32 v155, v203, v26, v155
	v_fma_f32 v156, v204, v30, v156
	global_store_dword v246, v153, s[18:19] offset:0
	global_store_dword v246, v154, s[18:19] offset:64
	global_store_dword v246, v155, s[18:19] offset:128
	global_store_dword v246, v156, s[18:19] offset:192
	s_add_u32 s18, s18, 0x1000
	s_addc_u32 s19, s19, 0
	v_fma_f32 v157, v201, v19, v157
	v_fma_f32 v158, v202, v23, v158
	v_fma_f32 v159, v203, v27, v159
	v_fma_f32 v160, v204, v31, v160
	global_store_dword v246, v157, s[18:19] offset:0
	global_store_dword v246, v158, s[18:19] offset:64
	global_store_dword v246, v159, s[18:19] offset:128
	global_store_dword v246, v160, s[18:19] offset:192
	s_add_u32 s18, s18, 0xd000
	s_addc_u32 s19, s19, 0
	v_fma_f32 v161, v201, v32, v161
	v_fma_f32 v170, v202, v36, v170
	v_fma_f32 v171, v203, v40, v171
	v_fma_f32 v172, v204, v44, v172
	global_store_dword v246, v161, s[18:19] offset:0
	global_store_dword v246, v170, s[18:19] offset:64
	global_store_dword v246, v171, s[18:19] offset:128
	global_store_dword v246, v172, s[18:19] offset:192
	s_add_u32 s18, s18, 0x1000
	s_addc_u32 s19, s19, 0
	v_fma_f32 v173, v201, v33, v173
	v_fma_f32 v174, v202, v37, v174
	v_fma_f32 v175, v203, v41, v175
	v_fma_f32 v176, v204, v45, v176
	global_store_dword v246, v173, s[18:19] offset:0
	global_store_dword v246, v174, s[18:19] offset:64
	global_store_dword v246, v175, s[18:19] offset:128
	global_store_dword v246, v176, s[18:19] offset:192
	s_add_u32 s18, s18, 0x1000
	s_addc_u32 s19, s19, 0
	v_fma_f32 v177, v201, v34, v177
	v_fma_f32 v178, v202, v38, v178
	v_fma_f32 v179, v203, v42, v179
	v_fma_f32 v180, v204, v46, v180
	global_store_dword v246, v177, s[18:19] offset:0
	global_store_dword v246, v178, s[18:19] offset:64
	global_store_dword v246, v179, s[18:19] offset:128
	global_store_dword v246, v180, s[18:19] offset:192
	s_add_u32 s18, s18, 0x1000
	s_addc_u32 s19, s19, 0
	v_fma_f32 v181, v201, v35, v181
	v_fma_f32 v182, v202, v39, v182
	v_fma_f32 v183, v203, v43, v183
	v_fma_f32 v184, v204, v47, v184
	global_store_dword v246, v181, s[18:19] offset:0
	global_store_dword v246, v182, s[18:19] offset:64
	global_store_dword v246, v183, s[18:19] offset:128
	global_store_dword v246, v184, s[18:19] offset:192
	s_add_u32 s18, s18, 0xd000
	s_addc_u32 s19, s19, 0
	v_fma_f32 v185, v201, v48, v185
	v_fma_f32 v186, v202, v52, v186
	v_fma_f32 v187, v203, v56, v187
	v_fma_f32 v188, v204, v60, v188
	global_store_dword v246, v185, s[18:19] offset:0
	global_store_dword v246, v186, s[18:19] offset:64
	global_store_dword v246, v187, s[18:19] offset:128
	global_store_dword v246, v188, s[18:19] offset:192
	s_add_u32 s18, s18, 0x1000
	s_addc_u32 s19, s19, 0
	v_fma_f32 v189, v201, v49, v189
	v_fma_f32 v190, v202, v53, v190
	v_fma_f32 v191, v203, v57, v191
	v_fma_f32 v192, v204, v61, v192
	global_store_dword v246, v189, s[18:19] offset:0
	global_store_dword v246, v190, s[18:19] offset:64
	global_store_dword v246, v191, s[18:19] offset:128
	global_store_dword v246, v192, s[18:19] offset:192
	s_add_u32 s18, s18, 0x1000
	s_addc_u32 s19, s19, 0
	v_fma_f32 v193, v201, v50, v193
	v_fma_f32 v194, v202, v54, v194
	v_fma_f32 v195, v203, v58, v195
	v_fma_f32 v196, v204, v62, v196
	global_store_dword v246, v193, s[18:19] offset:0
	global_store_dword v246, v194, s[18:19] offset:64
	global_store_dword v246, v195, s[18:19] offset:128
	global_store_dword v246, v196, s[18:19] offset:192
	s_add_u32 s18, s18, 0x1000
	s_addc_u32 s19, s19, 0
	v_fma_f32 v197, v201, v51, v197
	v_fma_f32 v198, v202, v55, v198
	v_fma_f32 v199, v203, v59, v199
	v_fma_f32 v200, v204, v63, v200
	global_store_dword v246, v197, s[18:19] offset:0
	global_store_dword v246, v198, s[18:19] offset:64
	global_store_dword v246, v199, s[18:19] offset:128
	global_store_dword v246, v200, s[18:19] offset:192
	s_add_u32 s15, s15, s16
	s_branch .Lr6_tile

.Lf8_tile:
	s_cmp_lt_u32 s15, 0xb00
	s_cbranch_scc0 .Lf8_end
	s_and_b32 s2, s15, 63
	s_lshr_b32 s3, s15, 6
	s_lshl_b32 s14, s2, 18
	s_add_u32 s8, s26, s14
	s_addc_u32 s9, s27, 0
	s_lshl_b32 s14, s3, 18
	s_add_u32 s10, s28, s14
	s_addc_u32 s11, s29, 0
	s_mul_i32 s14, s2, 0xb0000
	s_lshl_b32 s6, s3, 7
	s_add_u32 s14, s14, s6
	s_add_u32 s20, s4, 0x9b7a100
	s_addc_u32 s21, s5, 0
	s_add_u32 s20, s20, s14
	s_addc_u32 s21, s21, 0
	v_readfirstlane_b32 s12, v247
	s_nop 3
	s_lshl_b32 s12, s12, 12
	s_add_u32 m0, s12, 0x0
	v_mov_b32_e32 v0, 0
	global_load_lds_dwordx4 v248, s[8:9]
	v_mov_b32_e32 v1, 0
	s_add_u32 m0, s12, 0x400
	v_mov_b32_e32 v2, 0
	global_load_lds_dwordx4 v249, s[8:9]
	v_mov_b32_e32 v3, 0
	s_add_u32 m0, s12, 0x800
	v_mov_b32_e32 v4, 0
	global_load_lds_dwordx4 v250, s[8:9]
	v_mov_b32_e32 v5, 0
	s_add_u32 m0, s12, 0xc00
	v_mov_b32_e32 v6, 0
	global_load_lds_dwordx4 v251, s[8:9]
	v_mov_b32_e32 v7, 0
	s_add_u32 m0, s12, 0x8000
	v_mov_b32_e32 v8, 0
	global_load_lds_dwordx4 v248, s[10:11] sc1
	v_mov_b32_e32 v9, 0
	s_add_u32 m0, s12, 0x8400
	v_mov_b32_e32 v10, 0
	global_load_lds_dwordx4 v249, s[10:11] sc1
	v_mov_b32_e32 v11, 0
	s_add_u32 m0, s12, 0x8800
	v_mov_b32_e32 v12, 0
	global_load_lds_dwordx4 v250, s[10:11] sc1
	v_mov_b32_e32 v13, 0
	s_add_u32 m0, s12, 0x8c00
	v_mov_b32_e32 v14, 0
	global_load_lds_dwordx4 v251, s[10:11] sc1
	v_mov_b32_e32 v15, 0
	s_add_u32 s8, s8, 0x80
	s_addc_u32 s9, s9, 0
	s_add_u32 s10, s10, 0x80
	s_addc_u32 s11, s11, 0
	s_add_u32 m0, s12, 0x4000
	v_mov_b32_e32 v16, 0
	global_load_lds_dwordx4 v248, s[8:9]
	v_mov_b32_e32 v17, 0
	s_add_u32 m0, s12, 0x4400
	v_mov_b32_e32 v18, 0
	global_load_lds_dwordx4 v249, s[8:9]
	v_mov_b32_e32 v19, 0
	s_add_u32 m0, s12, 0x4800
	v_mov_b32_e32 v20, 0
	global_load_lds_dwordx4 v250, s[8:9]
	v_mov_b32_e32 v21, 0
	s_add_u32 m0, s12, 0x4c00
	v_mov_b32_e32 v22, 0
	global_load_lds_dwordx4 v251, s[8:9]
	v_mov_b32_e32 v23, 0
	s_add_u32 m0, s12, 0xc000
	v_mov_b32_e32 v24, 0
	global_load_lds_dwordx4 v248, s[10:11] sc1
	v_mov_b32_e32 v25, 0
	s_add_u32 m0, s12, 0xc400
	v_mov_b32_e32 v26, 0
	global_load_lds_dwordx4 v249, s[10:11] sc1
	v_mov_b32_e32 v27, 0
	s_add_u32 m0, s12, 0xc800
	v_mov_b32_e32 v28, 0
	global_load_lds_dwordx4 v250, s[10:11] sc1
	v_mov_b32_e32 v29, 0
	s_add_u32 m0, s12, 0xcc00
	v_mov_b32_e32 v30, 0
	global_load_lds_dwordx4 v251, s[10:11] sc1
	v_mov_b32_e32 v31, 0
	s_add_u32 s8, s8, 0x80
	s_addc_u32 s9, s9, 0
	s_add_u32 s10, s10, 0x80
	s_addc_u32 s11, s11, 0
	v_mov_b32_e32 v32, 0
	v_mov_b32_e32 v33, 0
	v_mov_b32_e32 v34, 0
	v_mov_b32_e32 v35, 0
	v_mov_b32_e32 v36, 0
	v_mov_b32_e32 v37, 0
	v_mov_b32_e32 v38, 0
	v_mov_b32_e32 v39, 0
	v_mov_b32_e32 v40, 0
	v_mov_b32_e32 v41, 0
	v_mov_b32_e32 v42, 0
	v_mov_b32_e32 v43, 0
	v_mov_b32_e32 v44, 0
	v_mov_b32_e32 v45, 0
	v_mov_b32_e32 v46, 0
	v_mov_b32_e32 v47, 0
	v_mov_b32_e32 v48, 0
	v_mov_b32_e32 v49, 0
	v_mov_b32_e32 v50, 0
	v_mov_b32_e32 v51, 0
	v_mov_b32_e32 v52, 0
	v_mov_b32_e32 v53, 0
	v_mov_b32_e32 v54, 0
	v_mov_b32_e32 v55, 0
	v_mov_b32_e32 v56, 0
	v_mov_b32_e32 v57, 0
	v_mov_b32_e32 v58, 0
	v_mov_b32_e32 v59, 0
	v_mov_b32_e32 v60, 0
	v_mov_b32_e32 v61, 0
	v_mov_b32_e32 v62, 0
	v_mov_b32_e32 v63, 0
	s_waitcnt vmcnt(8)
	s_barrier
	ds_read_b128 v[64:67], v252 offset:0
	ds_read_b128 v[96:99], v254 offset:32768
	ds_read_b128 v[100:103], v254 offset:34816
	ds_read_b128 v[104:107], v254 offset:36864
	ds_read_b128 v[108:111], v254 offset:38912
	ds_read_b128 v[68:71], v252 offset:2048
	ds_read_b128 v[72:75], v252 offset:4096
	ds_read_b128 v[76:79], v252 offset:6144
	ds_read_b128 v[80:83], v253 offset:0
	ds_read_b128 v[112:115], v255 offset:32768
	ds_read_b128 v[116:119], v255 offset:34816
	ds_read_b128 v[120:123], v255 offset:36864
	ds_read_b128 v[124:127], v255 offset:38912
	s_waitcnt lgkmcnt(11)
	v_mfma_f32_16x16x32_bf16 v[0:3], v[96:99], v[64:67], v[0:3]
	s_waitcnt lgkmcnt(10)
	v_mfma_f32_16x16x32_bf16 v[4:7], v[100:103], v[64:67], v[4:7]
	s_waitcnt lgkmcnt(9)
	v_mfma_f32_16x16x32_bf16 v[8:11], v[104:107], v[64:67], v[8:11]
	s_waitcnt lgkmcnt(8)
	v_mfma_f32_16x16x32_bf16 v[12:15], v[108:111], v[64:67], v[12:15]
	ds_read_b128 v[84:87], v253 offset:2048
	ds_read_b128 v[88:91], v253 offset:4096
	ds_read_b128 v[92:95], v253 offset:6144
	s_waitcnt lgkmcnt(10)
	v_mfma_f32_16x16x32_bf16 v[16:19], v[96:99], v[68:71], v[16:19]
	v_mfma_f32_16x16x32_bf16 v[20:23], v[100:103], v[68:71], v[20:23]
	v_mfma_f32_16x16x32_bf16 v[24:27], v[104:107], v[68:71], v[24:27]
	v_mfma_f32_16x16x32_bf16 v[28:31], v[108:111], v[68:71], v[28:31]
	s_waitcnt lgkmcnt(0)
	s_barrier
	s_add_u32 m0, s12, 0x0
	v_mfma_f32_16x16x32_bf16 v[32:35], v[96:99], v[72:75], v[32:35]
	global_load_lds_dwordx4 v248, s[8:9]
	s_add_u32 m0, s12, 0x400
	v_mfma_f32_16x16x32_bf16 v[36:39], v[100:103], v[72:75], v[36:39]
	global_load_lds_dwordx4 v249, s[8:9]
	s_add_u32 m0, s12, 0x800
	v_mfma_f32_16x16x32_bf16 v[40:43], v[104:107], v[72:75], v[40:43]
	global_load_lds_dwordx4 v250, s[8:9]
	s_add_u32 m0, s12, 0xc00
	v_mfma_f32_16x16x32_bf16 v[44:47], v[108:111], v[72:75], v[44:47]
	global_load_lds_dwordx4 v251, s[8:9]
	s_add_u32 m0, s12, 0x8000
	v_mfma_f32_16x16x32_bf16 v[48:51], v[96:99], v[76:79], v[48:51]
	global_load_lds_dwordx4 v248, s[10:11] sc1
	s_add_u32 m0, s12, 0x8400
	v_mfma_f32_16x16x32_bf16 v[52:55], v[100:103], v[76:79], v[52:55]
	global_load_lds_dwordx4 v249, s[10:11] sc1
	s_add_u32 m0, s12, 0x8800
	v_mfma_f32_16x16x32_bf16 v[56:59], v[104:107], v[76:79], v[56:59]
	global_load_lds_dwordx4 v250, s[10:11] sc1
	s_add_u32 m0, s12, 0x8c00
	v_mfma_f32_16x16x32_bf16 v[60:63], v[108:111], v[76:79], v[60:63]
	global_load_lds_dwordx4 v251, s[10:11] sc1
	s_add_u32 s8, s8, 0x80
	s_addc_u32 s9, s9, 0
	s_add_u32 s10, s10, 0x80
	s_addc_u32 s11, s11, 0
	s_waitcnt vmcnt(8)
	s_barrier
	ds_read_b128 v[64:67], v252 offset:16384
	ds_read_b128 v[96:99], v254 offset:49152
	ds_read_b128 v[100:103], v254 offset:51200
	ds_read_b128 v[104:107], v254 offset:53248
	ds_read_b128 v[108:111], v254 offset:55296
	ds_read_b128 v[68:71], v252 offset:18432
	ds_read_b128 v[72:75], v252 offset:20480
	ds_read_b128 v[76:79], v252 offset:22528
	v_mfma_f32_16x16x32_bf16 v[0:3], v[112:115], v[80:83], v[0:3]
	v_mfma_f32_16x16x32_bf16 v[4:7], v[116:119], v[80:83], v[4:7]
	v_mfma_f32_16x16x32_bf16 v[8:11], v[120:123], v[80:83], v[8:11]
	v_mfma_f32_16x16x32_bf16 v[12:15], v[124:127], v[80:83], v[12:15]
	v_mfma_f32_16x16x32_bf16 v[16:19], v[112:115], v[84:87], v[16:19]
	v_mfma_f32_16x16x32_bf16 v[20:23], v[116:119], v[84:87], v[20:23]
	v_mfma_f32_16x16x32_bf16 v[24:27], v[120:123], v[84:87], v[24:27]
	v_mfma_f32_16x16x32_bf16 v[28:31], v[124:127], v[84:87], v[28:31]
	v_mfma_f32_16x16x32_bf16 v[32:35], v[112:115], v[88:91], v[32:35]
	v_mfma_f32_16x16x32_bf16 v[36:39], v[116:119], v[88:91], v[36:39]
	v_mfma_f32_16x16x32_bf16 v[40:43], v[120:123], v[88:91], v[40:43]
	v_mfma_f32_16x16x32_bf16 v[44:47], v[124:127], v[88:91], v[44:47]
	v_mfma_f32_16x16x32_bf16 v[48:51], v[112:115], v[92:95], v[48:51]
	v_mfma_f32_16x16x32_bf16 v[52:55], v[116:119], v[92:95], v[52:55]
	v_mfma_f32_16x16x32_bf16 v[56:59], v[120:123], v[92:95], v[56:59]
	v_mfma_f32_16x16x32_bf16 v[60:63], v[124:127], v[92:95], v[60:63]
	ds_read_b128 v[80:83], v253 offset:16384
	ds_read_b128 v[112:115], v255 offset:49152
	ds_read_b128 v[116:119], v255 offset:51200
	ds_read_b128 v[120:123], v255 offset:53248
	ds_read_b128 v[124:127], v255 offset:55296
	ds_read_b128 v[84:87], v253 offset:18432
	ds_read_b128 v[88:91], v253 offset:20480
	ds_read_b128 v[92:95], v253 offset:22528
	s_waitcnt lgkmcnt(14)
	v_mfma_f32_16x16x32_bf16 v[0:3], v[96:99], v[64:67], v[0:3]
	s_waitcnt lgkmcnt(13)
	v_mfma_f32_16x16x32_bf16 v[4:7], v[100:103], v[64:67], v[4:7]
	s_waitcnt lgkmcnt(12)
	v_mfma_f32_16x16x32_bf16 v[8:11], v[104:107], v[64:67], v[8:11]
	s_waitcnt lgkmcnt(11)
	v_mfma_f32_16x16x32_bf16 v[12:15], v[108:111], v[64:67], v[12:15]
	s_waitcnt lgkmcnt(10)
	v_mfma_f32_16x16x32_bf16 v[16:19], v[96:99], v[68:71], v[16:19]
	v_mfma_f32_16x16x32_bf16 v[20:23], v[100:103], v[68:71], v[20:23]
	v_mfma_f32_16x16x32_bf16 v[24:27], v[104:107], v[68:71], v[24:27]
	v_mfma_f32_16x16x32_bf16 v[28:31], v[108:111], v[68:71], v[28:31]
	s_waitcnt lgkmcnt(0)
	s_barrier
	s_add_u32 m0, s12, 0x4000
	v_mfma_f32_16x16x32_bf16 v[32:35], v[96:99], v[72:75], v[32:35]
	global_load_lds_dwordx4 v248, s[8:9]
	s_add_u32 m0, s12, 0x4400
	v_mfma_f32_16x16x32_bf16 v[36:39], v[100:103], v[72:75], v[36:39]
	global_load_lds_dwordx4 v249, s[8:9]
	s_add_u32 m0, s12, 0x4800
	v_mfma_f32_16x16x32_bf16 v[40:43], v[104:107], v[72:75], v[40:43]
	global_load_lds_dwordx4 v250, s[8:9]
	s_add_u32 m0, s12, 0x4c00
	v_mfma_f32_16x16x32_bf16 v[44:47], v[108:111], v[72:75], v[44:47]
	global_load_lds_dwordx4 v251, s[8:9]
	s_add_u32 m0, s12, 0xc000
	v_mfma_f32_16x16x32_bf16 v[48:51], v[96:99], v[76:79], v[48:51]
	global_load_lds_dwordx4 v248, s[10:11] sc1
	s_add_u32 m0, s12, 0xc400
	v_mfma_f32_16x16x32_bf16 v[52:55], v[100:103], v[76:79], v[52:55]
	global_load_lds_dwordx4 v249, s[10:11] sc1
	s_add_u32 m0, s12, 0xc800
	v_mfma_f32_16x16x32_bf16 v[56:59], v[104:107], v[76:79], v[56:59]
	global_load_lds_dwordx4 v250, s[10:11] sc1
	s_add_u32 m0, s12, 0xcc00
	v_mfma_f32_16x16x32_bf16 v[60:63], v[108:111], v[76:79], v[60:63]
	global_load_lds_dwordx4 v251, s[10:11] sc1
	s_add_u32 s8, s8, 0x80
	s_addc_u32 s9, s9, 0
	s_add_u32 s10, s10, 0x80
	s_addc_u32 s11, s11, 0
	s_mov_b32 s13, 6
.Lf8_loop:
	s_waitcnt vmcnt(8)
	s_barrier
	ds_read_b128 v[64:67], v252 offset:0
	ds_read_b128 v[96:99], v254 offset:32768
	ds_read_b128 v[100:103], v254 offset:34816
	ds_read_b128 v[104:107], v254 offset:36864
	ds_read_b128 v[108:111], v254 offset:38912
	ds_read_b128 v[68:71], v252 offset:2048
	ds_read_b128 v[72:75], v252 offset:4096
	ds_read_b128 v[76:79], v252 offset:6144
	v_mfma_f32_16x16x32_bf16 v[0:3], v[112:115], v[80:83], v[0:3]
	v_mfma_f32_16x16x32_bf16 v[4:7], v[116:119], v[80:83], v[4:7]
	v_mfma_f32_16x16x32_bf16 v[8:11], v[120:123], v[80:83], v[8:11]
	v_mfma_f32_16x16x32_bf16 v[12:15], v[124:127], v[80:83], v[12:15]
	v_mfma_f32_16x16x32_bf16 v[16:19], v[112:115], v[84:87], v[16:19]
	v_mfma_f32_16x16x32_bf16 v[20:23], v[116:119], v[84:87], v[20:23]
	v_mfma_f32_16x16x32_bf16 v[24:27], v[120:123], v[84:87], v[24:27]
	v_mfma_f32_16x16x32_bf16 v[28:31], v[124:127], v[84:87], v[28:31]
	v_mfma_f32_16x16x32_bf16 v[32:35], v[112:115], v[88:91], v[32:35]
	v_mfma_f32_16x16x32_bf16 v[36:39], v[116:119], v[88:91], v[36:39]
	v_mfma_f32_16x16x32_bf16 v[40:43], v[120:123], v[88:91], v[40:43]
	v_mfma_f32_16x16x32_bf16 v[44:47], v[124:127], v[88:91], v[44:47]
	v_mfma_f32_16x16x32_bf16 v[48:51], v[112:115], v[92:95], v[48:51]
	v_mfma_f32_16x16x32_bf16 v[52:55], v[116:119], v[92:95], v[52:55]
	v_mfma_f32_16x16x32_bf16 v[56:59], v[120:123], v[92:95], v[56:59]
	v_mfma_f32_16x16x32_bf16 v[60:63], v[124:127], v[92:95], v[60:63]
	ds_read_b128 v[80:83], v253 offset:0
	ds_read_b128 v[112:115], v255 offset:32768
	ds_read_b128 v[116:119], v255 offset:34816
	ds_read_b128 v[120:123], v255 offset:36864
	ds_read_b128 v[124:127], v255 offset:38912
	ds_read_b128 v[84:87], v253 offset:2048
	ds_read_b128 v[88:91], v253 offset:4096
	ds_read_b128 v[92:95], v253 offset:6144
	s_waitcnt lgkmcnt(14)
	v_mfma_f32_16x16x32_bf16 v[0:3], v[96:99], v[64:67], v[0:3]
	s_waitcnt lgkmcnt(13)
	v_mfma_f32_16x16x32_bf16 v[4:7], v[100:103], v[64:67], v[4:7]
	s_waitcnt lgkmcnt(12)
	v_mfma_f32_16x16x32_bf16 v[8:11], v[104:107], v[64:67], v[8:11]
	s_waitcnt lgkmcnt(11)
	v_mfma_f32_16x16x32_bf16 v[12:15], v[108:111], v[64:67], v[12:15]
	s_waitcnt lgkmcnt(10)
	v_mfma_f32_16x16x32_bf16 v[16:19], v[96:99], v[68:71], v[16:19]
	v_mfma_f32_16x16x32_bf16 v[20:23], v[100:103], v[68:71], v[20:23]
	v_mfma_f32_16x16x32_bf16 v[24:27], v[104:107], v[68:71], v[24:27]
	v_mfma_f32_16x16x32_bf16 v[28:31], v[108:111], v[68:71], v[28:31]
	s_waitcnt lgkmcnt(0)
	s_barrier
	s_add_u32 m0, s12, 0x0
	v_mfma_f32_16x16x32_bf16 v[32:35], v[96:99], v[72:75], v[32:35]
	global_load_lds_dwordx4 v248, s[8:9]
	s_add_u32 m0, s12, 0x400
	v_mfma_f32_16x16x32_bf16 v[36:39], v[100:103], v[72:75], v[36:39]
	global_load_lds_dwordx4 v249, s[8:9]
	s_add_u32 m0, s12, 0x800
	v_mfma_f32_16x16x32_bf16 v[40:43], v[104:107], v[72:75], v[40:43]
	global_load_lds_dwordx4 v250, s[8:9]
	s_add_u32 m0, s12, 0xc00
	v_mfma_f32_16x16x32_bf16 v[44:47], v[108:111], v[72:75], v[44:47]
	global_load_lds_dwordx4 v251, s[8:9]
	s_add_u32 m0, s12, 0x8000
	v_mfma_f32_16x16x32_bf16 v[48:51], v[96:99], v[76:79], v[48:51]
	global_load_lds_dwordx4 v248, s[10:11] sc1
	s_add_u32 m0, s12, 0x8400
	v_mfma_f32_16x16x32_bf16 v[52:55], v[100:103], v[76:79], v[52:55]
	global_load_lds_dwordx4 v249, s[10:11] sc1
	s_add_u32 m0, s12, 0x8800
	v_mfma_f32_16x16x32_bf16 v[56:59], v[104:107], v[76:79], v[56:59]
	global_load_lds_dwordx4 v250, s[10:11] sc1
	s_add_u32 m0, s12, 0x8c00
	v_mfma_f32_16x16x32_bf16 v[60:63], v[108:111], v[76:79], v[60:63]
	global_load_lds_dwordx4 v251, s[10:11] sc1
	s_add_u32 s8, s8, 0x80
	s_addc_u32 s9, s9, 0
	s_add_u32 s10, s10, 0x80
	s_addc_u32 s11, s11, 0
	s_waitcnt vmcnt(8)
	s_barrier
	ds_read_b128 v[64:67], v252 offset:16384
	ds_read_b128 v[96:99], v254 offset:49152
	ds_read_b128 v[100:103], v254 offset:51200
	ds_read_b128 v[104:107], v254 offset:53248
	ds_read_b128 v[108:111], v254 offset:55296
	ds_read_b128 v[68:71], v252 offset:18432
	ds_read_b128 v[72:75], v252 offset:20480
	ds_read_b128 v[76:79], v252 offset:22528
	v_mfma_f32_16x16x32_bf16 v[0:3], v[112:115], v[80:83], v[0:3]
	v_mfma_f32_16x16x32_bf16 v[4:7], v[116:119], v[80:83], v[4:7]
	v_mfma_f32_16x16x32_bf16 v[8:11], v[120:123], v[80:83], v[8:11]
	v_mfma_f32_16x16x32_bf16 v[12:15], v[124:127], v[80:83], v[12:15]
	v_mfma_f32_16x16x32_bf16 v[16:19], v[112:115], v[84:87], v[16:19]
	v_mfma_f32_16x16x32_bf16 v[20:23], v[116:119], v[84:87], v[20:23]
	v_mfma_f32_16x16x32_bf16 v[24:27], v[120:123], v[84:87], v[24:27]
	v_mfma_f32_16x16x32_bf16 v[28:31], v[124:127], v[84:87], v[28:31]
	v_mfma_f32_16x16x32_bf16 v[32:35], v[112:115], v[88:91], v[32:35]
	v_mfma_f32_16x16x32_bf16 v[36:39], v[116:119], v[88:91], v[36:39]
	v_mfma_f32_16x16x32_bf16 v[40:43], v[120:123], v[88:91], v[40:43]
	v_mfma_f32_16x16x32_bf16 v[44:47], v[124:127], v[88:91], v[44:47]
	v_mfma_f32_16x16x32_bf16 v[48:51], v[112:115], v[92:95], v[48:51]
	v_mfma_f32_16x16x32_bf16 v[52:55], v[116:119], v[92:95], v[52:55]
	v_mfma_f32_16x16x32_bf16 v[56:59], v[120:123], v[92:95], v[56:59]
	v_mfma_f32_16x16x32_bf16 v[60:63], v[124:127], v[92:95], v[60:63]
	ds_read_b128 v[80:83], v253 offset:16384
	ds_read_b128 v[112:115], v255 offset:49152
	ds_read_b128 v[116:119], v255 offset:51200
	ds_read_b128 v[120:123], v255 offset:53248
	ds_read_b128 v[124:127], v255 offset:55296
	ds_read_b128 v[84:87], v253 offset:18432
	ds_read_b128 v[88:91], v253 offset:20480
	ds_read_b128 v[92:95], v253 offset:22528
	s_waitcnt lgkmcnt(14)
	v_mfma_f32_16x16x32_bf16 v[0:3], v[96:99], v[64:67], v[0:3]
	s_waitcnt lgkmcnt(13)
	v_mfma_f32_16x16x32_bf16 v[4:7], v[100:103], v[64:67], v[4:7]
	s_waitcnt lgkmcnt(12)
	v_mfma_f32_16x16x32_bf16 v[8:11], v[104:107], v[64:67], v[8:11]
	s_waitcnt lgkmcnt(11)
	v_mfma_f32_16x16x32_bf16 v[12:15], v[108:111], v[64:67], v[12:15]
	s_waitcnt lgkmcnt(10)
	v_mfma_f32_16x16x32_bf16 v[16:19], v[96:99], v[68:71], v[16:19]
	v_mfma_f32_16x16x32_bf16 v[20:23], v[100:103], v[68:71], v[20:23]
	v_mfma_f32_16x16x32_bf16 v[24:27], v[104:107], v[68:71], v[24:27]
	v_mfma_f32_16x16x32_bf16 v[28:31], v[108:111], v[68:71], v[28:31]
	s_waitcnt lgkmcnt(0)
	s_barrier
	s_add_u32 m0, s12, 0x4000
	v_mfma_f32_16x16x32_bf16 v[32:35], v[96:99], v[72:75], v[32:35]
	global_load_lds_dwordx4 v248, s[8:9]
	s_add_u32 m0, s12, 0x4400
	v_mfma_f32_16x16x32_bf16 v[36:39], v[100:103], v[72:75], v[36:39]
	global_load_lds_dwordx4 v249, s[8:9]
	s_add_u32 m0, s12, 0x4800
	v_mfma_f32_16x16x32_bf16 v[40:43], v[104:107], v[72:75], v[40:43]
	global_load_lds_dwordx4 v250, s[8:9]
	s_add_u32 m0, s12, 0x4c00
	v_mfma_f32_16x16x32_bf16 v[44:47], v[108:111], v[72:75], v[44:47]
	global_load_lds_dwordx4 v251, s[8:9]
	s_add_u32 m0, s12, 0xc000
	v_mfma_f32_16x16x32_bf16 v[48:51], v[96:99], v[76:79], v[48:51]
	global_load_lds_dwordx4 v248, s[10:11] sc1
	s_add_u32 m0, s12, 0xc400
	v_mfma_f32_16x16x32_bf16 v[52:55], v[100:103], v[76:79], v[52:55]
	global_load_lds_dwordx4 v249, s[10:11] sc1
	s_add_u32 m0, s12, 0xc800
	v_mfma_f32_16x16x32_bf16 v[56:59], v[104:107], v[76:79], v[56:59]
	global_load_lds_dwordx4 v250, s[10:11] sc1
	s_add_u32 m0, s12, 0xcc00
	v_mfma_f32_16x16x32_bf16 v[60:63], v[108:111], v[76:79], v[60:63]
	global_load_lds_dwordx4 v251, s[10:11] sc1
	s_add_u32 s8, s8, 0x80
	s_addc_u32 s9, s9, 0
	s_add_u32 s10, s10, 0x80
	s_addc_u32 s11, s11, 0
	s_sub_u32 s13, s13, 1
	s_cmp_lg_u32 s13, 0
	s_cbranch_scc1 .Lf8_loop
	s_waitcnt vmcnt(8)
	s_barrier
	ds_read_b128 v[64:67], v252 offset:0
	ds_read_b128 v[96:99], v254 offset:32768
	ds_read_b128 v[100:103], v254 offset:34816
	ds_read_b128 v[104:107], v254 offset:36864
	ds_read_b128 v[108:111], v254 offset:38912
	ds_read_b128 v[68:71], v252 offset:2048
	ds_read_b128 v[72:75], v252 offset:4096
	ds_read_b128 v[76:79], v252 offset:6144
	v_mfma_f32_16x16x32_bf16 v[0:3], v[112:115], v[80:83], v[0:3]
	v_mfma_f32_16x16x32_bf16 v[4:7], v[116:119], v[80:83], v[4:7]
	v_mfma_f32_16x16x32_bf16 v[8:11], v[120:123], v[80:83], v[8:11]
	v_mfma_f32_16x16x32_bf16 v[12:15], v[124:127], v[80:83], v[12:15]
	v_mfma_f32_16x16x32_bf16 v[16:19], v[112:115], v[84:87], v[16:19]
	v_mfma_f32_16x16x32_bf16 v[20:23], v[116:119], v[84:87], v[20:23]
	v_mfma_f32_16x16x32_bf16 v[24:27], v[120:123], v[84:87], v[24:27]
	v_mfma_f32_16x16x32_bf16 v[28:31], v[124:127], v[84:87], v[28:31]
	v_mfma_f32_16x16x32_bf16 v[32:35], v[112:115], v[88:91], v[32:35]
	v_mfma_f32_16x16x32_bf16 v[36:39], v[116:119], v[88:91], v[36:39]
	v_mfma_f32_16x16x32_bf16 v[40:43], v[120:123], v[88:91], v[40:43]
	v_mfma_f32_16x16x32_bf16 v[44:47], v[124:127], v[88:91], v[44:47]
	v_mfma_f32_16x16x32_bf16 v[48:51], v[112:115], v[92:95], v[48:51]
	v_mfma_f32_16x16x32_bf16 v[52:55], v[116:119], v[92:95], v[52:55]
	v_mfma_f32_16x16x32_bf16 v[56:59], v[120:123], v[92:95], v[56:59]
	v_mfma_f32_16x16x32_bf16 v[60:63], v[124:127], v[92:95], v[60:63]
	ds_read_b128 v[80:83], v253 offset:0
	ds_read_b128 v[112:115], v255 offset:32768
	ds_read_b128 v[116:119], v255 offset:34816
	ds_read_b128 v[120:123], v255 offset:36864
	ds_read_b128 v[124:127], v255 offset:38912
	ds_read_b128 v[84:87], v253 offset:2048
	ds_read_b128 v[88:91], v253 offset:4096
	ds_read_b128 v[92:95], v253 offset:6144
	s_waitcnt lgkmcnt(14)
	v_mfma_f32_16x16x32_bf16 v[0:3], v[96:99], v[64:67], v[0:3]
	s_waitcnt lgkmcnt(13)
	v_mfma_f32_16x16x32_bf16 v[4:7], v[100:103], v[64:67], v[4:7]
	s_waitcnt lgkmcnt(12)
	v_mfma_f32_16x16x32_bf16 v[8:11], v[104:107], v[64:67], v[8:11]
	s_waitcnt lgkmcnt(11)
	v_mfma_f32_16x16x32_bf16 v[12:15], v[108:111], v[64:67], v[12:15]
	s_waitcnt lgkmcnt(10)
	v_mfma_f32_16x16x32_bf16 v[16:19], v[96:99], v[68:71], v[16:19]
	v_mfma_f32_16x16x32_bf16 v[20:23], v[100:103], v[68:71], v[20:23]
	v_mfma_f32_16x16x32_bf16 v[24:27], v[104:107], v[68:71], v[24:27]
	v_mfma_f32_16x16x32_bf16 v[28:31], v[108:111], v[68:71], v[28:31]
	s_waitcnt lgkmcnt(0)
	s_barrier
	v_mfma_f32_16x16x32_bf16 v[32:35], v[96:99], v[72:75], v[32:35]
	v_mfma_f32_16x16x32_bf16 v[36:39], v[100:103], v[72:75], v[36:39]
	v_mfma_f32_16x16x32_bf16 v[40:43], v[104:107], v[72:75], v[40:43]
	v_mfma_f32_16x16x32_bf16 v[44:47], v[108:111], v[72:75], v[44:47]
	v_mfma_f32_16x16x32_bf16 v[48:51], v[96:99], v[76:79], v[48:51]
	v_mfma_f32_16x16x32_bf16 v[52:55], v[100:103], v[76:79], v[52:55]
	v_mfma_f32_16x16x32_bf16 v[56:59], v[104:107], v[76:79], v[56:59]
	v_mfma_f32_16x16x32_bf16 v[60:63], v[108:111], v[76:79], v[60:63]
	s_waitcnt vmcnt(0)
	s_barrier
	ds_read_b128 v[64:67], v252 offset:16384
	ds_read_b128 v[96:99], v254 offset:49152
	ds_read_b128 v[100:103], v254 offset:51200
	ds_read_b128 v[104:107], v254 offset:53248
	ds_read_b128 v[108:111], v254 offset:55296
	ds_read_b128 v[68:71], v252 offset:18432
	ds_read_b128 v[72:75], v252 offset:20480
	ds_read_b128 v[76:79], v252 offset:22528
	v_mfma_f32_16x16x32_bf16 v[0:3], v[112:115], v[80:83], v[0:3]
	v_mfma_f32_16x16x32_bf16 v[4:7], v[116:119], v[80:83], v[4:7]
	v_mfma_f32_16x16x32_bf16 v[8:11], v[120:123], v[80:83], v[8:11]
	v_mfma_f32_16x16x32_bf16 v[12:15], v[124:127], v[80:83], v[12:15]
	v_mfma_f32_16x16x32_bf16 v[16:19], v[112:115], v[84:87], v[16:19]
	v_mfma_f32_16x16x32_bf16 v[20:23], v[116:119], v[84:87], v[20:23]
	v_mfma_f32_16x16x32_bf16 v[24:27], v[120:123], v[84:87], v[24:27]
	v_mfma_f32_16x16x32_bf16 v[28:31], v[124:127], v[84:87], v[28:31]
	v_mfma_f32_16x16x32_bf16 v[32:35], v[112:115], v[88:91], v[32:35]
	v_mfma_f32_16x16x32_bf16 v[36:39], v[116:119], v[88:91], v[36:39]
	v_mfma_f32_16x16x32_bf16 v[40:43], v[120:123], v[88:91], v[40:43]
	v_mfma_f32_16x16x32_bf16 v[44:47], v[124:127], v[88:91], v[44:47]
	v_mfma_f32_16x16x32_bf16 v[48:51], v[112:115], v[92:95], v[48:51]
	v_mfma_f32_16x16x32_bf16 v[52:55], v[116:119], v[92:95], v[52:55]
	v_mfma_f32_16x16x32_bf16 v[56:59], v[120:123], v[92:95], v[56:59]
	v_mfma_f32_16x16x32_bf16 v[60:63], v[124:127], v[92:95], v[60:63]
	ds_read_b128 v[80:83], v253 offset:16384
	ds_read_b128 v[112:115], v255 offset:49152
	ds_read_b128 v[116:119], v255 offset:51200
	ds_read_b128 v[120:123], v255 offset:53248
	ds_read_b128 v[124:127], v255 offset:55296
	ds_read_b128 v[84:87], v253 offset:18432
	ds_read_b128 v[88:91], v253 offset:20480
	ds_read_b128 v[92:95], v253 offset:22528
	s_waitcnt lgkmcnt(14)
	v_mfma_f32_16x16x32_bf16 v[0:3], v[96:99], v[64:67], v[0:3]
	s_waitcnt lgkmcnt(13)
	v_mfma_f32_16x16x32_bf16 v[4:7], v[100:103], v[64:67], v[4:7]
	s_waitcnt lgkmcnt(12)
	v_mfma_f32_16x16x32_bf16 v[8:11], v[104:107], v[64:67], v[8:11]
	s_waitcnt lgkmcnt(11)
	v_mfma_f32_16x16x32_bf16 v[12:15], v[108:111], v[64:67], v[12:15]
	s_waitcnt lgkmcnt(10)
	v_mfma_f32_16x16x32_bf16 v[16:19], v[96:99], v[68:71], v[16:19]
	v_mfma_f32_16x16x32_bf16 v[20:23], v[100:103], v[68:71], v[20:23]
	v_mfma_f32_16x16x32_bf16 v[24:27], v[104:107], v[68:71], v[24:27]
	v_mfma_f32_16x16x32_bf16 v[28:31], v[108:111], v[68:71], v[28:31]
	s_waitcnt lgkmcnt(0)
	s_barrier
	v_mfma_f32_16x16x32_bf16 v[32:35], v[96:99], v[72:75], v[32:35]
	v_mfma_f32_16x16x32_bf16 v[36:39], v[100:103], v[72:75], v[36:39]
	v_mfma_f32_16x16x32_bf16 v[40:43], v[104:107], v[72:75], v[40:43]
	v_mfma_f32_16x16x32_bf16 v[44:47], v[108:111], v[72:75], v[44:47]
	v_mfma_f32_16x16x32_bf16 v[48:51], v[96:99], v[76:79], v[48:51]
	v_mfma_f32_16x16x32_bf16 v[52:55], v[100:103], v[76:79], v[52:55]
	v_mfma_f32_16x16x32_bf16 v[56:59], v[104:107], v[76:79], v[56:59]
	v_mfma_f32_16x16x32_bf16 v[60:63], v[108:111], v[76:79], v[60:63]
	v_mfma_f32_16x16x32_bf16 v[0:3], v[112:115], v[80:83], v[0:3]
	v_mfma_f32_16x16x32_bf16 v[4:7], v[116:119], v[80:83], v[4:7]
	v_mfma_f32_16x16x32_bf16 v[8:11], v[120:123], v[80:83], v[8:11]
	v_mfma_f32_16x16x32_bf16 v[12:15], v[124:127], v[80:83], v[12:15]
	v_mfma_f32_16x16x32_bf16 v[16:19], v[112:115], v[84:87], v[16:19]
	v_mfma_f32_16x16x32_bf16 v[20:23], v[116:119], v[84:87], v[20:23]
	v_mfma_f32_16x16x32_bf16 v[24:27], v[120:123], v[84:87], v[24:27]
	v_mfma_f32_16x16x32_bf16 v[28:31], v[124:127], v[84:87], v[28:31]
	v_mfma_f32_16x16x32_bf16 v[32:35], v[112:115], v[88:91], v[32:35]
	v_mfma_f32_16x16x32_bf16 v[36:39], v[116:119], v[88:91], v[36:39]
	v_mfma_f32_16x16x32_bf16 v[40:43], v[120:123], v[88:91], v[40:43]
	v_mfma_f32_16x16x32_bf16 v[44:47], v[124:127], v[88:91], v[44:47]
	v_mfma_f32_16x16x32_bf16 v[48:51], v[112:115], v[92:95], v[48:51]
	v_mfma_f32_16x16x32_bf16 v[52:55], v[116:119], v[92:95], v[52:55]
	v_mfma_f32_16x16x32_bf16 v[56:59], v[120:123], v[92:95], v[56:59]
	v_mfma_f32_16x16x32_bf16 v[60:63], v[124:127], v[92:95], v[60:63]
	s_nop 7
	s_nop 1
	v_mul_f32_e32 v130, 0xbfb8aa3b, v0
	v_mul_f32_e32 v131, 0xbfb8aa3b, v1
	v_mul_f32_e32 v132, 0xbfb8aa3b, v2
	v_mul_f32_e32 v133, 0xbfb8aa3b, v3
	v_mul_f32_e32 v134, 0xbfb8aa3b, v4
	v_mul_f32_e32 v135, 0xbfb8aa3b, v5
	v_mul_f32_e32 v136, 0xbfb8aa3b, v6
	v_mul_f32_e32 v137, 0xbfb8aa3b, v7
	v_exp_f32_e32 v130, v130
	v_exp_f32_e32 v131, v131
	v_exp_f32_e32 v132, v132
	v_exp_f32_e32 v133, v133
	v_exp_f32_e32 v134, v134
	v_exp_f32_e32 v135, v135
	v_exp_f32_e32 v136, v136
	v_exp_f32_e32 v137, v137
	v_add_f32_e32 v130, 1.0, v130
	v_add_f32_e32 v131, 1.0, v131
	v_add_f32_e32 v132, 1.0, v132
	v_add_f32_e32 v133, 1.0, v133
	v_add_f32_e32 v134, 1.0, v134
	v_add_f32_e32 v135, 1.0, v135
	v_add_f32_e32 v136, 1.0, v136
	v_add_f32_e32 v137, 1.0, v137
	v_rcp_f32_e32 v130, v130
	v_rcp_f32_e32 v131, v131
	v_rcp_f32_e32 v132, v132
	v_rcp_f32_e32 v133, v133
	v_rcp_f32_e32 v134, v134
	v_rcp_f32_e32 v135, v135
	v_rcp_f32_e32 v136, v136
	v_rcp_f32_e32 v137, v137
	v_mul_f32_e32 v130, v0, v130
	v_mul_f32_e32 v131, v1, v131
	v_mul_f32_e32 v132, v2, v132
	v_mul_f32_e32 v133, v3, v133
	v_mul_f32_e32 v134, v4, v134
	v_mul_f32_e32 v135, v5, v135
	v_mul_f32_e32 v136, v6, v136
	v_mul_f32_e32 v137, v7, v137
	v_mul_f32_e32 v130, v8, v130
	v_mul_f32_e32 v131, v9, v131
	v_mul_f32_e32 v132, v10, v132
	v_mul_f32_e32 v133, v11, v133
	v_mul_f32_e32 v134, v12, v134
	v_mul_f32_e32 v135, v13, v135
	v_mul_f32_e32 v136, v14, v136
	v_mul_f32_e32 v137, v15, v137
	v_cvt_pk_bf16_f32 v0, v130, v131
	v_cvt_pk_bf16_f32 v1, v132, v133
	v_cvt_pk_bf16_f32 v2, v134, v135
	v_cvt_pk_bf16_f32 v3, v136, v137
	ds_write_b64 v245, v[0:1] offset:0
	ds_write_b64 v245, v[2:3] offset:32
	v_mul_f32_e32 v130, 0xbfb8aa3b, v16
	v_mul_f32_e32 v131, 0xbfb8aa3b, v17
	v_mul_f32_e32 v132, 0xbfb8aa3b, v18
	v_mul_f32_e32 v133, 0xbfb8aa3b, v19
	v_mul_f32_e32 v134, 0xbfb8aa3b, v20
	v_mul_f32_e32 v135, 0xbfb8aa3b, v21
	v_mul_f32_e32 v136, 0xbfb8aa3b, v22
	v_mul_f32_e32 v137, 0xbfb8aa3b, v23
	v_exp_f32_e32 v130, v130
	v_exp_f32_e32 v131, v131
	v_exp_f32_e32 v132, v132
	v_exp_f32_e32 v133, v133
	v_exp_f32_e32 v134, v134
	v_exp_f32_e32 v135, v135
	v_exp_f32_e32 v136, v136
	v_exp_f32_e32 v137, v137
	v_add_f32_e32 v130, 1.0, v130
	v_add_f32_e32 v131, 1.0, v131
	v_add_f32_e32 v132, 1.0, v132
	v_add_f32_e32 v133, 1.0, v133
	v_add_f32_e32 v134, 1.0, v134
	v_add_f32_e32 v135, 1.0, v135
	v_add_f32_e32 v136, 1.0, v136
	v_add_f32_e32 v137, 1.0, v137
	v_rcp_f32_e32 v130, v130
	v_rcp_f32_e32 v131, v131
	v_rcp_f32_e32 v132, v132
	v_rcp_f32_e32 v133, v133
	v_rcp_f32_e32 v134, v134
	v_rcp_f32_e32 v135, v135
	v_rcp_f32_e32 v136, v136
	v_rcp_f32_e32 v137, v137
	v_mul_f32_e32 v130, v16, v130
	v_mul_f32_e32 v131, v17, v131
	v_mul_f32_e32 v132, v18, v132
	v_mul_f32_e32 v133, v19, v133
	v_mul_f32_e32 v134, v20, v134
	v_mul_f32_e32 v135, v21, v135
	v_mul_f32_e32 v136, v22, v136
	v_mul_f32_e32 v137, v23, v137
	v_mul_f32_e32 v130, v24, v130
	v_mul_f32_e32 v131, v25, v131
	v_mul_f32_e32 v132, v26, v132
	v_mul_f32_e32 v133, v27, v133
	v_mul_f32_e32 v134, v28, v134
	v_mul_f32_e32 v135, v29, v135
	v_mul_f32_e32 v136, v30, v136
	v_mul_f32_e32 v137, v31, v137
	v_cvt_pk_bf16_f32 v16, v130, v131
	v_cvt_pk_bf16_f32 v17, v132, v133
	v_cvt_pk_bf16_f32 v18, v134, v135
	v_cvt_pk_bf16_f32 v19, v136, v137
	ds_write_b64 v245, v[16:17] offset:1280
	ds_write_b64 v245, v[18:19] offset:1312
	v_mul_f32_e32 v130, 0xbfb8aa3b, v32
	v_mul_f32_e32 v131, 0xbfb8aa3b, v33
	v_mul_f32_e32 v132, 0xbfb8aa3b, v34
	v_mul_f32_e32 v133, 0xbfb8aa3b, v35
	v_mul_f32_e32 v134, 0xbfb8aa3b, v36
	v_mul_f32_e32 v135, 0xbfb8aa3b, v37
	v_mul_f32_e32 v136, 0xbfb8aa3b, v38
	v_mul_f32_e32 v137, 0xbfb8aa3b, v39
	v_exp_f32_e32 v130, v130
	v_exp_f32_e32 v131, v131
	v_exp_f32_e32 v132, v132
	v_exp_f32_e32 v133, v133
	v_exp_f32_e32 v134, v134
	v_exp_f32_e32 v135, v135
	v_exp_f32_e32 v136, v136
	v_exp_f32_e32 v137, v137
	v_add_f32_e32 v130, 1.0, v130
	v_add_f32_e32 v131, 1.0, v131
	v_add_f32_e32 v132, 1.0, v132
	v_add_f32_e32 v133, 1.0, v133
	v_add_f32_e32 v134, 1.0, v134
	v_add_f32_e32 v135, 1.0, v135
	v_add_f32_e32 v136, 1.0, v136
	v_add_f32_e32 v137, 1.0, v137
	v_rcp_f32_e32 v130, v130
	v_rcp_f32_e32 v131, v131
	v_rcp_f32_e32 v132, v132
	v_rcp_f32_e32 v133, v133
	v_rcp_f32_e32 v134, v134
	v_rcp_f32_e32 v135, v135
	v_rcp_f32_e32 v136, v136
	v_rcp_f32_e32 v137, v137
	v_mul_f32_e32 v130, v32, v130
	v_mul_f32_e32 v131, v33, v131
	v_mul_f32_e32 v132, v34, v132
	v_mul_f32_e32 v133, v35, v133
	v_mul_f32_e32 v134, v36, v134
	v_mul_f32_e32 v135, v37, v135
	v_mul_f32_e32 v136, v38, v136
	v_mul_f32_e32 v137, v39, v137
	v_mul_f32_e32 v130, v40, v130
	v_mul_f32_e32 v131, v41, v131
	v_mul_f32_e32 v132, v42, v132
	v_mul_f32_e32 v133, v43, v133
	v_mul_f32_e32 v134, v44, v134
	v_mul_f32_e32 v135, v45, v135
	v_mul_f32_e32 v136, v46, v136
	v_mul_f32_e32 v137, v47, v137
	v_cvt_pk_bf16_f32 v32, v130, v131
	v_cvt_pk_bf16_f32 v33, v132, v133
	v_cvt_pk_bf16_f32 v34, v134, v135
	v_cvt_pk_bf16_f32 v35, v136, v137
	ds_write_b64 v245, v[32:33] offset:2560
	ds_write_b64 v245, v[34:35] offset:2592
	v_mul_f32_e32 v130, 0xbfb8aa3b, v48
	v_mul_f32_e32 v131, 0xbfb8aa3b, v49
	v_mul_f32_e32 v132, 0xbfb8aa3b, v50
	v_mul_f32_e32 v133, 0xbfb8aa3b, v51
	v_mul_f32_e32 v134, 0xbfb8aa3b, v52
	v_mul_f32_e32 v135, 0xbfb8aa3b, v53
	v_mul_f32_e32 v136, 0xbfb8aa3b, v54
	v_mul_f32_e32 v137, 0xbfb8aa3b, v55
	v_exp_f32_e32 v130, v130
	v_exp_f32_e32 v131, v131
	v_exp_f32_e32 v132, v132
	v_exp_f32_e32 v133, v133
	v_exp_f32_e32 v134, v134
	v_exp_f32_e32 v135, v135
	v_exp_f32_e32 v136, v136
	v_exp_f32_e32 v137, v137
	v_add_f32_e32 v130, 1.0, v130
	v_add_f32_e32 v131, 1.0, v131
	v_add_f32_e32 v132, 1.0, v132
	v_add_f32_e32 v133, 1.0, v133
	v_add_f32_e32 v134, 1.0, v134
	v_add_f32_e32 v135, 1.0, v135
	v_add_f32_e32 v136, 1.0, v136
	v_add_f32_e32 v137, 1.0, v137
	v_rcp_f32_e32 v130, v130
	v_rcp_f32_e32 v131, v131
	v_rcp_f32_e32 v132, v132
	v_rcp_f32_e32 v133, v133
	v_rcp_f32_e32 v134, v134
	v_rcp_f32_e32 v135, v135
	v_rcp_f32_e32 v136, v136
	v_rcp_f32_e32 v137, v137
	v_mul_f32_e32 v130, v48, v130
	v_mul_f32_e32 v131, v49, v131
	v_mul_f32_e32 v132, v50, v132
	v_mul_f32_e32 v133, v51, v133
	v_mul_f32_e32 v134, v52, v134
	v_mul_f32_e32 v135, v53, v135
	v_mul_f32_e32 v136, v54, v136
	v_mul_f32_e32 v137, v55, v137
	v_mul_f32_e32 v130, v56, v130
	v_mul_f32_e32 v131, v57, v131
	v_mul_f32_e32 v132, v58, v132
	v_mul_f32_e32 v133, v59, v133
	v_mul_f32_e32 v134, v60, v134
	v_mul_f32_e32 v135, v61, v135
	v_mul_f32_e32 v136, v62, v136
	v_mul_f32_e32 v137, v63, v137
	v_cvt_pk_bf16_f32 v48, v130, v131
	v_cvt_pk_bf16_f32 v49, v132, v133
	v_cvt_pk_bf16_f32 v50, v134, v135
	v_cvt_pk_bf16_f32 v51, v136, v137
	ds_write_b64 v245, v[48:49] offset:3840
	ds_write_b64 v245, v[50:51] offset:3872
	s_waitcnt lgkmcnt(0)
	ds_read_b128 v[138:141], v246 offset:0
	ds_read_b128 v[142:145], v246 offset:1280
	ds_read_b128 v[146:149], v246 offset:2560
	ds_read_b128 v[150:153], v246 offset:3840
	s_mov_b64 s[18:19], s[20:21]
	s_waitcnt lgkmcnt(3)
	global_store_dwordx4 v239, v[138:141], s[18:19]
	s_add_u32 s18, s18, 0x16000
	s_addc_u32 s19, s19, 0
	s_waitcnt lgkmcnt(2)
	global_store_dwordx4 v239, v[142:145], s[18:19]
	s_add_u32 s18, s18, 0x16000
	s_addc_u32 s19, s19, 0
	s_waitcnt lgkmcnt(1)
	global_store_dwordx4 v239, v[146:149], s[18:19]
	s_add_u32 s18, s18, 0x16000
	s_addc_u32 s19, s19, 0
	s_waitcnt lgkmcnt(0)
	global_store_dwordx4 v239, v[150:153], s[18:19]
	s_barrier
	s_add_u32 s15, s15, s16
	s_branch .Lf8_tile

.Lr9_tile:
	s_cmp_lt_u32 s15, 0x200
	s_cbranch_scc0 .Lr9_end
	s_and_b32 s2, s15, 63
	s_lshr_b32 s3, s15, 6
	s_mul_i32 s14, s2, 0xb0000
	s_add_u32 s8, s26, s14
	s_addc_u32 s9, s27, 0
	s_mul_i32 s14, s3, 0xb0000
	s_add_u32 s10, s28, s14
	s_addc_u32 s11, s29, 0
	s_lshl_b32 s14, s2, 19
	s_lshl_b32 s6, s3, 9
	s_add_u32 s14, s14, s6
	s_add_u32 s20, s4, 0x6b7a100
	s_addc_u32 s21, s5, 0
	s_add_u32 s20, s20, s14
	s_addc_u32 s21, s21, 0
	s_sub_u32 s7, s2, 32
	s_lshr_b32 s7, s7, 3
	s_add_u32 s7, s7, 1
	s_cmp_lt_u32 s2, 32
	s_cselect_b32 s7, 0, s7
	s_mul_i32 s7, s7, 0x6000
	s_add_u32 s7, s7, s6
	s_add_u32 s22, s4, 0x6b07000
	s_addc_u32 s23, s5, 0
	s_add_u32 s22, s22, s7
	s_addc_u32 s23, s23, 0
	v_readfirstlane_b32 s12, v247
	s_lshl_b32 s12, s12, 12
	s_add_u32 m0, s12, 0x0
	v_mov_b32_e32 v0, 0
	global_load_lds_dwordx4 v248, s[8:9]
	v_mov_b32_e32 v1, 0
	s_add_u32 m0, s12, 0x400
	v_mov_b32_e32 v2, 0
	global_load_lds_dwordx4 v249, s[8:9]
	v_mov_b32_e32 v3, 0
	s_add_u32 m0, s12, 0x800
	v_mov_b32_e32 v4, 0
	global_load_lds_dwordx4 v250, s[8:9]
	v_mov_b32_e32 v5, 0
	s_add_u32 m0, s12, 0xc00
	v_mov_b32_e32 v6, 0
	global_load_lds_dwordx4 v251, s[8:9]
	v_mov_b32_e32 v7, 0
	s_add_u32 m0, s12, 0x8000
	v_mov_b32_e32 v8, 0
	global_load_lds_dwordx4 v248, s[10:11] sc1
	v_mov_b32_e32 v9, 0
	s_add_u32 m0, s12, 0x8400
	v_mov_b32_e32 v10, 0
	global_load_lds_dwordx4 v249, s[10:11] sc1
	v_mov_b32_e32 v11, 0
	s_add_u32 m0, s12, 0x8800
	v_mov_b32_e32 v12, 0
	global_load_lds_dwordx4 v250, s[10:11] sc1
	v_mov_b32_e32 v13, 0
	s_add_u32 m0, s12, 0x8c00
	v_mov_b32_e32 v14, 0
	global_load_lds_dwordx4 v251, s[10:11] sc1
	v_mov_b32_e32 v15, 0
	s_add_u32 s8, s8, 0x80
	s_addc_u32 s9, s9, 0
	s_add_u32 s10, s10, 0x80
	s_addc_u32 s11, s11, 0
	s_add_u32 m0, s12, 0x4000
	v_mov_b32_e32 v16, 0
	global_load_lds_dwordx4 v248, s[8:9]
	v_mov_b32_e32 v17, 0
	s_add_u32 m0, s12, 0x4400
	v_mov_b32_e32 v18, 0
	global_load_lds_dwordx4 v249, s[8:9]
	v_mov_b32_e32 v19, 0
	s_add_u32 m0, s12, 0x4800
	v_mov_b32_e32 v20, 0
	global_load_lds_dwordx4 v250, s[8:9]
	v_mov_b32_e32 v21, 0
	s_add_u32 m0, s12, 0x4c00
	v_mov_b32_e32 v22, 0
	global_load_lds_dwordx4 v251, s[8:9]
	v_mov_b32_e32 v23, 0
	s_add_u32 m0, s12, 0xc000
	v_mov_b32_e32 v24, 0
	global_load_lds_dwordx4 v248, s[10:11] sc1
	v_mov_b32_e32 v25, 0
	s_add_u32 m0, s12, 0xc400
	v_mov_b32_e32 v26, 0
	global_load_lds_dwordx4 v249, s[10:11] sc1
	v_mov_b32_e32 v27, 0
	s_add_u32 m0, s12, 0xc800
	v_mov_b32_e32 v28, 0
	global_load_lds_dwordx4 v250, s[10:11] sc1
	v_mov_b32_e32 v29, 0
	s_add_u32 m0, s12, 0xcc00
	v_mov_b32_e32 v30, 0
	global_load_lds_dwordx4 v251, s[10:11] sc1
	v_mov_b32_e32 v31, 0
	s_add_u32 s8, s8, 0x80
	s_addc_u32 s9, s9, 0
	s_add_u32 s10, s10, 0x80
	s_addc_u32 s11, s11, 0
	v_mov_b32_e32 v32, 0
	v_mov_b32_e32 v33, 0
	v_mov_b32_e32 v34, 0
	v_mov_b32_e32 v35, 0
	v_mov_b32_e32 v36, 0
	v_mov_b32_e32 v37, 0
	v_mov_b32_e32 v38, 0
	v_mov_b32_e32 v39, 0
	v_mov_b32_e32 v40, 0
	v_mov_b32_e32 v41, 0
	v_mov_b32_e32 v42, 0
	v_mov_b32_e32 v43, 0
	v_mov_b32_e32 v44, 0
	v_mov_b32_e32 v45, 0
	v_mov_b32_e32 v46, 0
	v_mov_b32_e32 v47, 0
	v_mov_b32_e32 v48, 0
	v_mov_b32_e32 v49, 0
	v_mov_b32_e32 v50, 0
	v_mov_b32_e32 v51, 0
	v_mov_b32_e32 v52, 0
	v_mov_b32_e32 v53, 0
	v_mov_b32_e32 v54, 0
	v_mov_b32_e32 v55, 0
	v_mov_b32_e32 v56, 0
	v_mov_b32_e32 v57, 0
	v_mov_b32_e32 v58, 0
	v_mov_b32_e32 v59, 0
	v_mov_b32_e32 v60, 0
	v_mov_b32_e32 v61, 0
	v_mov_b32_e32 v62, 0
	v_mov_b32_e32 v63, 0
	global_load_dword v201, v245, s[22:23] offset:0
	global_load_dword v202, v245, s[22:23] offset:64
	global_load_dword v203, v245, s[22:23] offset:128
	global_load_dword v204, v245, s[22:23] offset:192
	s_mov_b64 s[18:19], s[20:21]
	global_load_dword v129, v246, s[18:19] offset:0
	global_load_dword v130, v246, s[18:19] offset:64
	global_load_dword v131, v246, s[18:19] offset:128
	global_load_dword v132, v246, s[18:19] offset:192
	s_add_u32 s18, s18, 0x1000
	s_addc_u32 s19, s19, 0
	global_load_dword v133, v246, s[18:19] offset:0
	global_load_dword v134, v246, s[18:19] offset:64
	global_load_dword v135, v246, s[18:19] offset:128
	global_load_dword v136, v246, s[18:19] offset:192
	s_add_u32 s18, s18, 0x1000
	s_addc_u32 s19, s19, 0
	global_load_dword v137, v246, s[18:19] offset:0
	global_load_dword v138, v246, s[18:19] offset:64
	global_load_dword v139, v246, s[18:19] offset:128
	global_load_dword v140, v246, s[18:19] offset:192
	s_add_u32 s18, s18, 0x1000
	s_addc_u32 s19, s19, 0
	global_load_dword v141, v246, s[18:19] offset:0
	global_load_dword v142, v246, s[18:19] offset:64
	global_load_dword v143, v246, s[18:19] offset:128
	global_load_dword v144, v246, s[18:19] offset:192
	s_add_u32 s18, s18, 0xd000
	s_addc_u32 s19, s19, 0
	global_load_dword v145, v246, s[18:19] offset:0
	global_load_dword v146, v246, s[18:19] offset:64
	global_load_dword v147, v246, s[18:19] offset:128
	global_load_dword v148, v246, s[18:19] offset:192
	s_add_u32 s18, s18, 0x1000
	s_addc_u32 s19, s19, 0
	global_load_dword v149, v246, s[18:19] offset:0
	global_load_dword v150, v246, s[18:19] offset:64
	global_load_dword v151, v246, s[18:19] offset:128
	global_load_dword v152, v246, s[18:19] offset:192
	s_add_u32 s18, s18, 0x1000
	s_addc_u32 s19, s19, 0
	global_load_dword v153, v246, s[18:19] offset:0
	global_load_dword v154, v246, s[18:19] offset:64
	global_load_dword v155, v246, s[18:19] offset:128
	global_load_dword v156, v246, s[18:19] offset:192
	s_add_u32 s18, s18, 0x1000
	s_addc_u32 s19, s19, 0
	global_load_dword v157, v246, s[18:19] offset:0
	global_load_dword v158, v246, s[18:19] offset:64
	global_load_dword v159, v246, s[18:19] offset:128
	global_load_dword v160, v246, s[18:19] offset:192
	s_add_u32 s18, s18, 0xd000
	s_addc_u32 s19, s19, 0
	global_load_dword v161, v246, s[18:19] offset:0
	global_load_dword v170, v246, s[18:19] offset:64
	global_load_dword v171, v246, s[18:19] offset:128
	global_load_dword v172, v246, s[18:19] offset:192
	s_add_u32 s18, s18, 0x1000
	s_addc_u32 s19, s19, 0
	global_load_dword v173, v246, s[18:19] offset:0
	global_load_dword v174, v246, s[18:19] offset:64
	global_load_dword v175, v246, s[18:19] offset:128
	global_load_dword v176, v246, s[18:19] offset:192
	s_add_u32 s18, s18, 0x1000
	s_addc_u32 s19, s19, 0
	global_load_dword v177, v246, s[18:19] offset:0
	global_load_dword v178, v246, s[18:19] offset:64
	global_load_dword v179, v246, s[18:19] offset:128
	global_load_dword v180, v246, s[18:19] offset:192
	s_add_u32 s18, s18, 0x1000
	s_addc_u32 s19, s19, 0
	global_load_dword v181, v246, s[18:19] offset:0
	global_load_dword v182, v246, s[18:19] offset:64
	global_load_dword v183, v246, s[18:19] offset:128
	global_load_dword v184, v246, s[18:19] offset:192
	s_add_u32 s18, s18, 0xd000
	s_addc_u32 s19, s19, 0
	global_load_dword v185, v246, s[18:19] offset:0
	global_load_dword v186, v246, s[18:19] offset:64
	global_load_dword v187, v246, s[18:19] offset:128
	global_load_dword v188, v246, s[18:19] offset:192
	s_add_u32 s18, s18, 0x1000
	s_addc_u32 s19, s19, 0
	global_load_dword v189, v246, s[18:19] offset:0
	global_load_dword v190, v246, s[18:19] offset:64
	global_load_dword v191, v246, s[18:19] offset:128
	global_load_dword v192, v246, s[18:19] offset:192
	s_add_u32 s18, s18, 0x1000
	s_addc_u32 s19, s19, 0
	global_load_dword v193, v246, s[18:19] offset:0
	global_load_dword v194, v246, s[18:19] offset:64
	global_load_dword v195, v246, s[18:19] offset:128
	global_load_dword v196, v246, s[18:19] offset:192
	s_add_u32 s18, s18, 0x1000
	s_addc_u32 s19, s19, 0
	global_load_dword v197, v246, s[18:19] offset:0
	global_load_dword v198, v246, s[18:19] offset:64
	global_load_dword v199, v246, s[18:19] offset:128
	global_load_dword v200, v246, s[18:19] offset:192
	s_waitcnt vmcnt(63)
	s_barrier
	ds_read_b128 v[64:67], v252 offset:0
	ds_read_b128 v[96:99], v254 offset:32768
	ds_read_b128 v[100:103], v254 offset:34816
	ds_read_b128 v[104:107], v254 offset:36864
	ds_read_b128 v[108:111], v254 offset:38912
	ds_read_b128 v[68:71], v252 offset:2048
	ds_read_b128 v[72:75], v252 offset:4096
	ds_read_b128 v[76:79], v252 offset:6144
	ds_read_b128 v[80:83], v253 offset:0
	ds_read_b128 v[112:115], v255 offset:32768
	ds_read_b128 v[116:119], v255 offset:34816
	ds_read_b128 v[120:123], v255 offset:36864
	ds_read_b128 v[124:127], v255 offset:38912
	s_waitcnt lgkmcnt(11)
	v_mfma_f32_16x16x32_bf16 v[0:3], v[64:67], v[96:99], v[0:3]
	s_waitcnt lgkmcnt(10)
	v_mfma_f32_16x16x32_bf16 v[4:7], v[64:67], v[100:103], v[4:7]
	s_waitcnt lgkmcnt(9)
	v_mfma_f32_16x16x32_bf16 v[8:11], v[64:67], v[104:107], v[8:11]
	s_waitcnt lgkmcnt(8)
	v_mfma_f32_16x16x32_bf16 v[12:15], v[64:67], v[108:111], v[12:15]
	ds_read_b128 v[84:87], v253 offset:2048
	ds_read_b128 v[88:91], v253 offset:4096
	ds_read_b128 v[92:95], v253 offset:6144
	s_waitcnt lgkmcnt(10)
	v_mfma_f32_16x16x32_bf16 v[16:19], v[68:71], v[96:99], v[16:19]
	v_mfma_f32_16x16x32_bf16 v[20:23], v[68:71], v[100:103], v[20:23]
	v_mfma_f32_16x16x32_bf16 v[24:27], v[68:71], v[104:107], v[24:27]
	v_mfma_f32_16x16x32_bf16 v[28:31], v[68:71], v[108:111], v[28:31]
	s_waitcnt lgkmcnt(0)
	s_barrier
	s_add_u32 m0, s12, 0x0
	v_mfma_f32_16x16x32_bf16 v[32:35], v[72:75], v[96:99], v[32:35]
	global_load_lds_dwordx4 v248, s[8:9]
	s_add_u32 m0, s12, 0x400
	v_mfma_f32_16x16x32_bf16 v[36:39], v[72:75], v[100:103], v[36:39]
	global_load_lds_dwordx4 v249, s[8:9]
	s_add_u32 m0, s12, 0x800
	v_mfma_f32_16x16x32_bf16 v[40:43], v[72:75], v[104:107], v[40:43]
	global_load_lds_dwordx4 v250, s[8:9]
	s_add_u32 m0, s12, 0xc00
	v_mfma_f32_16x16x32_bf16 v[44:47], v[72:75], v[108:111], v[44:47]
	global_load_lds_dwordx4 v251, s[8:9]
	s_add_u32 m0, s12, 0x8000
	v_mfma_f32_16x16x32_bf16 v[48:51], v[76:79], v[96:99], v[48:51]
	global_load_lds_dwordx4 v248, s[10:11] sc1
	s_add_u32 m0, s12, 0x8400
	v_mfma_f32_16x16x32_bf16 v[52:55], v[76:79], v[100:103], v[52:55]
	global_load_lds_dwordx4 v249, s[10:11] sc1
	s_add_u32 m0, s12, 0x8800
	v_mfma_f32_16x16x32_bf16 v[56:59], v[76:79], v[104:107], v[56:59]
	global_load_lds_dwordx4 v250, s[10:11] sc1
	s_add_u32 m0, s12, 0x8c00
	v_mfma_f32_16x16x32_bf16 v[60:63], v[76:79], v[108:111], v[60:63]
	global_load_lds_dwordx4 v251, s[10:11] sc1
	s_add_u32 s8, s8, 0x80
	s_addc_u32 s9, s9, 0
	s_add_u32 s10, s10, 0x80
	s_addc_u32 s11, s11, 0
	s_waitcnt vmcnt(63)
	s_barrier
	ds_read_b128 v[64:67], v252 offset:16384
	ds_read_b128 v[96:99], v254 offset:49152
	ds_read_b128 v[100:103], v254 offset:51200
	ds_read_b128 v[104:107], v254 offset:53248
	ds_read_b128 v[108:111], v254 offset:55296
	ds_read_b128 v[68:71], v252 offset:18432
	ds_read_b128 v[72:75], v252 offset:20480
	ds_read_b128 v[76:79], v252 offset:22528
	v_mfma_f32_16x16x32_bf16 v[0:3], v[80:83], v[112:115], v[0:3]
	v_mfma_f32_16x16x32_bf16 v[4:7], v[80:83], v[116:119], v[4:7]
	v_mfma_f32_16x16x32_bf16 v[8:11], v[80:83], v[120:123], v[8:11]
	v_mfma_f32_16x16x32_bf16 v[12:15], v[80:83], v[124:127], v[12:15]
	v_mfma_f32_16x16x32_bf16 v[16:19], v[84:87], v[112:115], v[16:19]
	v_mfma_f32_16x16x32_bf16 v[20:23], v[84:87], v[116:119], v[20:23]
	v_mfma_f32_16x16x32_bf16 v[24:27], v[84:87], v[120:123], v[24:27]
	v_mfma_f32_16x16x32_bf16 v[28:31], v[84:87], v[124:127], v[28:31]
	v_mfma_f32_16x16x32_bf16 v[32:35], v[88:91], v[112:115], v[32:35]
	v_mfma_f32_16x16x32_bf16 v[36:39], v[88:91], v[116:119], v[36:39]
	v_mfma_f32_16x16x32_bf16 v[40:43], v[88:91], v[120:123], v[40:43]
	v_mfma_f32_16x16x32_bf16 v[44:47], v[88:91], v[124:127], v[44:47]
	v_mfma_f32_16x16x32_bf16 v[48:51], v[92:95], v[112:115], v[48:51]
	v_mfma_f32_16x16x32_bf16 v[52:55], v[92:95], v[116:119], v[52:55]
	v_mfma_f32_16x16x32_bf16 v[56:59], v[92:95], v[120:123], v[56:59]
	v_mfma_f32_16x16x32_bf16 v[60:63], v[92:95], v[124:127], v[60:63]
	ds_read_b128 v[80:83], v253 offset:16384
	ds_read_b128 v[112:115], v255 offset:49152
	ds_read_b128 v[116:119], v255 offset:51200
	ds_read_b128 v[120:123], v255 offset:53248
	ds_read_b128 v[124:127], v255 offset:55296
	ds_read_b128 v[84:87], v253 offset:18432
	ds_read_b128 v[88:91], v253 offset:20480
	ds_read_b128 v[92:95], v253 offset:22528
	s_waitcnt lgkmcnt(14)
	v_mfma_f32_16x16x32_bf16 v[0:3], v[64:67], v[96:99], v[0:3]
	s_waitcnt lgkmcnt(13)
	v_mfma_f32_16x16x32_bf16 v[4:7], v[64:67], v[100:103], v[4:7]
	s_waitcnt lgkmcnt(12)
	v_mfma_f32_16x16x32_bf16 v[8:11], v[64:67], v[104:107], v[8:11]
	s_waitcnt lgkmcnt(11)
	v_mfma_f32_16x16x32_bf16 v[12:15], v[64:67], v[108:111], v[12:15]
	s_waitcnt lgkmcnt(10)
	v_mfma_f32_16x16x32_bf16 v[16:19], v[68:71], v[96:99], v[16:19]
	v_mfma_f32_16x16x32_bf16 v[20:23], v[68:71], v[100:103], v[20:23]
	v_mfma_f32_16x16x32_bf16 v[24:27], v[68:71], v[104:107], v[24:27]
	v_mfma_f32_16x16x32_bf16 v[28:31], v[68:71], v[108:111], v[28:31]
	s_waitcnt lgkmcnt(0)
	s_barrier
	s_add_u32 m0, s12, 0x4000
	v_mfma_f32_16x16x32_bf16 v[32:35], v[72:75], v[96:99], v[32:35]
	global_load_lds_dwordx4 v248, s[8:9]
	s_add_u32 m0, s12, 0x4400
	v_mfma_f32_16x16x32_bf16 v[36:39], v[72:75], v[100:103], v[36:39]
	global_load_lds_dwordx4 v249, s[8:9]
	s_add_u32 m0, s12, 0x4800
	v_mfma_f32_16x16x32_bf16 v[40:43], v[72:75], v[104:107], v[40:43]
	global_load_lds_dwordx4 v250, s[8:9]
	s_add_u32 m0, s12, 0x4c00
	v_mfma_f32_16x16x32_bf16 v[44:47], v[72:75], v[108:111], v[44:47]
	global_load_lds_dwordx4 v251, s[8:9]
	s_add_u32 m0, s12, 0xc000
	v_mfma_f32_16x16x32_bf16 v[48:51], v[76:79], v[96:99], v[48:51]
	global_load_lds_dwordx4 v248, s[10:11] sc1
	s_add_u32 m0, s12, 0xc400
	v_mfma_f32_16x16x32_bf16 v[52:55], v[76:79], v[100:103], v[52:55]
	global_load_lds_dwordx4 v249, s[10:11] sc1
	s_add_u32 m0, s12, 0xc800
	v_mfma_f32_16x16x32_bf16 v[56:59], v[76:79], v[104:107], v[56:59]
	global_load_lds_dwordx4 v250, s[10:11] sc1
	s_add_u32 m0, s12, 0xcc00
	v_mfma_f32_16x16x32_bf16 v[60:63], v[76:79], v[108:111], v[60:63]
	global_load_lds_dwordx4 v251, s[10:11] sc1
	s_add_u32 s8, s8, 0x80
	s_addc_u32 s9, s9, 0
	s_add_u32 s10, s10, 0x80
	s_addc_u32 s11, s11, 0
	s_mov_b32 s13, 20

.Lr13_tile:
	s_cmp_lt_u32 s15, 0x200
	s_cbranch_scc0 .Lr13_end
	s_and_b32 s2, s15, 63
	s_lshr_b32 s3, s15, 6
	s_mul_i32 s14, s2, 0x40000
	s_add_u32 s8, s26, s14
	s_addc_u32 s9, s27, 0
	s_mul_i32 s14, s3, 0x40000
	s_add_u32 s10, s28, s14
	s_addc_u32 s11, s29, 0
	s_lshl_b32 s14, s2, 19
	s_lshl_b32 s6, s3, 9
	s_add_u32 s14, s14, s6
	s_add_u32 s20, s4, 0x6b7a100
	s_addc_u32 s21, s5, 0
	s_add_u32 s20, s20, s14
	s_addc_u32 s21, s21, 0
	s_sub_u32 s7, s2, 32
	s_lshr_b32 s7, s7, 3
	s_add_u32 s7, s7, 1
	s_cmp_lt_u32 s2, 32
	s_cselect_b32 s7, 0, s7
	s_mul_i32 s7, s7, 0x6000
	s_add_u32 s7, s7, s6
	s_add_u32 s22, s4, 0x6b22000
	s_addc_u32 s23, s5, 0
	s_add_u32 s22, s22, s7
	s_addc_u32 s23, s23, 0
	s_add_u32 s30, s24, 0x0
	s_addc_u32 s31, s25, 0
	s_add_u32 s30, s30, s6
	s_addc_u32 s31, s31, 0
	v_readfirstlane_b32 s12, v247
	s_lshl_b32 s12, s12, 12
	s_add_u32 m0, s12, 0x0
	v_mov_b32_e32 v0, 0
	global_load_lds_dwordx4 v248, s[8:9]
	v_mov_b32_e32 v1, 0
	s_add_u32 m0, s12, 0x400
	v_mov_b32_e32 v2, 0
	global_load_lds_dwordx4 v249, s[8:9]
	v_mov_b32_e32 v3, 0
	s_add_u32 m0, s12, 0x800
	v_mov_b32_e32 v4, 0
	global_load_lds_dwordx4 v250, s[8:9]
	v_mov_b32_e32 v5, 0
	s_add_u32 m0, s12, 0xc00
	v_mov_b32_e32 v6, 0
	global_load_lds_dwordx4 v251, s[8:9]
	v_mov_b32_e32 v7, 0
	s_add_u32 m0, s12, 0x8000
	v_mov_b32_e32 v8, 0
	global_load_lds_dwordx4 v248, s[10:11] sc1
	v_mov_b32_e32 v9, 0
	s_add_u32 m0, s12, 0x8400
	v_mov_b32_e32 v10, 0
	global_load_lds_dwordx4 v249, s[10:11] sc1
	v_mov_b32_e32 v11, 0
	s_add_u32 m0, s12, 0x8800
	v_mov_b32_e32 v12, 0
	global_load_lds_dwordx4 v250, s[10:11] sc1
	v_mov_b32_e32 v13, 0
	s_add_u32 m0, s12, 0x8c00
	v_mov_b32_e32 v14, 0
	global_load_lds_dwordx4 v251, s[10:11] sc1
	v_mov_b32_e32 v15, 0
	s_add_u32 s8, s8, 0x80
	s_addc_u32 s9, s9, 0
	s_add_u32 s10, s10, 0x80
	s_addc_u32 s11, s11, 0
	s_add_u32 m0, s12, 0x4000
	v_mov_b32_e32 v16, 0
	global_load_lds_dwordx4 v248, s[8:9]
	v_mov_b32_e32 v17, 0
	s_add_u32 m0, s12, 0x4400
	v_mov_b32_e32 v18, 0
	global_load_lds_dwordx4 v249, s[8:9]
	v_mov_b32_e32 v19, 0
	s_add_u32 m0, s12, 0x4800
	v_mov_b32_e32 v20, 0
	global_load_lds_dwordx4 v250, s[8:9]
	v_mov_b32_e32 v21, 0
	s_add_u32 m0, s12, 0x4c00
	v_mov_b32_e32 v22, 0
	global_load_lds_dwordx4 v251, s[8:9]
	v_mov_b32_e32 v23, 0
	s_add_u32 m0, s12, 0xc000
	v_mov_b32_e32 v24, 0
	global_load_lds_dwordx4 v248, s[10:11] sc1
	v_mov_b32_e32 v25, 0
	s_add_u32 m0, s12, 0xc400
	v_mov_b32_e32 v26, 0
	global_load_lds_dwordx4 v249, s[10:11] sc1
	v_mov_b32_e32 v27, 0
	s_add_u32 m0, s12, 0xc800
	v_mov_b32_e32 v28, 0
	global_load_lds_dwordx4 v250, s[10:11] sc1
	v_mov_b32_e32 v29, 0
	s_add_u32 m0, s12, 0xcc00
	v_mov_b32_e32 v30, 0
	global_load_lds_dwordx4 v251, s[10:11] sc1
	v_mov_b32_e32 v31, 0
	s_add_u32 s8, s8, 0x80
	s_addc_u32 s9, s9, 0
	s_add_u32 s10, s10, 0x80
	s_addc_u32 s11, s11, 0
	v_mov_b32_e32 v32, 0
	v_mov_b32_e32 v33, 0
	v_mov_b32_e32 v34, 0
	v_mov_b32_e32 v35, 0
	v_mov_b32_e32 v36, 0
	v_mov_b32_e32 v37, 0
	v_mov_b32_e32 v38, 0
	v_mov_b32_e32 v39, 0
	v_mov_b32_e32 v40, 0
	v_mov_b32_e32 v41, 0
	v_mov_b32_e32 v42, 0
	v_mov_b32_e32 v43, 0
	v_mov_b32_e32 v44, 0
	v_mov_b32_e32 v45, 0
	v_mov_b32_e32 v46, 0
	v_mov_b32_e32 v47, 0
	v_mov_b32_e32 v48, 0
	v_mov_b32_e32 v49, 0
	v_mov_b32_e32 v50, 0
	v_mov_b32_e32 v51, 0
	v_mov_b32_e32 v52, 0
	v_mov_b32_e32 v53, 0
	v_mov_b32_e32 v54, 0
	v_mov_b32_e32 v55, 0
	v_mov_b32_e32 v56, 0
	v_mov_b32_e32 v57, 0
	v_mov_b32_e32 v58, 0
	v_mov_b32_e32 v59, 0
	v_mov_b32_e32 v60, 0
	v_mov_b32_e32 v61, 0
	v_mov_b32_e32 v62, 0
	v_mov_b32_e32 v63, 0
	global_load_dword v201, v245, s[22:23] offset:0
	global_load_dword v202, v245, s[22:23] offset:64
	global_load_dword v203, v245, s[22:23] offset:128
	global_load_dword v204, v245, s[22:23] offset:192
	global_load_dword v205, v245, s[30:31] offset:0
	global_load_dword v206, v245, s[30:31] offset:64
	global_load_dword v207, v245, s[30:31] offset:128
	global_load_dword v208, v245, s[30:31] offset:192
	s_mov_b64 s[18:19], s[20:21]
	global_load_dword v129, v246, s[18:19] offset:0
	global_load_dword v130, v246, s[18:19] offset:64
	global_load_dword v131, v246, s[18:19] offset:128
	global_load_dword v132, v246, s[18:19] offset:192
	s_add_u32 s18, s18, 0x1000
	s_addc_u32 s19, s19, 0
	global_load_dword v133, v246, s[18:19] offset:0
	global_load_dword v134, v246, s[18:19] offset:64
	global_load_dword v135, v246, s[18:19] offset:128
	global_load_dword v136, v246, s[18:19] offset:192
	s_add_u32 s18, s18, 0x1000
	s_addc_u32 s19, s19, 0
	global_load_dword v137, v246, s[18:19] offset:0
	global_load_dword v138, v246, s[18:19] offset:64
	global_load_dword v139, v246, s[18:19] offset:128
	global_load_dword v140, v246, s[18:19] offset:192
	s_add_u32 s18, s18, 0x1000
	s_addc_u32 s19, s19, 0
	global_load_dword v141, v246, s[18:19] offset:0
	global_load_dword v142, v246, s[18:19] offset:64
	global_load_dword v143, v246, s[18:19] offset:128
	global_load_dword v144, v246, s[18:19] offset:192
	s_add_u32 s18, s18, 0xd000
	s_addc_u32 s19, s19, 0
	global_load_dword v145, v246, s[18:19] offset:0
	global_load_dword v146, v246, s[18:19] offset:64
	global_load_dword v147, v246, s[18:19] offset:128
	global_load_dword v148, v246, s[18:19] offset:192
	s_add_u32 s18, s18, 0x1000
	s_addc_u32 s19, s19, 0
	global_load_dword v149, v246, s[18:19] offset:0
	global_load_dword v150, v246, s[18:19] offset:64
	global_load_dword v151, v246, s[18:19] offset:128
	global_load_dword v152, v246, s[18:19] offset:192
	s_add_u32 s18, s18, 0x1000
	s_addc_u32 s19, s19, 0
	global_load_dword v153, v246, s[18:19] offset:0
	global_load_dword v154, v246, s[18:19] offset:64
	global_load_dword v155, v246, s[18:19] offset:128
	global_load_dword v156, v246, s[18:19] offset:192
	s_add_u32 s18, s18, 0x1000
	s_addc_u32 s19, s19, 0
	global_load_dword v157, v246, s[18:19] offset:0
	global_load_dword v158, v246, s[18:19] offset:64
	global_load_dword v159, v246, s[18:19] offset:128
	global_load_dword v160, v246, s[18:19] offset:192
	s_add_u32 s18, s18, 0xd000
	s_addc_u32 s19, s19, 0
	global_load_dword v161, v246, s[18:19] offset:0
	global_load_dword v170, v246, s[18:19] offset:64
	global_load_dword v171, v246, s[18:19] offset:128
	global_load_dword v172, v246, s[18:19] offset:192
	s_add_u32 s18, s18, 0x1000
	s_addc_u32 s19, s19, 0
	global_load_dword v173, v246, s[18:19] offset:0
	global_load_dword v174, v246, s[18:19] offset:64
	global_load_dword v175, v246, s[18:19] offset:128
	global_load_dword v176, v246, s[18:19] offset:192
	s_add_u32 s18, s18, 0x1000
	s_addc_u32 s19, s19, 0
	global_load_dword v177, v246, s[18:19] offset:0
	global_load_dword v178, v246, s[18:19] offset:64
	global_load_dword v179, v246, s[18:19] offset:128
	global_load_dword v180, v246, s[18:19] offset:192
	s_add_u32 s18, s18, 0x1000
	s_addc_u32 s19, s19, 0
	global_load_dword v181, v246, s[18:19] offset:0
	global_load_dword v182, v246, s[18:19] offset:64
	global_load_dword v183, v246, s[18:19] offset:128
	global_load_dword v184, v246, s[18:19] offset:192
	s_add_u32 s18, s18, 0xd000
	s_addc_u32 s19, s19, 0
	global_load_dword v185, v246, s[18:19] offset:0
	global_load_dword v186, v246, s[18:19] offset:64
	global_load_dword v187, v246, s[18:19] offset:128
	global_load_dword v188, v246, s[18:19] offset:192
	s_add_u32 s18, s18, 0x1000
	s_addc_u32 s19, s19, 0
	global_load_dword v189, v246, s[18:19] offset:0
	global_load_dword v190, v246, s[18:19] offset:64
	global_load_dword v191, v246, s[18:19] offset:128
	global_load_dword v192, v246, s[18:19] offset:192
	s_add_u32 s18, s18, 0x1000
	s_addc_u32 s19, s19, 0
	global_load_dword v193, v246, s[18:19] offset:0
	global_load_dword v194, v246, s[18:19] offset:64
	global_load_dword v195, v246, s[18:19] offset:128
	global_load_dword v196, v246, s[18:19] offset:192
	s_add_u32 s18, s18, 0x1000
	s_addc_u32 s19, s19, 0
	global_load_dword v197, v246, s[18:19] offset:0
	global_load_dword v198, v246, s[18:19] offset:64
	global_load_dword v199, v246, s[18:19] offset:128
	global_load_dword v200, v246, s[18:19] offset:192
	s_waitcnt vmcnt(63)
	s_barrier
	ds_read_b128 v[64:67], v252 offset:0
	ds_read_b128 v[96:99], v254 offset:32768
	ds_read_b128 v[100:103], v254 offset:34816
	ds_read_b128 v[104:107], v254 offset:36864
	ds_read_b128 v[108:111], v254 offset:38912
	ds_read_b128 v[68:71], v252 offset:2048
	ds_read_b128 v[72:75], v252 offset:4096
	ds_read_b128 v[76:79], v252 offset:6144
	ds_read_b128 v[80:83], v253 offset:0
	ds_read_b128 v[112:115], v255 offset:32768
	ds_read_b128 v[116:119], v255 offset:34816
	ds_read_b128 v[120:123], v255 offset:36864
	ds_read_b128 v[124:127], v255 offset:38912
	s_waitcnt lgkmcnt(11)
	v_mfma_f32_16x16x32_bf16 v[0:3], v[64:67], v[96:99], v[0:3]
	s_waitcnt lgkmcnt(10)
	v_mfma_f32_16x16x32_bf16 v[4:7], v[64:67], v[100:103], v[4:7]
	s_waitcnt lgkmcnt(9)
	v_mfma_f32_16x16x32_bf16 v[8:11], v[64:67], v[104:107], v[8:11]
	s_waitcnt lgkmcnt(8)
	v_mfma_f32_16x16x32_bf16 v[12:15], v[64:67], v[108:111], v[12:15]
	ds_read_b128 v[84:87], v253 offset:2048
	ds_read_b128 v[88:91], v253 offset:4096
	ds_read_b128 v[92:95], v253 offset:6144
	s_waitcnt lgkmcnt(10)
	v_mfma_f32_16x16x32_bf16 v[16:19], v[68:71], v[96:99], v[16:19]
	v_mfma_f32_16x16x32_bf16 v[20:23], v[68:71], v[100:103], v[20:23]
	v_mfma_f32_16x16x32_bf16 v[24:27], v[68:71], v[104:107], v[24:27]
	v_mfma_f32_16x16x32_bf16 v[28:31], v[68:71], v[108:111], v[28:31]
	s_waitcnt lgkmcnt(0)
	s_barrier
	s_add_u32 m0, s12, 0x0
	v_mfma_f32_16x16x32_bf16 v[32:35], v[72:75], v[96:99], v[32:35]
	global_load_lds_dwordx4 v248, s[8:9]
	s_add_u32 m0, s12, 0x400
	v_mfma_f32_16x16x32_bf16 v[36:39], v[72:75], v[100:103], v[36:39]
	global_load_lds_dwordx4 v249, s[8:9]
	s_add_u32 m0, s12, 0x800
	v_mfma_f32_16x16x32_bf16 v[40:43], v[72:75], v[104:107], v[40:43]
	global_load_lds_dwordx4 v250, s[8:9]
	s_add_u32 m0, s12, 0xc00
	v_mfma_f32_16x16x32_bf16 v[44:47], v[72:75], v[108:111], v[44:47]
	global_load_lds_dwordx4 v251, s[8:9]
	s_add_u32 m0, s12, 0x8000
	v_mfma_f32_16x16x32_bf16 v[48:51], v[76:79], v[96:99], v[48:51]
	global_load_lds_dwordx4 v248, s[10:11] sc1
	s_add_u32 m0, s12, 0x8400
	v_mfma_f32_16x16x32_bf16 v[52:55], v[76:79], v[100:103], v[52:55]
	global_load_lds_dwordx4 v249, s[10:11] sc1
	s_add_u32 m0, s12, 0x8800
	v_mfma_f32_16x16x32_bf16 v[56:59], v[76:79], v[104:107], v[56:59]
	global_load_lds_dwordx4 v250, s[10:11] sc1
	s_add_u32 m0, s12, 0x8c00
	v_mfma_f32_16x16x32_bf16 v[60:63], v[76:79], v[108:111], v[60:63]
	global_load_lds_dwordx4 v251, s[10:11] sc1
	s_add_u32 s8, s8, 0x80
	s_addc_u32 s9, s9, 0
	s_add_u32 s10, s10, 0x80
	s_addc_u32 s11, s11, 0
	s_waitcnt vmcnt(63)
	s_barrier
	ds_read_b128 v[64:67], v252 offset:16384
	ds_read_b128 v[96:99], v254 offset:49152
	ds_read_b128 v[100:103], v254 offset:51200
	ds_read_b128 v[104:107], v254 offset:53248
	ds_read_b128 v[108:111], v254 offset:55296
	ds_read_b128 v[68:71], v252 offset:18432
	ds_read_b128 v[72:75], v252 offset:20480
	ds_read_b128 v[76:79], v252 offset:22528
	v_mfma_f32_16x16x32_bf16 v[0:3], v[80:83], v[112:115], v[0:3]
	v_mfma_f32_16x16x32_bf16 v[4:7], v[80:83], v[116:119], v[4:7]
	v_mfma_f32_16x16x32_bf16 v[8:11], v[80:83], v[120:123], v[8:11]
	v_mfma_f32_16x16x32_bf16 v[12:15], v[80:83], v[124:127], v[12:15]
	v_mfma_f32_16x16x32_bf16 v[16:19], v[84:87], v[112:115], v[16:19]
	v_mfma_f32_16x16x32_bf16 v[20:23], v[84:87], v[116:119], v[20:23]
	v_mfma_f32_16x16x32_bf16 v[24:27], v[84:87], v[120:123], v[24:27]
	v_mfma_f32_16x16x32_bf16 v[28:31], v[84:87], v[124:127], v[28:31]
	v_mfma_f32_16x16x32_bf16 v[32:35], v[88:91], v[112:115], v[32:35]
	v_mfma_f32_16x16x32_bf16 v[36:39], v[88:91], v[116:119], v[36:39]
	v_mfma_f32_16x16x32_bf16 v[40:43], v[88:91], v[120:123], v[40:43]
	v_mfma_f32_16x16x32_bf16 v[44:47], v[88:91], v[124:127], v[44:47]
	v_mfma_f32_16x16x32_bf16 v[48:51], v[92:95], v[112:115], v[48:51]
	v_mfma_f32_16x16x32_bf16 v[52:55], v[92:95], v[116:119], v[52:55]
	v_mfma_f32_16x16x32_bf16 v[56:59], v[92:95], v[120:123], v[56:59]
	v_mfma_f32_16x16x32_bf16 v[60:63], v[92:95], v[124:127], v[60:63]
	ds_read_b128 v[80:83], v253 offset:16384
	ds_read_b128 v[112:115], v255 offset:49152
	ds_read_b128 v[116:119], v255 offset:51200
	ds_read_b128 v[120:123], v255 offset:53248
	ds_read_b128 v[124:127], v255 offset:55296
	ds_read_b128 v[84:87], v253 offset:18432
	ds_read_b128 v[88:91], v253 offset:20480
	ds_read_b128 v[92:95], v253 offset:22528
	s_waitcnt lgkmcnt(14)
	v_mfma_f32_16x16x32_bf16 v[0:3], v[64:67], v[96:99], v[0:3]
	s_waitcnt lgkmcnt(13)
	v_mfma_f32_16x16x32_bf16 v[4:7], v[64:67], v[100:103], v[4:7]
	s_waitcnt lgkmcnt(12)
	v_mfma_f32_16x16x32_bf16 v[8:11], v[64:67], v[104:107], v[8:11]
	s_waitcnt lgkmcnt(11)
	v_mfma_f32_16x16x32_bf16 v[12:15], v[64:67], v[108:111], v[12:15]
	s_waitcnt lgkmcnt(10)
	v_mfma_f32_16x16x32_bf16 v[16:19], v[68:71], v[96:99], v[16:19]
	v_mfma_f32_16x16x32_bf16 v[20:23], v[68:71], v[100:103], v[20:23]
	v_mfma_f32_16x16x32_bf16 v[24:27], v[68:71], v[104:107], v[24:27]
	v_mfma_f32_16x16x32_bf16 v[28:31], v[68:71], v[108:111], v[28:31]
	s_waitcnt lgkmcnt(0)
	s_barrier
	s_add_u32 m0, s12, 0x4000
	v_mfma_f32_16x16x32_bf16 v[32:35], v[72:75], v[96:99], v[32:35]
	global_load_lds_dwordx4 v248, s[8:9]
	s_add_u32 m0, s12, 0x4400
	v_mfma_f32_16x16x32_bf16 v[36:39], v[72:75], v[100:103], v[36:39]
	global_load_lds_dwordx4 v249, s[8:9]
	s_add_u32 m0, s12, 0x4800
	v_mfma_f32_16x16x32_bf16 v[40:43], v[72:75], v[104:107], v[40:43]
	global_load_lds_dwordx4 v250, s[8:9]
	s_add_u32 m0, s12, 0x4c00
	v_mfma_f32_16x16x32_bf16 v[44:47], v[72:75], v[108:111], v[44:47]
	global_load_lds_dwordx4 v251, s[8:9]
	s_add_u32 m0, s12, 0xc000
	v_mfma_f32_16x16x32_bf16 v[48:51], v[76:79], v[96:99], v[48:51]
	global_load_lds_dwordx4 v248, s[10:11] sc1
	s_add_u32 m0, s12, 0xc400
	v_mfma_f32_16x16x32_bf16 v[52:55], v[76:79], v[100:103], v[52:55]
	global_load_lds_dwordx4 v249, s[10:11] sc1
	s_add_u32 m0, s12, 0xc800
	v_mfma_f32_16x16x32_bf16 v[56:59], v[76:79], v[104:107], v[56:59]
	global_load_lds_dwordx4 v250, s[10:11] sc1
	s_add_u32 m0, s12, 0xcc00
	v_mfma_f32_16x16x32_bf16 v[60:63], v[76:79], v[108:111], v[60:63]
	global_load_lds_dwordx4 v251, s[10:11] sc1
	s_add_u32 s8, s8, 0x80
	s_addc_u32 s9, s9, 0
	s_add_u32 s10, s10, 0x80
	s_addc_u32 s11, s11, 0
	s_mov_b32 s13, 6
.Lr13_loop:
	s_waitcnt vmcnt(8)
	s_barrier
	ds_read_b128 v[64:67], v252 offset:0
	ds_read_b128 v[96:99], v254 offset:32768
	ds_read_b128 v[100:103], v254 offset:34816
	ds_read_b128 v[104:107], v254 offset:36864
	ds_read_b128 v[108:111], v254 offset:38912
	ds_read_b128 v[68:71], v252 offset:2048
	ds_read_b128 v[72:75], v252 offset:4096
	ds_read_b128 v[76:79], v252 offset:6144
	v_mfma_f32_16x16x32_bf16 v[0:3], v[80:83], v[112:115], v[0:3]
	v_mfma_f32_16x16x32_bf16 v[4:7], v[80:83], v[116:119], v[4:7]
	v_mfma_f32_16x16x32_bf16 v[8:11], v[80:83], v[120:123], v[8:11]
	v_mfma_f32_16x16x32_bf16 v[12:15], v[80:83], v[124:127], v[12:15]
	v_mfma_f32_16x16x32_bf16 v[16:19], v[84:87], v[112:115], v[16:19]
	v_mfma_f32_16x16x32_bf16 v[20:23], v[84:87], v[116:119], v[20:23]
	v_mfma_f32_16x16x32_bf16 v[24:27], v[84:87], v[120:123], v[24:27]
	v_mfma_f32_16x16x32_bf16 v[28:31], v[84:87], v[124:127], v[28:31]
	v_mfma_f32_16x16x32_bf16 v[32:35], v[88:91], v[112:115], v[32:35]
	v_mfma_f32_16x16x32_bf16 v[36:39], v[88:91], v[116:119], v[36:39]
	v_mfma_f32_16x16x32_bf16 v[40:43], v[88:91], v[120:123], v[40:43]
	v_mfma_f32_16x16x32_bf16 v[44:47], v[88:91], v[124:127], v[44:47]
	v_mfma_f32_16x16x32_bf16 v[48:51], v[92:95], v[112:115], v[48:51]
	v_mfma_f32_16x16x32_bf16 v[52:55], v[92:95], v[116:119], v[52:55]
	v_mfma_f32_16x16x32_bf16 v[56:59], v[92:95], v[120:123], v[56:59]
	v_mfma_f32_16x16x32_bf16 v[60:63], v[92:95], v[124:127], v[60:63]
	ds_read_b128 v[80:83], v253 offset:0
	ds_read_b128 v[112:115], v255 offset:32768
	ds_read_b128 v[116:119], v255 offset:34816
	ds_read_b128 v[120:123], v255 offset:36864
	ds_read_b128 v[124:127], v255 offset:38912
	ds_read_b128 v[84:87], v253 offset:2048
	ds_read_b128 v[88:91], v253 offset:4096
	ds_read_b128 v[92:95], v253 offset:6144
	s_waitcnt lgkmcnt(14)
	v_mfma_f32_16x16x32_bf16 v[0:3], v[64:67], v[96:99], v[0:3]
	s_waitcnt lgkmcnt(13)
	v_mfma_f32_16x16x32_bf16 v[4:7], v[64:67], v[100:103], v[4:7]
	s_waitcnt lgkmcnt(12)
	v_mfma_f32_16x16x32_bf16 v[8:11], v[64:67], v[104:107], v[8:11]
	s_waitcnt lgkmcnt(11)
	v_mfma_f32_16x16x32_bf16 v[12:15], v[64:67], v[108:111], v[12:15]
	s_waitcnt lgkmcnt(10)
	v_mfma_f32_16x16x32_bf16 v[16:19], v[68:71], v[96:99], v[16:19]
	v_mfma_f32_16x16x32_bf16 v[20:23], v[68:71], v[100:103], v[20:23]
	v_mfma_f32_16x16x32_bf16 v[24:27], v[68:71], v[104:107], v[24:27]
	v_mfma_f32_16x16x32_bf16 v[28:31], v[68:71], v[108:111], v[28:31]
	s_waitcnt lgkmcnt(0)
	s_barrier
	s_add_u32 m0, s12, 0x0
	v_mfma_f32_16x16x32_bf16 v[32:35], v[72:75], v[96:99], v[32:35]
	global_load_lds_dwordx4 v248, s[8:9]
	s_add_u32 m0, s12, 0x400
	v_mfma_f32_16x16x32_bf16 v[36:39], v[72:75], v[100:103], v[36:39]
	global_load_lds_dwordx4 v249, s[8:9]
	s_add_u32 m0, s12, 0x800
	v_mfma_f32_16x16x32_bf16 v[40:43], v[72:75], v[104:107], v[40:43]
	global_load_lds_dwordx4 v250, s[8:9]
	s_add_u32 m0, s12, 0xc00
	v_mfma_f32_16x16x32_bf16 v[44:47], v[72:75], v[108:111], v[44:47]
	global_load_lds_dwordx4 v251, s[8:9]
	s_add_u32 m0, s12, 0x8000
	v_mfma_f32_16x16x32_bf16 v[48:51], v[76:79], v[96:99], v[48:51]
	global_load_lds_dwordx4 v248, s[10:11] sc1
	s_add_u32 m0, s12, 0x8400
	v_mfma_f32_16x16x32_bf16 v[52:55], v[76:79], v[100:103], v[52:55]
	global_load_lds_dwordx4 v249, s[10:11] sc1
	s_add_u32 m0, s12, 0x8800
	v_mfma_f32_16x16x32_bf16 v[56:59], v[76:79], v[104:107], v[56:59]
	global_load_lds_dwordx4 v250, s[10:11] sc1
	s_add_u32 m0, s12, 0x8c00
	v_mfma_f32_16x16x32_bf16 v[60:63], v[76:79], v[108:111], v[60:63]
	global_load_lds_dwordx4 v251, s[10:11] sc1
	s_add_u32 s8, s8, 0x80
	s_addc_u32 s9, s9, 0
	s_add_u32 s10, s10, 0x80
	s_addc_u32 s11, s11, 0
	s_waitcnt vmcnt(8)
	s_barrier
	ds_read_b128 v[64:67], v252 offset:16384
	ds_read_b128 v[96:99], v254 offset:49152
	ds_read_b128 v[100:103], v254 offset:51200
	ds_read_b128 v[104:107], v254 offset:53248
	ds_read_b128 v[108:111], v254 offset:55296
	ds_read_b128 v[68:71], v252 offset:18432
	ds_read_b128 v[72:75], v252 offset:20480
	ds_read_b128 v[76:79], v252 offset:22528
	v_mfma_f32_16x16x32_bf16 v[0:3], v[80:83], v[112:115], v[0:3]
	v_mfma_f32_16x16x32_bf16 v[4:7], v[80:83], v[116:119], v[4:7]
	v_mfma_f32_16x16x32_bf16 v[8:11], v[80:83], v[120:123], v[8:11]
	v_mfma_f32_16x16x32_bf16 v[12:15], v[80:83], v[124:127], v[12:15]
	v_mfma_f32_16x16x32_bf16 v[16:19], v[84:87], v[112:115], v[16:19]
	v_mfma_f32_16x16x32_bf16 v[20:23], v[84:87], v[116:119], v[20:23]
	v_mfma_f32_16x16x32_bf16 v[24:27], v[84:87], v[120:123], v[24:27]
	v_mfma_f32_16x16x32_bf16 v[28:31], v[84:87], v[124:127], v[28:31]
	v_mfma_f32_16x16x32_bf16 v[32:35], v[88:91], v[112:115], v[32:35]
	v_mfma_f32_16x16x32_bf16 v[36:39], v[88:91], v[116:119], v[36:39]
	v_mfma_f32_16x16x32_bf16 v[40:43], v[88:91], v[120:123], v[40:43]
	v_mfma_f32_16x16x32_bf16 v[44:47], v[88:91], v[124:127], v[44:47]
	v_mfma_f32_16x16x32_bf16 v[48:51], v[92:95], v[112:115], v[48:51]
	v_mfma_f32_16x16x32_bf16 v[52:55], v[92:95], v[116:119], v[52:55]
	v_mfma_f32_16x16x32_bf16 v[56:59], v[92:95], v[120:123], v[56:59]
	v_mfma_f32_16x16x32_bf16 v[60:63], v[92:95], v[124:127], v[60:63]
	ds_read_b128 v[80:83], v253 offset:16384
	ds_read_b128 v[112:115], v255 offset:49152
	ds_read_b128 v[116:119], v255 offset:51200
	ds_read_b128 v[120:123], v255 offset:53248
	ds_read_b128 v[124:127], v255 offset:55296
	ds_read_b128 v[84:87], v253 offset:18432
	ds_read_b128 v[88:91], v253 offset:20480
	ds_read_b128 v[92:95], v253 offset:22528
	s_waitcnt lgkmcnt(14)
	v_mfma_f32_16x16x32_bf16 v[0:3], v[64:67], v[96:99], v[0:3]
	s_waitcnt lgkmcnt(13)
	v_mfma_f32_16x16x32_bf16 v[4:7], v[64:67], v[100:103], v[4:7]
	s_waitcnt lgkmcnt(12)
	v_mfma_f32_16x16x32_bf16 v[8:11], v[64:67], v[104:107], v[8:11]
	s_waitcnt lgkmcnt(11)
	v_mfma_f32_16x16x32_bf16 v[12:15], v[64:67], v[108:111], v[12:15]
	s_waitcnt lgkmcnt(10)
	v_mfma_f32_16x16x32_bf16 v[16:19], v[68:71], v[96:99], v[16:19]
	v_mfma_f32_16x16x32_bf16 v[20:23], v[68:71], v[100:103], v[20:23]
	v_mfma_f32_16x16x32_bf16 v[24:27], v[68:71], v[104:107], v[24:27]
	v_mfma_f32_16x16x32_bf16 v[28:31], v[68:71], v[108:111], v[28:31]
	s_waitcnt lgkmcnt(0)
	s_barrier
	s_add_u32 m0, s12, 0x4000
	v_mfma_f32_16x16x32_bf16 v[32:35], v[72:75], v[96:99], v[32:35]
	global_load_lds_dwordx4 v248, s[8:9]
	s_add_u32 m0, s12, 0x4400
	v_mfma_f32_16x16x32_bf16 v[36:39], v[72:75], v[100:103], v[36:39]
	global_load_lds_dwordx4 v249, s[8:9]
	s_add_u32 m0, s12, 0x4800
	v_mfma_f32_16x16x32_bf16 v[40:43], v[72:75], v[104:107], v[40:43]
	global_load_lds_dwordx4 v250, s[8:9]
	s_add_u32 m0, s12, 0x4c00
	v_mfma_f32_16x16x32_bf16 v[44:47], v[72:75], v[108:111], v[44:47]
	global_load_lds_dwordx4 v251, s[8:9]
	s_add_u32 m0, s12, 0xc000
	v_mfma_f32_16x16x32_bf16 v[48:51], v[76:79], v[96:99], v[48:51]
	global_load_lds_dwordx4 v248, s[10:11] sc1
	s_add_u32 m0, s12, 0xc400
	v_mfma_f32_16x16x32_bf16 v[52:55], v[76:79], v[100:103], v[52:55]
	global_load_lds_dwordx4 v249, s[10:11] sc1
	s_add_u32 m0, s12, 0xc800
	v_mfma_f32_16x16x32_bf16 v[56:59], v[76:79], v[104:107], v[56:59]
	global_load_lds_dwordx4 v250, s[10:11] sc1
	s_add_u32 m0, s12, 0xcc00
	v_mfma_f32_16x16x32_bf16 v[60:63], v[76:79], v[108:111], v[60:63]
	global_load_lds_dwordx4 v251, s[10:11] sc1
	s_add_u32 s8, s8, 0x80
	s_addc_u32 s9, s9, 0
	s_add_u32 s10, s10, 0x80
	s_addc_u32 s11, s11, 0
	s_sub_u32 s13, s13, 1
	s_cmp_lg_u32 s13, 0
	s_cbranch_scc1 .Lr13_loop
	s_waitcnt vmcnt(8)
	s_barrier
	ds_read_b128 v[64:67], v252 offset:0
	ds_read_b128 v[96:99], v254 offset:32768
	ds_read_b128 v[100:103], v254 offset:34816
	ds_read_b128 v[104:107], v254 offset:36864
	ds_read_b128 v[108:111], v254 offset:38912
	ds_read_b128 v[68:71], v252 offset:2048
	ds_read_b128 v[72:75], v252 offset:4096
	ds_read_b128 v[76:79], v252 offset:6144
	v_mfma_f32_16x16x32_bf16 v[0:3], v[80:83], v[112:115], v[0:3]
	v_mfma_f32_16x16x32_bf16 v[4:7], v[80:83], v[116:119], v[4:7]
	v_mfma_f32_16x16x32_bf16 v[8:11], v[80:83], v[120:123], v[8:11]
	v_mfma_f32_16x16x32_bf16 v[12:15], v[80:83], v[124:127], v[12:15]
	v_mfma_f32_16x16x32_bf16 v[16:19], v[84:87], v[112:115], v[16:19]
	v_mfma_f32_16x16x32_bf16 v[20:23], v[84:87], v[116:119], v[20:23]
	v_mfma_f32_16x16x32_bf16 v[24:27], v[84:87], v[120:123], v[24:27]
	v_mfma_f32_16x16x32_bf16 v[28:31], v[84:87], v[124:127], v[28:31]
	v_mfma_f32_16x16x32_bf16 v[32:35], v[88:91], v[112:115], v[32:35]
	v_mfma_f32_16x16x32_bf16 v[36:39], v[88:91], v[116:119], v[36:39]
	v_mfma_f32_16x16x32_bf16 v[40:43], v[88:91], v[120:123], v[40:43]
	v_mfma_f32_16x16x32_bf16 v[44:47], v[88:91], v[124:127], v[44:47]
	v_mfma_f32_16x16x32_bf16 v[48:51], v[92:95], v[112:115], v[48:51]
	v_mfma_f32_16x16x32_bf16 v[52:55], v[92:95], v[116:119], v[52:55]
	v_mfma_f32_16x16x32_bf16 v[56:59], v[92:95], v[120:123], v[56:59]
	v_mfma_f32_16x16x32_bf16 v[60:63], v[92:95], v[124:127], v[60:63]
	ds_read_b128 v[80:83], v253 offset:0
	ds_read_b128 v[112:115], v255 offset:32768
	ds_read_b128 v[116:119], v255 offset:34816
	ds_read_b128 v[120:123], v255 offset:36864
	ds_read_b128 v[124:127], v255 offset:38912
	ds_read_b128 v[84:87], v253 offset:2048
	ds_read_b128 v[88:91], v253 offset:4096
	ds_read_b128 v[92:95], v253 offset:6144
	s_waitcnt lgkmcnt(14)
	v_mfma_f32_16x16x32_bf16 v[0:3], v[64:67], v[96:99], v[0:3]
	s_waitcnt lgkmcnt(13)
	v_mfma_f32_16x16x32_bf16 v[4:7], v[64:67], v[100:103], v[4:7]
	s_waitcnt lgkmcnt(12)
	v_mfma_f32_16x16x32_bf16 v[8:11], v[64:67], v[104:107], v[8:11]
	s_waitcnt lgkmcnt(11)
	v_mfma_f32_16x16x32_bf16 v[12:15], v[64:67], v[108:111], v[12:15]
	s_waitcnt lgkmcnt(10)
	v_mfma_f32_16x16x32_bf16 v[16:19], v[68:71], v[96:99], v[16:19]
	v_mfma_f32_16x16x32_bf16 v[20:23], v[68:71], v[100:103], v[20:23]
	v_mfma_f32_16x16x32_bf16 v[24:27], v[68:71], v[104:107], v[24:27]
	v_mfma_f32_16x16x32_bf16 v[28:31], v[68:71], v[108:111], v[28:31]
	s_waitcnt lgkmcnt(0)
	s_barrier
	v_mfma_f32_16x16x32_bf16 v[32:35], v[72:75], v[96:99], v[32:35]
	v_mfma_f32_16x16x32_bf16 v[36:39], v[72:75], v[100:103], v[36:39]
	v_mfma_f32_16x16x32_bf16 v[40:43], v[72:75], v[104:107], v[40:43]
	v_mfma_f32_16x16x32_bf16 v[44:47], v[72:75], v[108:111], v[44:47]
	v_mfma_f32_16x16x32_bf16 v[48:51], v[76:79], v[96:99], v[48:51]
	v_mfma_f32_16x16x32_bf16 v[52:55], v[76:79], v[100:103], v[52:55]
	v_mfma_f32_16x16x32_bf16 v[56:59], v[76:79], v[104:107], v[56:59]
	v_mfma_f32_16x16x32_bf16 v[60:63], v[76:79], v[108:111], v[60:63]
	s_waitcnt vmcnt(0)
	s_barrier
	ds_read_b128 v[64:67], v252 offset:16384
	ds_read_b128 v[96:99], v254 offset:49152
	ds_read_b128 v[100:103], v254 offset:51200
	ds_read_b128 v[104:107], v254 offset:53248
	ds_read_b128 v[108:111], v254 offset:55296
	ds_read_b128 v[68:71], v252 offset:18432
	ds_read_b128 v[72:75], v252 offset:20480
	ds_read_b128 v[76:79], v252 offset:22528
	v_mfma_f32_16x16x32_bf16 v[0:3], v[80:83], v[112:115], v[0:3]
	v_mfma_f32_16x16x32_bf16 v[4:7], v[80:83], v[116:119], v[4:7]
	v_mfma_f32_16x16x32_bf16 v[8:11], v[80:83], v[120:123], v[8:11]
	v_mfma_f32_16x16x32_bf16 v[12:15], v[80:83], v[124:127], v[12:15]
	v_mfma_f32_16x16x32_bf16 v[16:19], v[84:87], v[112:115], v[16:19]
	v_mfma_f32_16x16x32_bf16 v[20:23], v[84:87], v[116:119], v[20:23]
	v_mfma_f32_16x16x32_bf16 v[24:27], v[84:87], v[120:123], v[24:27]
	v_mfma_f32_16x16x32_bf16 v[28:31], v[84:87], v[124:127], v[28:31]
	v_mfma_f32_16x16x32_bf16 v[32:35], v[88:91], v[112:115], v[32:35]
	v_mfma_f32_16x16x32_bf16 v[36:39], v[88:91], v[116:119], v[36:39]
	v_mfma_f32_16x16x32_bf16 v[40:43], v[88:91], v[120:123], v[40:43]
	v_mfma_f32_16x16x32_bf16 v[44:47], v[88:91], v[124:127], v[44:47]
	v_mfma_f32_16x16x32_bf16 v[48:51], v[92:95], v[112:115], v[48:51]
	v_mfma_f32_16x16x32_bf16 v[52:55], v[92:95], v[116:119], v[52:55]
	v_mfma_f32_16x16x32_bf16 v[56:59], v[92:95], v[120:123], v[56:59]
	v_mfma_f32_16x16x32_bf16 v[60:63], v[92:95], v[124:127], v[60:63]
	ds_read_b128 v[80:83], v253 offset:16384
	ds_read_b128 v[112:115], v255 offset:49152
	ds_read_b128 v[116:119], v255 offset:51200
	ds_read_b128 v[120:123], v255 offset:53248
	ds_read_b128 v[124:127], v255 offset:55296
	ds_read_b128 v[84:87], v253 offset:18432
	ds_read_b128 v[88:91], v253 offset:20480
	ds_read_b128 v[92:95], v253 offset:22528
	s_waitcnt lgkmcnt(14)
	v_mfma_f32_16x16x32_bf16 v[0:3], v[64:67], v[96:99], v[0:3]
	s_waitcnt lgkmcnt(13)
	v_mfma_f32_16x16x32_bf16 v[4:7], v[64:67], v[100:103], v[4:7]
	s_waitcnt lgkmcnt(12)
	v_mfma_f32_16x16x32_bf16 v[8:11], v[64:67], v[104:107], v[8:11]
	s_waitcnt lgkmcnt(11)
	v_mfma_f32_16x16x32_bf16 v[12:15], v[64:67], v[108:111], v[12:15]
	s_waitcnt lgkmcnt(10)
	v_mfma_f32_16x16x32_bf16 v[16:19], v[68:71], v[96:99], v[16:19]
	v_mfma_f32_16x16x32_bf16 v[20:23], v[68:71], v[100:103], v[20:23]
	v_mfma_f32_16x16x32_bf16 v[24:27], v[68:71], v[104:107], v[24:27]
	v_mfma_f32_16x16x32_bf16 v[28:31], v[68:71], v[108:111], v[28:31]
	s_waitcnt lgkmcnt(0)
	s_barrier
	v_mfma_f32_16x16x32_bf16 v[32:35], v[72:75], v[96:99], v[32:35]
	v_mfma_f32_16x16x32_bf16 v[36:39], v[72:75], v[100:103], v[36:39]
	v_mfma_f32_16x16x32_bf16 v[40:43], v[72:75], v[104:107], v[40:43]
	v_mfma_f32_16x16x32_bf16 v[44:47], v[72:75], v[108:111], v[44:47]
	v_mfma_f32_16x16x32_bf16 v[48:51], v[76:79], v[96:99], v[48:51]
	v_mfma_f32_16x16x32_bf16 v[52:55], v[76:79], v[100:103], v[52:55]
	v_mfma_f32_16x16x32_bf16 v[56:59], v[76:79], v[104:107], v[56:59]
	v_mfma_f32_16x16x32_bf16 v[60:63], v[76:79], v[108:111], v[60:63]
	v_mfma_f32_16x16x32_bf16 v[0:3], v[80:83], v[112:115], v[0:3]
	v_mfma_f32_16x16x32_bf16 v[4:7], v[80:83], v[116:119], v[4:7]
	v_mfma_f32_16x16x32_bf16 v[8:11], v[80:83], v[120:123], v[8:11]
	v_mfma_f32_16x16x32_bf16 v[12:15], v[80:83], v[124:127], v[12:15]
	v_mfma_f32_16x16x32_bf16 v[16:19], v[84:87], v[112:115], v[16:19]
	v_mfma_f32_16x16x32_bf16 v[20:23], v[84:87], v[116:119], v[20:23]
	v_mfma_f32_16x16x32_bf16 v[24:27], v[84:87], v[120:123], v[24:27]
	v_mfma_f32_16x16x32_bf16 v[28:31], v[84:87], v[124:127], v[28:31]
	v_mfma_f32_16x16x32_bf16 v[32:35], v[88:91], v[112:115], v[32:35]
	v_mfma_f32_16x16x32_bf16 v[36:39], v[88:91], v[116:119], v[36:39]
	v_mfma_f32_16x16x32_bf16 v[40:43], v[88:91], v[120:123], v[40:43]
	v_mfma_f32_16x16x32_bf16 v[44:47], v[88:91], v[124:127], v[44:47]
	v_mfma_f32_16x16x32_bf16 v[48:51], v[92:95], v[112:115], v[48:51]
	v_mfma_f32_16x16x32_bf16 v[52:55], v[92:95], v[116:119], v[52:55]
	v_mfma_f32_16x16x32_bf16 v[56:59], v[92:95], v[120:123], v[56:59]
	v_mfma_f32_16x16x32_bf16 v[60:63], v[92:95], v[124:127], v[60:63]
	s_nop 7
	s_nop 1
	s_mov_b64 s[18:19], s[20:21]
	v_add_f32_e32 v0, v0, v205
	v_add_f32_e32 v4, v4, v206
	v_add_f32_e32 v8, v8, v207
	v_add_f32_e32 v12, v12, v208
	v_fma_f32 v129, v201, v0, v129
	v_fma_f32 v130, v202, v4, v130
	v_fma_f32 v131, v203, v8, v131
	v_fma_f32 v132, v204, v12, v132
	global_store_dword v246, v129, s[18:19] offset:0
	global_store_dword v246, v130, s[18:19] offset:64
	global_store_dword v246, v131, s[18:19] offset:128
	global_store_dword v246, v132, s[18:19] offset:192
	s_add_u32 s18, s18, 0x1000
	s_addc_u32 s19, s19, 0
	v_add_f32_e32 v1, v1, v205
	v_add_f32_e32 v5, v5, v206
	v_add_f32_e32 v9, v9, v207
	v_add_f32_e32 v13, v13, v208
	v_fma_f32 v133, v201, v1, v133
	v_fma_f32 v134, v202, v5, v134
	v_fma_f32 v135, v203, v9, v135
	v_fma_f32 v136, v204, v13, v136
	global_store_dword v246, v133, s[18:19] offset:0
	global_store_dword v246, v134, s[18:19] offset:64
	global_store_dword v246, v135, s[18:19] offset:128
	global_store_dword v246, v136, s[18:19] offset:192
	s_add_u32 s18, s18, 0x1000
	s_addc_u32 s19, s19, 0
	v_add_f32_e32 v2, v2, v205
	v_add_f32_e32 v6, v6, v206
	v_add_f32_e32 v10, v10, v207
	v_add_f32_e32 v14, v14, v208
	v_fma_f32 v137, v201, v2, v137
	v_fma_f32 v138, v202, v6, v138
	v_fma_f32 v139, v203, v10, v139
	v_fma_f32 v140, v204, v14, v140
	global_store_dword v246, v137, s[18:19] offset:0
	global_store_dword v246, v138, s[18:19] offset:64
	global_store_dword v246, v139, s[18:19] offset:128
	global_store_dword v246, v140, s[18:19] offset:192
	s_add_u32 s18, s18, 0x1000
	s_addc_u32 s19, s19, 0
	v_add_f32_e32 v3, v3, v205
	v_add_f32_e32 v7, v7, v206
	v_add_f32_e32 v11, v11, v207
	v_add_f32_e32 v15, v15, v208
	v_fma_f32 v141, v201, v3, v141
	v_fma_f32 v142, v202, v7, v142
	v_fma_f32 v143, v203, v11, v143
	v_fma_f32 v144, v204, v15, v144
	global_store_dword v246, v141, s[18:19] offset:0
	global_store_dword v246, v142, s[18:19] offset:64
	global_store_dword v246, v143, s[18:19] offset:128
	global_store_dword v246, v144, s[18:19] offset:192
	s_add_u32 s18, s18, 0xd000
	s_addc_u32 s19, s19, 0
	v_add_f32_e32 v16, v16, v205
	v_add_f32_e32 v20, v20, v206
	v_add_f32_e32 v24, v24, v207
	v_add_f32_e32 v28, v28, v208
	v_fma_f32 v145, v201, v16, v145
	v_fma_f32 v146, v202, v20, v146
	v_fma_f32 v147, v203, v24, v147
	v_fma_f32 v148, v204, v28, v148
	global_store_dword v246, v145, s[18:19] offset:0
	global_store_dword v246, v146, s[18:19] offset:64
	global_store_dword v246, v147, s[18:19] offset:128
	global_store_dword v246, v148, s[18:19] offset:192
	s_add_u32 s18, s18, 0x1000
	s_addc_u32 s19, s19, 0
	v_add_f32_e32 v17, v17, v205
	v_add_f32_e32 v21, v21, v206
	v_add_f32_e32 v25, v25, v207
	v_add_f32_e32 v29, v29, v208
	v_fma_f32 v149, v201, v17, v149
	v_fma_f32 v150, v202, v21, v150
	v_fma_f32 v151, v203, v25, v151
	v_fma_f32 v152, v204, v29, v152
	global_store_dword v246, v149, s[18:19] offset:0
	global_store_dword v246, v150, s[18:19] offset:64
	global_store_dword v246, v151, s[18:19] offset:128
	global_store_dword v246, v152, s[18:19] offset:192
	s_add_u32 s18, s18, 0x1000
	s_addc_u32 s19, s19, 0
	v_add_f32_e32 v18, v18, v205
	v_add_f32_e32 v22, v22, v206
	v_add_f32_e32 v26, v26, v207
	v_add_f32_e32 v30, v30, v208
	v_fma_f32 v153, v201, v18, v153
	v_fma_f32 v154, v202, v22, v154
	v_fma_f32 v155, v203, v26, v155
	v_fma_f32 v156, v204, v30, v156
	global_store_dword v246, v153, s[18:19] offset:0
	global_store_dword v246, v154, s[18:19] offset:64
	global_store_dword v246, v155, s[18:19] offset:128
	global_store_dword v246, v156, s[18:19] offset:192
	s_add_u32 s18, s18, 0x1000
	s_addc_u32 s19, s19, 0
	v_add_f32_e32 v19, v19, v205
	v_add_f32_e32 v23, v23, v206
	v_add_f32_e32 v27, v27, v207
	v_add_f32_e32 v31, v31, v208
	v_fma_f32 v157, v201, v19, v157
	v_fma_f32 v158, v202, v23, v158
	v_fma_f32 v159, v203, v27, v159
	v_fma_f32 v160, v204, v31, v160
	global_store_dword v246, v157, s[18:19] offset:0
	global_store_dword v246, v158, s[18:19] offset:64
	global_store_dword v246, v159, s[18:19] offset:128
	global_store_dword v246, v160, s[18:19] offset:192
	s_add_u32 s18, s18, 0xd000
	s_addc_u32 s19, s19, 0
	v_add_f32_e32 v32, v32, v205
	v_add_f32_e32 v36, v36, v206
	v_add_f32_e32 v40, v40, v207
	v_add_f32_e32 v44, v44, v208
	v_fma_f32 v161, v201, v32, v161
	v_fma_f32 v170, v202, v36, v170
	v_fma_f32 v171, v203, v40, v171
	v_fma_f32 v172, v204, v44, v172
	global_store_dword v246, v161, s[18:19] offset:0
	global_store_dword v246, v170, s[18:19] offset:64
	global_store_dword v246, v171, s[18:19] offset:128
	global_store_dword v246, v172, s[18:19] offset:192
	s_add_u32 s18, s18, 0x1000
	s_addc_u32 s19, s19, 0
	v_add_f32_e32 v33, v33, v205
	v_add_f32_e32 v37, v37, v206
	v_add_f32_e32 v41, v41, v207
	v_add_f32_e32 v45, v45, v208
	v_fma_f32 v173, v201, v33, v173
	v_fma_f32 v174, v202, v37, v174
	v_fma_f32 v175, v203, v41, v175
	v_fma_f32 v176, v204, v45, v176
	global_store_dword v246, v173, s[18:19] offset:0
	global_store_dword v246, v174, s[18:19] offset:64
	global_store_dword v246, v175, s[18:19] offset:128
	global_store_dword v246, v176, s[18:19] offset:192
	s_add_u32 s18, s18, 0x1000
	s_addc_u32 s19, s19, 0
	v_add_f32_e32 v34, v34, v205
	v_add_f32_e32 v38, v38, v206
	v_add_f32_e32 v42, v42, v207
	v_add_f32_e32 v46, v46, v208
	v_fma_f32 v177, v201, v34, v177
	v_fma_f32 v178, v202, v38, v178
	v_fma_f32 v179, v203, v42, v179
	v_fma_f32 v180, v204, v46, v180
	global_store_dword v246, v177, s[18:19] offset:0
	global_store_dword v246, v178, s[18:19] offset:64
	global_store_dword v246, v179, s[18:19] offset:128
	global_store_dword v246, v180, s[18:19] offset:192
	s_add_u32 s18, s18, 0x1000
	s_addc_u32 s19, s19, 0
	v_add_f32_e32 v35, v35, v205
	v_add_f32_e32 v39, v39, v206
	v_add_f32_e32 v43, v43, v207
	v_add_f32_e32 v47, v47, v208
	v_fma_f32 v181, v201, v35, v181
	v_fma_f32 v182, v202, v39, v182
	v_fma_f32 v183, v203, v43, v183
	v_fma_f32 v184, v204, v47, v184
	global_store_dword v246, v181, s[18:19] offset:0
	global_store_dword v246, v182, s[18:19] offset:64
	global_store_dword v246, v183, s[18:19] offset:128
	global_store_dword v246, v184, s[18:19] offset:192
	s_add_u32 s18, s18, 0xd000
	s_addc_u32 s19, s19, 0
	v_add_f32_e32 v48, v48, v205
	v_add_f32_e32 v52, v52, v206
	v_add_f32_e32 v56, v56, v207
	v_add_f32_e32 v60, v60, v208
	v_fma_f32 v185, v201, v48, v185
	v_fma_f32 v186, v202, v52, v186
	v_fma_f32 v187, v203, v56, v187
	v_fma_f32 v188, v204, v60, v188
	global_store_dword v246, v185, s[18:19] offset:0
	global_store_dword v246, v186, s[18:19] offset:64
	global_store_dword v246, v187, s[18:19] offset:128
	global_store_dword v246, v188, s[18:19] offset:192
	s_add_u32 s18, s18, 0x1000
	s_addc_u32 s19, s19, 0
	v_add_f32_e32 v49, v49, v205
	v_add_f32_e32 v53, v53, v206
	v_add_f32_e32 v57, v57, v207
	v_add_f32_e32 v61, v61, v208
	v_fma_f32 v189, v201, v49, v189
	v_fma_f32 v190, v202, v53, v190
	v_fma_f32 v191, v203, v57, v191
	v_fma_f32 v192, v204, v61, v192
	global_store_dword v246, v189, s[18:19] offset:0
	global_store_dword v246, v190, s[18:19] offset:64
	global_store_dword v246, v191, s[18:19] offset:128
	global_store_dword v246, v192, s[18:19] offset:192
	s_add_u32 s18, s18, 0x1000
	s_addc_u32 s19, s19, 0
	v_add_f32_e32 v50, v50, v205
	v_add_f32_e32 v54, v54, v206
	v_add_f32_e32 v58, v58, v207
	v_add_f32_e32 v62, v62, v208
	v_fma_f32 v193, v201, v50, v193
	v_fma_f32 v194, v202, v54, v194
	v_fma_f32 v195, v203, v58, v195
	v_fma_f32 v196, v204, v62, v196
	global_store_dword v246, v193, s[18:19] offset:0
	global_store_dword v246, v194, s[18:19] offset:64
	global_store_dword v246, v195, s[18:19] offset:128
	global_store_dword v246, v196, s[18:19] offset:192
	s_add_u32 s18, s18, 0x1000
	s_addc_u32 s19, s19, 0
	v_add_f32_e32 v51, v51, v205
	v_add_f32_e32 v55, v55, v206
	v_add_f32_e32 v59, v59, v207
	v_add_f32_e32 v63, v63, v208
	v_fma_f32 v197, v201, v51, v197
	v_fma_f32 v198, v202, v55, v198
	v_fma_f32 v199, v203, v59, v199
	v_fma_f32 v200, v204, v63, v200
	global_store_dword v246, v197, s[18:19] offset:0
	global_store_dword v246, v198, s[18:19] offset:64
	global_store_dword v246, v199, s[18:19] offset:128
	global_store_dword v246, v200, s[18:19] offset:192
	s_add_u32 s15, s15, s16
	s_branch .Lr13_tile

.Lr16_tile:
	s_cmp_lt_u32 s15, 0x200
	s_cbranch_scc0 .Lr16_end
	s_and_b32 s2, s15, 63
	s_lshr_b32 s3, s15, 6
	s_mul_i32 s14, s2, 0xb0000
	s_add_u32 s8, s26, s14
	s_addc_u32 s9, s27, 0
	s_mul_i32 s14, s3, 0xb0000
	s_add_u32 s10, s28, s14
	s_addc_u32 s11, s29, 0
	s_lshl_b32 s14, s2, 19
	s_lshl_b32 s6, s3, 9
	s_add_u32 s14, s14, s6
	s_add_u32 s20, s4, 0x6b7a100
	s_addc_u32 s21, s5, 0
	s_add_u32 s20, s20, s14
	s_addc_u32 s21, s21, 0
	s_sub_u32 s7, s2, 32
	s_lshr_b32 s7, s7, 3
	s_add_u32 s7, s7, 1
	s_cmp_lt_u32 s2, 32
	s_cselect_b32 s7, 0, s7
	s_mul_i32 s7, s7, 0x6000
	s_add_u32 s7, s7, s6
	s_add_u32 s22, s4, 0x6b25000
	s_addc_u32 s23, s5, 0
	s_add_u32 s22, s22, s7
	s_addc_u32 s23, s23, 0
	v_readfirstlane_b32 s12, v247
	s_lshl_b32 s12, s12, 12
	s_add_u32 m0, s12, 0x0
	v_mov_b32_e32 v0, 0
	global_load_lds_dwordx4 v248, s[8:9]
	v_mov_b32_e32 v1, 0
	s_add_u32 m0, s12, 0x400
	v_mov_b32_e32 v2, 0
	global_load_lds_dwordx4 v249, s[8:9]
	v_mov_b32_e32 v3, 0
	s_add_u32 m0, s12, 0x800
	v_mov_b32_e32 v4, 0
	global_load_lds_dwordx4 v250, s[8:9]
	v_mov_b32_e32 v5, 0
	s_add_u32 m0, s12, 0xc00
	v_mov_b32_e32 v6, 0
	global_load_lds_dwordx4 v251, s[8:9]
	v_mov_b32_e32 v7, 0
	s_add_u32 m0, s12, 0x8000
	v_mov_b32_e32 v8, 0
	global_load_lds_dwordx4 v248, s[10:11] sc1
	v_mov_b32_e32 v9, 0
	s_add_u32 m0, s12, 0x8400
	v_mov_b32_e32 v10, 0
	global_load_lds_dwordx4 v249, s[10:11] sc1
	v_mov_b32_e32 v11, 0
	s_add_u32 m0, s12, 0x8800
	v_mov_b32_e32 v12, 0
	global_load_lds_dwordx4 v250, s[10:11] sc1
	v_mov_b32_e32 v13, 0
	s_add_u32 m0, s12, 0x8c00
	v_mov_b32_e32 v14, 0
	global_load_lds_dwordx4 v251, s[10:11] sc1
	v_mov_b32_e32 v15, 0
	s_add_u32 s8, s8, 0x80
	s_addc_u32 s9, s9, 0
	s_add_u32 s10, s10, 0x80
	s_addc_u32 s11, s11, 0
	s_add_u32 m0, s12, 0x4000
	v_mov_b32_e32 v16, 0
	global_load_lds_dwordx4 v248, s[8:9]
	v_mov_b32_e32 v17, 0
	s_add_u32 m0, s12, 0x4400
	v_mov_b32_e32 v18, 0
	global_load_lds_dwordx4 v249, s[8:9]
	v_mov_b32_e32 v19, 0
	s_add_u32 m0, s12, 0x4800
	v_mov_b32_e32 v20, 0
	global_load_lds_dwordx4 v250, s[8:9]
	v_mov_b32_e32 v21, 0
	s_add_u32 m0, s12, 0x4c00
	v_mov_b32_e32 v22, 0
	global_load_lds_dwordx4 v251, s[8:9]
	v_mov_b32_e32 v23, 0
	s_add_u32 m0, s12, 0xc000
	v_mov_b32_e32 v24, 0
	global_load_lds_dwordx4 v248, s[10:11] sc1
	v_mov_b32_e32 v25, 0
	s_add_u32 m0, s12, 0xc400
	v_mov_b32_e32 v26, 0
	global_load_lds_dwordx4 v249, s[10:11] sc1
	v_mov_b32_e32 v27, 0
	s_add_u32 m0, s12, 0xc800
	v_mov_b32_e32 v28, 0
	global_load_lds_dwordx4 v250, s[10:11] sc1
	v_mov_b32_e32 v29, 0
	s_add_u32 m0, s12, 0xcc00
	v_mov_b32_e32 v30, 0
	global_load_lds_dwordx4 v251, s[10:11] sc1
	v_mov_b32_e32 v31, 0
	s_add_u32 s8, s8, 0x80
	s_addc_u32 s9, s9, 0
	s_add_u32 s10, s10, 0x80
	s_addc_u32 s11, s11, 0
	v_mov_b32_e32 v32, 0
	v_mov_b32_e32 v33, 0
	v_mov_b32_e32 v34, 0
	v_mov_b32_e32 v35, 0
	v_mov_b32_e32 v36, 0
	v_mov_b32_e32 v37, 0
	v_mov_b32_e32 v38, 0
	v_mov_b32_e32 v39, 0
	v_mov_b32_e32 v40, 0
	v_mov_b32_e32 v41, 0
	v_mov_b32_e32 v42, 0
	v_mov_b32_e32 v43, 0
	v_mov_b32_e32 v44, 0
	v_mov_b32_e32 v45, 0
	v_mov_b32_e32 v46, 0
	v_mov_b32_e32 v47, 0
	v_mov_b32_e32 v48, 0
	v_mov_b32_e32 v49, 0
	v_mov_b32_e32 v50, 0
	v_mov_b32_e32 v51, 0
	v_mov_b32_e32 v52, 0
	v_mov_b32_e32 v53, 0
	v_mov_b32_e32 v54, 0
	v_mov_b32_e32 v55, 0
	v_mov_b32_e32 v56, 0
	v_mov_b32_e32 v57, 0
	v_mov_b32_e32 v58, 0
	v_mov_b32_e32 v59, 0
	v_mov_b32_e32 v60, 0
	v_mov_b32_e32 v61, 0
	v_mov_b32_e32 v62, 0
	v_mov_b32_e32 v63, 0
	global_load_dword v201, v245, s[22:23] offset:0
	global_load_dword v202, v245, s[22:23] offset:64
	global_load_dword v203, v245, s[22:23] offset:128
	global_load_dword v204, v245, s[22:23] offset:192
	s_mov_b64 s[18:19], s[20:21]
	global_load_dword v129, v246, s[18:19] offset:0
	global_load_dword v130, v246, s[18:19] offset:64
	global_load_dword v131, v246, s[18:19] offset:128
	global_load_dword v132, v246, s[18:19] offset:192
	s_add_u32 s18, s18, 0x1000
	s_addc_u32 s19, s19, 0
	global_load_dword v133, v246, s[18:19] offset:0
	global_load_dword v134, v246, s[18:19] offset:64
	global_load_dword v135, v246, s[18:19] offset:128
	global_load_dword v136, v246, s[18:19] offset:192
	s_add_u32 s18, s18, 0x1000
	s_addc_u32 s19, s19, 0
	global_load_dword v137, v246, s[18:19] offset:0
	global_load_dword v138, v246, s[18:19] offset:64
	global_load_dword v139, v246, s[18:19] offset:128
	global_load_dword v140, v246, s[18:19] offset:192
	s_add_u32 s18, s18, 0x1000
	s_addc_u32 s19, s19, 0
	global_load_dword v141, v246, s[18:19] offset:0
	global_load_dword v142, v246, s[18:19] offset:64
	global_load_dword v143, v246, s[18:19] offset:128
	global_load_dword v144, v246, s[18:19] offset:192
	s_add_u32 s18, s18, 0xd000
	s_addc_u32 s19, s19, 0
	global_load_dword v145, v246, s[18:19] offset:0
	global_load_dword v146, v246, s[18:19] offset:64
	global_load_dword v147, v246, s[18:19] offset:128
	global_load_dword v148, v246, s[18:19] offset:192
	s_add_u32 s18, s18, 0x1000
	s_addc_u32 s19, s19, 0
	global_load_dword v149, v246, s[18:19] offset:0
	global_load_dword v150, v246, s[18:19] offset:64
	global_load_dword v151, v246, s[18:19] offset:128
	global_load_dword v152, v246, s[18:19] offset:192
	s_add_u32 s18, s18, 0x1000
	s_addc_u32 s19, s19, 0
	global_load_dword v153, v246, s[18:19] offset:0
	global_load_dword v154, v246, s[18:19] offset:64
	global_load_dword v155, v246, s[18:19] offset:128
	global_load_dword v156, v246, s[18:19] offset:192
	s_add_u32 s18, s18, 0x1000
	s_addc_u32 s19, s19, 0
	global_load_dword v157, v246, s[18:19] offset:0
	global_load_dword v158, v246, s[18:19] offset:64
	global_load_dword v159, v246, s[18:19] offset:128
	global_load_dword v160, v246, s[18:19] offset:192
	s_add_u32 s18, s18, 0xd000
	s_addc_u32 s19, s19, 0
	global_load_dword v161, v246, s[18:19] offset:0
	global_load_dword v170, v246, s[18:19] offset:64
	global_load_dword v171, v246, s[18:19] offset:128
	global_load_dword v172, v246, s[18:19] offset:192
	s_add_u32 s18, s18, 0x1000
	s_addc_u32 s19, s19, 0
	global_load_dword v173, v246, s[18:19] offset:0
	global_load_dword v174, v246, s[18:19] offset:64
	global_load_dword v175, v246, s[18:19] offset:128
	global_load_dword v176, v246, s[18:19] offset:192
	s_add_u32 s18, s18, 0x1000
	s_addc_u32 s19, s19, 0
	global_load_dword v177, v246, s[18:19] offset:0
	global_load_dword v178, v246, s[18:19] offset:64
	global_load_dword v179, v246, s[18:19] offset:128
	global_load_dword v180, v246, s[18:19] offset:192
	s_add_u32 s18, s18, 0x1000
	s_addc_u32 s19, s19, 0
	global_load_dword v181, v246, s[18:19] offset:0
	global_load_dword v182, v246, s[18:19] offset:64
	global_load_dword v183, v246, s[18:19] offset:128
	global_load_dword v184, v246, s[18:19] offset:192
	s_add_u32 s18, s18, 0xd000
	s_addc_u32 s19, s19, 0
	global_load_dword v185, v246, s[18:19] offset:0
	global_load_dword v186, v246, s[18:19] offset:64
	global_load_dword v187, v246, s[18:19] offset:128
	global_load_dword v188, v246, s[18:19] offset:192
	s_add_u32 s18, s18, 0x1000
	s_addc_u32 s19, s19, 0
	global_load_dword v189, v246, s[18:19] offset:0
	global_load_dword v190, v246, s[18:19] offset:64
	global_load_dword v191, v246, s[18:19] offset:128
	global_load_dword v192, v246, s[18:19] offset:192
	s_add_u32 s18, s18, 0x1000
	s_addc_u32 s19, s19, 0
	global_load_dword v193, v246, s[18:19] offset:0
	global_load_dword v194, v246, s[18:19] offset:64
	global_load_dword v195, v246, s[18:19] offset:128
	global_load_dword v196, v246, s[18:19] offset:192
	s_add_u32 s18, s18, 0x1000
	s_addc_u32 s19, s19, 0
	global_load_dword v197, v246, s[18:19] offset:0
	global_load_dword v198, v246, s[18:19] offset:64
	global_load_dword v199, v246, s[18:19] offset:128
	global_load_dword v200, v246, s[18:19] offset:192
	s_waitcnt vmcnt(63)
	s_barrier
	ds_read_b128 v[64:67], v252 offset:0
	ds_read_b128 v[96:99], v254 offset:32768
	ds_read_b128 v[100:103], v254 offset:34816
	ds_read_b128 v[104:107], v254 offset:36864
	ds_read_b128 v[108:111], v254 offset:38912
	ds_read_b128 v[68:71], v252 offset:2048
	ds_read_b128 v[72:75], v252 offset:4096
	ds_read_b128 v[76:79], v252 offset:6144
	ds_read_b128 v[80:83], v253 offset:0
	ds_read_b128 v[112:115], v255 offset:32768
	ds_read_b128 v[116:119], v255 offset:34816
	ds_read_b128 v[120:123], v255 offset:36864
	ds_read_b128 v[124:127], v255 offset:38912
	s_waitcnt lgkmcnt(11)
	v_mfma_f32_16x16x32_bf16 v[0:3], v[64:67], v[96:99], v[0:3]
	s_waitcnt lgkmcnt(10)
	v_mfma_f32_16x16x32_bf16 v[4:7], v[64:67], v[100:103], v[4:7]
	s_waitcnt lgkmcnt(9)
	v_mfma_f32_16x16x32_bf16 v[8:11], v[64:67], v[104:107], v[8:11]
	s_waitcnt lgkmcnt(8)
	v_mfma_f32_16x16x32_bf16 v[12:15], v[64:67], v[108:111], v[12:15]
	ds_read_b128 v[84:87], v253 offset:2048
	ds_read_b128 v[88:91], v253 offset:4096
	ds_read_b128 v[92:95], v253 offset:6144
	s_waitcnt lgkmcnt(10)
	v_mfma_f32_16x16x32_bf16 v[16:19], v[68:71], v[96:99], v[16:19]
	v_mfma_f32_16x16x32_bf16 v[20:23], v[68:71], v[100:103], v[20:23]
	v_mfma_f32_16x16x32_bf16 v[24:27], v[68:71], v[104:107], v[24:27]
	v_mfma_f32_16x16x32_bf16 v[28:31], v[68:71], v[108:111], v[28:31]
	s_waitcnt lgkmcnt(0)
	s_barrier
	s_add_u32 m0, s12, 0x0
	v_mfma_f32_16x16x32_bf16 v[32:35], v[72:75], v[96:99], v[32:35]
	global_load_lds_dwordx4 v248, s[8:9]
	s_add_u32 m0, s12, 0x400
	v_mfma_f32_16x16x32_bf16 v[36:39], v[72:75], v[100:103], v[36:39]
	global_load_lds_dwordx4 v249, s[8:9]
	s_add_u32 m0, s12, 0x800
	v_mfma_f32_16x16x32_bf16 v[40:43], v[72:75], v[104:107], v[40:43]
	global_load_lds_dwordx4 v250, s[8:9]
	s_add_u32 m0, s12, 0xc00
	v_mfma_f32_16x16x32_bf16 v[44:47], v[72:75], v[108:111], v[44:47]
	global_load_lds_dwordx4 v251, s[8:9]
	s_add_u32 m0, s12, 0x8000
	v_mfma_f32_16x16x32_bf16 v[48:51], v[76:79], v[96:99], v[48:51]
	global_load_lds_dwordx4 v248, s[10:11] sc1
	s_add_u32 m0, s12, 0x8400
	v_mfma_f32_16x16x32_bf16 v[52:55], v[76:79], v[100:103], v[52:55]
	global_load_lds_dwordx4 v249, s[10:11] sc1
	s_add_u32 m0, s12, 0x8800
	v_mfma_f32_16x16x32_bf16 v[56:59], v[76:79], v[104:107], v[56:59]
	global_load_lds_dwordx4 v250, s[10:11] sc1
	s_add_u32 m0, s12, 0x8c00
	v_mfma_f32_16x16x32_bf16 v[60:63], v[76:79], v[108:111], v[60:63]
	global_load_lds_dwordx4 v251, s[10:11] sc1
	s_add_u32 s8, s8, 0x80
	s_addc_u32 s9, s9, 0
	s_add_u32 s10, s10, 0x80
	s_addc_u32 s11, s11, 0
	s_waitcnt vmcnt(63)
	s_barrier
	ds_read_b128 v[64:67], v252 offset:16384
	ds_read_b128 v[96:99], v254 offset:49152
	ds_read_b128 v[100:103], v254 offset:51200
	ds_read_b128 v[104:107], v254 offset:53248
	ds_read_b128 v[108:111], v254 offset:55296
	ds_read_b128 v[68:71], v252 offset:18432
	ds_read_b128 v[72:75], v252 offset:20480
	ds_read_b128 v[76:79], v252 offset:22528
	v_mfma_f32_16x16x32_bf16 v[0:3], v[80:83], v[112:115], v[0:3]
	v_mfma_f32_16x16x32_bf16 v[4:7], v[80:83], v[116:119], v[4:7]
	v_mfma_f32_16x16x32_bf16 v[8:11], v[80:83], v[120:123], v[8:11]
	v_mfma_f32_16x16x32_bf16 v[12:15], v[80:83], v[124:127], v[12:15]
	v_mfma_f32_16x16x32_bf16 v[16:19], v[84:87], v[112:115], v[16:19]
	v_mfma_f32_16x16x32_bf16 v[20:23], v[84:87], v[116:119], v[20:23]
	v_mfma_f32_16x16x32_bf16 v[24:27], v[84:87], v[120:123], v[24:27]
	v_mfma_f32_16x16x32_bf16 v[28:31], v[84:87], v[124:127], v[28:31]
	v_mfma_f32_16x16x32_bf16 v[32:35], v[88:91], v[112:115], v[32:35]
	v_mfma_f32_16x16x32_bf16 v[36:39], v[88:91], v[116:119], v[36:39]
	v_mfma_f32_16x16x32_bf16 v[40:43], v[88:91], v[120:123], v[40:43]
	v_mfma_f32_16x16x32_bf16 v[44:47], v[88:91], v[124:127], v[44:47]
	v_mfma_f32_16x16x32_bf16 v[48:51], v[92:95], v[112:115], v[48:51]
	v_mfma_f32_16x16x32_bf16 v[52:55], v[92:95], v[116:119], v[52:55]
	v_mfma_f32_16x16x32_bf16 v[56:59], v[92:95], v[120:123], v[56:59]
	v_mfma_f32_16x16x32_bf16 v[60:63], v[92:95], v[124:127], v[60:63]
	ds_read_b128 v[80:83], v253 offset:16384
	ds_read_b128 v[112:115], v255 offset:49152
	ds_read_b128 v[116:119], v255 offset:51200
	ds_read_b128 v[120:123], v255 offset:53248
	ds_read_b128 v[124:127], v255 offset:55296
	ds_read_b128 v[84:87], v253 offset:18432
	ds_read_b128 v[88:91], v253 offset:20480
	ds_read_b128 v[92:95], v253 offset:22528
	s_waitcnt lgkmcnt(14)
	v_mfma_f32_16x16x32_bf16 v[0:3], v[64:67], v[96:99], v[0:3]
	s_waitcnt lgkmcnt(13)
	v_mfma_f32_16x16x32_bf16 v[4:7], v[64:67], v[100:103], v[4:7]
	s_waitcnt lgkmcnt(12)
	v_mfma_f32_16x16x32_bf16 v[8:11], v[64:67], v[104:107], v[8:11]
	s_waitcnt lgkmcnt(11)
	v_mfma_f32_16x16x32_bf16 v[12:15], v[64:67], v[108:111], v[12:15]
	s_waitcnt lgkmcnt(10)
	v_mfma_f32_16x16x32_bf16 v[16:19], v[68:71], v[96:99], v[16:19]
	v_mfma_f32_16x16x32_bf16 v[20:23], v[68:71], v[100:103], v[20:23]
	v_mfma_f32_16x16x32_bf16 v[24:27], v[68:71], v[104:107], v[24:27]
	v_mfma_f32_16x16x32_bf16 v[28:31], v[68:71], v[108:111], v[28:31]
	s_waitcnt lgkmcnt(0)
	s_barrier
	s_add_u32 m0, s12, 0x4000
	v_mfma_f32_16x16x32_bf16 v[32:35], v[72:75], v[96:99], v[32:35]
	global_load_lds_dwordx4 v248, s[8:9]
	s_add_u32 m0, s12, 0x4400
	v_mfma_f32_16x16x32_bf16 v[36:39], v[72:75], v[100:103], v[36:39]
	global_load_lds_dwordx4 v249, s[8:9]
	s_add_u32 m0, s12, 0x4800
	v_mfma_f32_16x16x32_bf16 v[40:43], v[72:75], v[104:107], v[40:43]
	global_load_lds_dwordx4 v250, s[8:9]
	s_add_u32 m0, s12, 0x4c00
	v_mfma_f32_16x16x32_bf16 v[44:47], v[72:75], v[108:111], v[44:47]
	global_load_lds_dwordx4 v251, s[8:9]
	s_add_u32 m0, s12, 0xc000
	v_mfma_f32_16x16x32_bf16 v[48:51], v[76:79], v[96:99], v[48:51]
	global_load_lds_dwordx4 v248, s[10:11] sc1
	s_add_u32 m0, s12, 0xc400
	v_mfma_f32_16x16x32_bf16 v[52:55], v[76:79], v[100:103], v[52:55]
	global_load_lds_dwordx4 v249, s[10:11] sc1
	s_add_u32 m0, s12, 0xc800
	v_mfma_f32_16x16x32_bf16 v[56:59], v[76:79], v[104:107], v[56:59]
	global_load_lds_dwordx4 v250, s[10:11] sc1
	s_add_u32 m0, s12, 0xcc00
	v_mfma_f32_16x16x32_bf16 v[60:63], v[76:79], v[108:111], v[60:63]
	global_load_lds_dwordx4 v251, s[10:11] sc1
	s_add_u32 s8, s8, 0x80
	s_addc_u32 s9, s9, 0
	s_add_u32 s10, s10, 0x80
	s_addc_u32 s11, s11, 0
	s_mov_b32 s13, 20

.LBB0_1581:
	s_and_b32 s8, s68, 0xffffff80
	s_ashr_i32 s9, s8, 31
	s_lshl_b32 s7, s70, 11
	s_lshl_b64 s[8:9], s[8:9], 11
	s_and_b32 s22, s7, 0xfc0000
	s_add_i32 s2, s2, s3
	s_cmpk_gt_i32 s2, 0xbff
	s_cselect_b64 s[62:63], -1, 0
	s_lshl_b32 s7, s2, 18
	s_and_b32 s7, s7, 0xfc0000
	s_add_u32 s7, s18, s7
	v_lshl_add_u64 v[126:127], v[114:115], 0, s[8:9]
	s_addc_u32 s10, s19, 0
	s_ashr_i32 s8, s2, 6
	s_ashr_i32 s9, s8, 31
	s_lshl_b64 s[8:9], s[8:9], 18
	v_lshl_add_u64 v[130:131], v[116:117], 0, s[22:23]
	s_add_u32 s22, s20, s8
	s_addc_u32 s11, s21, s9
	s_cmpk_lt_i32 s2, 0xc00
	s_cselect_b64 vcc, -1, 0
	s_and_b64 s[8:9], vcc, exec
	s_cselect_b32 s9, s10, 0
	s_cselect_b32 s8, s7, 0
	v_lshl_add_u64 v[2:3], s[8:9], 0, v[118:119]
	v_lshl_add_u64 v[0:1], v[122:123], 0, s[46:47]
	s_cselect_b32 s11, s11, 0
	s_cselect_b32 s10, s22, 0
	v_lshl_add_u64 v[2:3], v[2:3], 0, v[120:121]
	v_cndmask_b32_e32 v97, v1, v3, vcc
	v_cndmask_b32_e32 v98, v0, v2, vcc
	v_lshl_add_u64 v[0:1], s[10:11], 0, v[118:119]
	v_lshl_add_u64 v[0:1], v[0:1], 0, v[120:121]
	v_lshl_add_u64 v[2:3], v[124:125], 0, s[46:47]
	v_cndmask_b32_e32 v144, v2, v0, vcc
	v_mov_b32_e32 v0, 0
	v_lshl_add_u64 v[146:147], v[122:123], 0, s[30:31]
	v_lshl_add_u64 v[132:133], v[122:123], 0, s[34:35]
	v_lshl_add_u64 v[150:151], v[122:123], 0, s[36:37]
	v_lshl_add_u64 v[134:135], v[122:123], 0, s[38:39]
	v_lshl_add_u64 v[152:153], v[122:123], 0, s[40:41]
	v_lshl_add_u64 v[136:137], v[122:123], 0, s[42:43]
	v_lshl_add_u64 v[154:155], v[122:123], 0, s[44:45]
	v_lshl_add_u64 v[148:149], v[124:125], 0, s[30:31]
	v_lshl_add_u64 v[138:139], v[124:125], 0, s[34:35]
	v_lshl_add_u64 v[156:157], v[124:125], 0, s[36:37]
	v_lshl_add_u64 v[140:141], v[124:125], 0, s[38:39]
	v_lshl_add_u64 v[158:159], v[124:125], 0, s[40:41]
	v_lshl_add_u64 v[142:143], v[124:125], 0, s[42:43]
	v_lshl_add_u64 v[160:161], v[124:125], 0, s[44:45]
	v_cndmask_b32_e32 v129, v3, v1, vcc
	s_mov_b32 s7, -2
	v_mov_b32_e32 v1, v0
	v_mov_b32_e32 v2, v0
	v_mov_b32_e32 v3, v0
	v_mov_b32_e32 v20, v0
	v_mov_b32_e32 v21, v0
	v_mov_b32_e32 v22, v0
	v_mov_b32_e32 v23, v0
	v_mov_b32_e32 v24, v0
	v_mov_b32_e32 v25, v0
	v_mov_b32_e32 v26, v0
	v_mov_b32_e32 v27, v0
	v_mov_b32_e32 v32, v0
	v_mov_b32_e32 v33, v0
	v_mov_b32_e32 v34, v0
	v_mov_b32_e32 v35, v0
	v_mov_b32_e32 v8, v0
	v_mov_b32_e32 v9, v0
	v_mov_b32_e32 v10, v0
	v_mov_b32_e32 v11, v0
	v_mov_b32_e32 v4, v0
	v_mov_b32_e32 v5, v0
	v_mov_b32_e32 v6, v0
	v_mov_b32_e32 v7, v0
	v_mov_b32_e32 v12, v0
	v_mov_b32_e32 v13, v0
	v_mov_b32_e32 v14, v0
	v_mov_b32_e32 v15, v0
	v_mov_b32_e32 v16, v0
	v_mov_b32_e32 v17, v0
	v_mov_b32_e32 v18, v0
	v_mov_b32_e32 v19, v0
	v_mov_b32_e32 v28, v0
	v_mov_b32_e32 v29, v0
	v_mov_b32_e32 v30, v0
	v_mov_b32_e32 v31, v0
	v_mov_b32_e32 v36, v0
	v_mov_b32_e32 v37, v0
	v_mov_b32_e32 v38, v0
	v_mov_b32_e32 v39, v0
	v_mov_b32_e32 v40, v0
	v_mov_b32_e32 v41, v0
	v_mov_b32_e32 v42, v0
	v_mov_b32_e32 v43, v0
	v_mov_b32_e32 v44, v0
	v_mov_b32_e32 v45, v0
	v_mov_b32_e32 v46, v0
	v_mov_b32_e32 v47, v0
	v_mov_b32_e32 v48, v0
	v_mov_b32_e32 v49, v0
	v_mov_b32_e32 v50, v0
	v_mov_b32_e32 v51, v0
	v_mov_b32_e32 v52, v0
	v_mov_b32_e32 v53, v0
	v_mov_b32_e32 v54, v0
	v_mov_b32_e32 v55, v0
	v_mov_b32_e32 v56, v0
	v_mov_b32_e32 v57, v0
	v_mov_b32_e32 v58, v0
	v_mov_b32_e32 v59, v0
	v_mov_b32_e32 v60, v0
	v_mov_b32_e32 v61, v0
	v_mov_b32_e32 v62, v0
	v_mov_b32_e32 v63, v0
	v_readfirstlane_b32 s8, v122
	v_readfirstlane_b32 s9, v123
	v_readfirstlane_b32 s64, v124
	v_readfirstlane_b32 s65, v125
	v_readfirstlane_b32 s7, v247
	s_nop 3
	s_mul_i32 s66, s7, 0x4000
	s_sub_u32 s8, s8, s66
	s_subb_u32 s9, s9, 0
	s_sub_u32 s64, s64, s66
	s_subb_u32 s65, s65, 0
	s_lshl_b32 s7, s7, 12
	s_add_u32 m0, s7, 0x0
	v_mov_b32_e32 v60, 0
	global_load_lds_dwordx4 v248, s[8:9]
	v_mov_b32_e32 v61, 0
	s_add_u32 m0, s7, 0x400
	v_mov_b32_e32 v62, 0
	global_load_lds_dwordx4 v249, s[8:9]
	v_mov_b32_e32 v63, 0
	s_add_u32 m0, s7, 0x800
	v_mov_b32_e32 v56, 0
	global_load_lds_dwordx4 v250, s[8:9]
	v_mov_b32_e32 v57, 0
	s_add_u32 m0, s7, 0xc00
	v_mov_b32_e32 v58, 0
	global_load_lds_dwordx4 v251, s[8:9]
	v_mov_b32_e32 v59, 0
	s_add_u32 m0, s7, 0x8000
	v_mov_b32_e32 v52, 0
	global_load_lds_dwordx4 v248, s[64:65] sc1
	v_mov_b32_e32 v53, 0
	s_add_u32 m0, s7, 0x8400
	v_mov_b32_e32 v54, 0
	global_load_lds_dwordx4 v249, s[64:65] sc1
	v_mov_b32_e32 v55, 0
	s_add_u32 m0, s7, 0x8800
	v_mov_b32_e32 v48, 0
	global_load_lds_dwordx4 v250, s[64:65] sc1
	v_mov_b32_e32 v49, 0
	s_add_u32 m0, s7, 0x8c00
	v_mov_b32_e32 v50, 0
	global_load_lds_dwordx4 v251, s[64:65] sc1
	v_mov_b32_e32 v51, 0
	s_add_u32 s8, s8, 0x80
	s_addc_u32 s9, s9, 0
	s_add_u32 s64, s64, 0x80
	s_addc_u32 s65, s65, 0
	s_add_u32 m0, s7, 0x4000
	v_mov_b32_e32 v44, 0
	global_load_lds_dwordx4 v248, s[8:9]
	v_mov_b32_e32 v45, 0
	s_add_u32 m0, s7, 0x4400
	v_mov_b32_e32 v46, 0
	global_load_lds_dwordx4 v249, s[8:9]
	v_mov_b32_e32 v47, 0
	s_add_u32 m0, s7, 0x4800
	v_mov_b32_e32 v40, 0
	global_load_lds_dwordx4 v250, s[8:9]
	v_mov_b32_e32 v41, 0
	s_add_u32 m0, s7, 0x4c00
	v_mov_b32_e32 v42, 0
	global_load_lds_dwordx4 v251, s[8:9]
	v_mov_b32_e32 v43, 0
	s_add_u32 m0, s7, 0xc000
	v_mov_b32_e32 v36, 0
	global_load_lds_dwordx4 v248, s[64:65] sc1
	v_mov_b32_e32 v37, 0
	s_add_u32 m0, s7, 0xc400
	v_mov_b32_e32 v38, 0
	global_load_lds_dwordx4 v249, s[64:65] sc1
	v_mov_b32_e32 v39, 0
	s_add_u32 m0, s7, 0xc800
	v_mov_b32_e32 v28, 0
	global_load_lds_dwordx4 v250, s[64:65] sc1
	v_mov_b32_e32 v29, 0
	s_add_u32 m0, s7, 0xcc00
	v_mov_b32_e32 v30, 0
	global_load_lds_dwordx4 v251, s[64:65] sc1
	v_mov_b32_e32 v31, 0
	s_add_u32 s8, s8, 0x80
	s_addc_u32 s9, s9, 0
	s_add_u32 s64, s64, 0x80
	s_addc_u32 s65, s65, 0
	v_mov_b32_e32 v16, 0
	v_mov_b32_e32 v17, 0
	v_mov_b32_e32 v18, 0
	v_mov_b32_e32 v19, 0
	v_mov_b32_e32 v12, 0
	v_mov_b32_e32 v13, 0
	v_mov_b32_e32 v14, 0
	v_mov_b32_e32 v15, 0
	v_mov_b32_e32 v4, 0
	v_mov_b32_e32 v5, 0
	v_mov_b32_e32 v6, 0
	v_mov_b32_e32 v7, 0
	v_mov_b32_e32 v8, 0
	v_mov_b32_e32 v9, 0
	v_mov_b32_e32 v10, 0
	v_mov_b32_e32 v11, 0
	v_mov_b32_e32 v32, 0
	v_mov_b32_e32 v33, 0
	v_mov_b32_e32 v34, 0
	v_mov_b32_e32 v35, 0
	v_mov_b32_e32 v24, 0
	v_mov_b32_e32 v25, 0
	v_mov_b32_e32 v26, 0
	v_mov_b32_e32 v27, 0
	v_mov_b32_e32 v20, 0
	v_mov_b32_e32 v21, 0
	v_mov_b32_e32 v22, 0
	v_mov_b32_e32 v23, 0
	v_mov_b32_e32 v0, 0
	v_mov_b32_e32 v1, 0
	v_mov_b32_e32 v2, 0
	v_mov_b32_e32 v3, 0
	s_waitcnt vmcnt(8)
	s_barrier
	ds_read_b128 v[80:83], v252 offset:0
	ds_read_b128 v[144:147], v254 offset:32768
	ds_read_b128 v[148:151], v254 offset:34816
	ds_read_b128 v[152:155], v254 offset:36864
	ds_read_b128 v[156:159], v254 offset:38912
	ds_read_b128 v[84:87], v252 offset:2048
	ds_read_b128 v[88:91], v252 offset:4096
	ds_read_b128 v[92:95], v252 offset:6144
	ds_read_b128 v[124:127], v253 offset:0
	ds_read_b128 v[180:183], v255 offset:32768
	ds_read_b128 v[184:187], v255 offset:34816
	ds_read_b128 v[188:191], v255 offset:36864
	ds_read_b128 v[192:195], v255 offset:38912
	s_waitcnt lgkmcnt(11)
	v_mfma_f32_16x16x32_bf16 v[60:63], v[80:83], v[144:147], v[60:63]
	s_waitcnt lgkmcnt(10)
	v_mfma_f32_16x16x32_bf16 v[56:59], v[80:83], v[148:151], v[56:59]
	s_waitcnt lgkmcnt(9)
	v_mfma_f32_16x16x32_bf16 v[52:55], v[80:83], v[152:155], v[52:55]
	s_waitcnt lgkmcnt(8)
	v_mfma_f32_16x16x32_bf16 v[48:51], v[80:83], v[156:159], v[48:51]
	ds_read_b128 v[132:135], v253 offset:2048
	ds_read_b128 v[136:139], v253 offset:4096
	ds_read_b128 v[140:143], v253 offset:6144
	s_waitcnt lgkmcnt(10)
	v_mfma_f32_16x16x32_bf16 v[44:47], v[84:87], v[144:147], v[44:47]
	v_mfma_f32_16x16x32_bf16 v[40:43], v[84:87], v[148:151], v[40:43]
	v_mfma_f32_16x16x32_bf16 v[36:39], v[84:87], v[152:155], v[36:39]
	v_mfma_f32_16x16x32_bf16 v[28:31], v[84:87], v[156:159], v[28:31]
	s_waitcnt lgkmcnt(0)
	s_barrier
	s_add_u32 m0, s7, 0x0
	v_mfma_f32_16x16x32_bf16 v[16:19], v[88:91], v[144:147], v[16:19]
	global_load_lds_dwordx4 v248, s[8:9]
	s_add_u32 m0, s7, 0x400
	v_mfma_f32_16x16x32_bf16 v[12:15], v[88:91], v[148:151], v[12:15]
	global_load_lds_dwordx4 v249, s[8:9]
	s_add_u32 m0, s7, 0x800
	v_mfma_f32_16x16x32_bf16 v[4:7], v[88:91], v[152:155], v[4:7]
	global_load_lds_dwordx4 v250, s[8:9]
	s_add_u32 m0, s7, 0xc00
	v_mfma_f32_16x16x32_bf16 v[8:11], v[88:91], v[156:159], v[8:11]
	global_load_lds_dwordx4 v251, s[8:9]
	s_add_u32 m0, s7, 0x8000
	v_mfma_f32_16x16x32_bf16 v[32:35], v[92:95], v[144:147], v[32:35]
	global_load_lds_dwordx4 v248, s[64:65] sc1
	s_add_u32 m0, s7, 0x8400
	v_mfma_f32_16x16x32_bf16 v[24:27], v[92:95], v[148:151], v[24:27]
	global_load_lds_dwordx4 v249, s[64:65] sc1
	s_add_u32 m0, s7, 0x8800
	v_mfma_f32_16x16x32_bf16 v[20:23], v[92:95], v[152:155], v[20:23]
	global_load_lds_dwordx4 v250, s[64:65] sc1
	s_add_u32 m0, s7, 0x8c00
	v_mfma_f32_16x16x32_bf16 v[0:3], v[92:95], v[156:159], v[0:3]
	global_load_lds_dwordx4 v251, s[64:65] sc1
	s_add_u32 s8, s8, 0x80
	s_addc_u32 s9, s9, 0
	s_add_u32 s64, s64, 0x80
	s_addc_u32 s65, s65, 0
	s_waitcnt vmcnt(8)
	s_barrier
	ds_read_b128 v[80:83], v252 offset:16384
	ds_read_b128 v[144:147], v254 offset:49152
	ds_read_b128 v[148:151], v254 offset:51200
	ds_read_b128 v[152:155], v254 offset:53248
	ds_read_b128 v[156:159], v254 offset:55296
	ds_read_b128 v[84:87], v252 offset:18432
	ds_read_b128 v[88:91], v252 offset:20480
	ds_read_b128 v[92:95], v252 offset:22528
	v_mfma_f32_16x16x32_bf16 v[60:63], v[124:127], v[180:183], v[60:63]
	v_mfma_f32_16x16x32_bf16 v[56:59], v[124:127], v[184:187], v[56:59]
	v_mfma_f32_16x16x32_bf16 v[52:55], v[124:127], v[188:191], v[52:55]
	v_mfma_f32_16x16x32_bf16 v[48:51], v[124:127], v[192:195], v[48:51]
	v_mfma_f32_16x16x32_bf16 v[44:47], v[132:135], v[180:183], v[44:47]
	v_mfma_f32_16x16x32_bf16 v[40:43], v[132:135], v[184:187], v[40:43]
	v_mfma_f32_16x16x32_bf16 v[36:39], v[132:135], v[188:191], v[36:39]
	v_mfma_f32_16x16x32_bf16 v[28:31], v[132:135], v[192:195], v[28:31]
	v_mfma_f32_16x16x32_bf16 v[16:19], v[136:139], v[180:183], v[16:19]
	v_mfma_f32_16x16x32_bf16 v[12:15], v[136:139], v[184:187], v[12:15]
	v_mfma_f32_16x16x32_bf16 v[4:7], v[136:139], v[188:191], v[4:7]
	v_mfma_f32_16x16x32_bf16 v[8:11], v[136:139], v[192:195], v[8:11]
	v_mfma_f32_16x16x32_bf16 v[32:35], v[140:143], v[180:183], v[32:35]
	v_mfma_f32_16x16x32_bf16 v[24:27], v[140:143], v[184:187], v[24:27]
	v_mfma_f32_16x16x32_bf16 v[20:23], v[140:143], v[188:191], v[20:23]
	v_mfma_f32_16x16x32_bf16 v[0:3], v[140:143], v[192:195], v[0:3]
	ds_read_b128 v[124:127], v253 offset:16384
	ds_read_b128 v[180:183], v255 offset:49152
	ds_read_b128 v[184:187], v255 offset:51200
	ds_read_b128 v[188:191], v255 offset:53248
	ds_read_b128 v[192:195], v255 offset:55296
	ds_read_b128 v[132:135], v253 offset:18432
	ds_read_b128 v[136:139], v253 offset:20480
	ds_read_b128 v[140:143], v253 offset:22528
	s_waitcnt lgkmcnt(14)
	v_mfma_f32_16x16x32_bf16 v[60:63], v[80:83], v[144:147], v[60:63]
	s_waitcnt lgkmcnt(13)
	v_mfma_f32_16x16x32_bf16 v[56:59], v[80:83], v[148:151], v[56:59]
	s_waitcnt lgkmcnt(12)
	v_mfma_f32_16x16x32_bf16 v[52:55], v[80:83], v[152:155], v[52:55]
	s_waitcnt lgkmcnt(11)
	v_mfma_f32_16x16x32_bf16 v[48:51], v[80:83], v[156:159], v[48:51]
	s_waitcnt lgkmcnt(10)
	v_mfma_f32_16x16x32_bf16 v[44:47], v[84:87], v[144:147], v[44:47]
	v_mfma_f32_16x16x32_bf16 v[40:43], v[84:87], v[148:151], v[40:43]
	v_mfma_f32_16x16x32_bf16 v[36:39], v[84:87], v[152:155], v[36:39]
	v_mfma_f32_16x16x32_bf16 v[28:31], v[84:87], v[156:159], v[28:31]
	s_waitcnt lgkmcnt(0)
	s_barrier
	s_add_u32 m0, s7, 0x4000
	v_mfma_f32_16x16x32_bf16 v[16:19], v[88:91], v[144:147], v[16:19]
	global_load_lds_dwordx4 v248, s[8:9]
	s_add_u32 m0, s7, 0x4400
	v_mfma_f32_16x16x32_bf16 v[12:15], v[88:91], v[148:151], v[12:15]
	global_load_lds_dwordx4 v249, s[8:9]
	s_add_u32 m0, s7, 0x4800
	v_mfma_f32_16x16x32_bf16 v[4:7], v[88:91], v[152:155], v[4:7]
	global_load_lds_dwordx4 v250, s[8:9]
	s_add_u32 m0, s7, 0x4c00
	v_mfma_f32_16x16x32_bf16 v[8:11], v[88:91], v[156:159], v[8:11]
	global_load_lds_dwordx4 v251, s[8:9]
	s_add_u32 m0, s7, 0xc000
	v_mfma_f32_16x16x32_bf16 v[32:35], v[92:95], v[144:147], v[32:35]
	global_load_lds_dwordx4 v248, s[64:65] sc1
	s_add_u32 m0, s7, 0xc400
	v_mfma_f32_16x16x32_bf16 v[24:27], v[92:95], v[148:151], v[24:27]
	global_load_lds_dwordx4 v249, s[64:65] sc1
	s_add_u32 m0, s7, 0xc800
	v_mfma_f32_16x16x32_bf16 v[20:23], v[92:95], v[152:155], v[20:23]
	global_load_lds_dwordx4 v250, s[64:65] sc1
	s_add_u32 m0, s7, 0xcc00
	v_mfma_f32_16x16x32_bf16 v[0:3], v[92:95], v[156:159], v[0:3]
	global_load_lds_dwordx4 v251, s[64:65] sc1
	s_add_u32 s8, s8, 0x80
	s_addc_u32 s9, s9, 0
	s_add_u32 s64, s64, 0x80
	s_addc_u32 s65, s65, 0
	s_mov_b32 s32, 6
.Lg18_loop:
	s_waitcnt vmcnt(8)
	s_barrier
	ds_read_b128 v[80:83], v252 offset:0
	ds_read_b128 v[144:147], v254 offset:32768
	ds_read_b128 v[148:151], v254 offset:34816
	ds_read_b128 v[152:155], v254 offset:36864
	ds_read_b128 v[156:159], v254 offset:38912
	ds_read_b128 v[84:87], v252 offset:2048
	ds_read_b128 v[88:91], v252 offset:4096
	ds_read_b128 v[92:95], v252 offset:6144
	v_mfma_f32_16x16x32_bf16 v[60:63], v[124:127], v[180:183], v[60:63]
	v_mfma_f32_16x16x32_bf16 v[56:59], v[124:127], v[184:187], v[56:59]
	v_mfma_f32_16x16x32_bf16 v[52:55], v[124:127], v[188:191], v[52:55]
	v_mfma_f32_16x16x32_bf16 v[48:51], v[124:127], v[192:195], v[48:51]
	v_mfma_f32_16x16x32_bf16 v[44:47], v[132:135], v[180:183], v[44:47]
	v_mfma_f32_16x16x32_bf16 v[40:43], v[132:135], v[184:187], v[40:43]
	v_mfma_f32_16x16x32_bf16 v[36:39], v[132:135], v[188:191], v[36:39]
	v_mfma_f32_16x16x32_bf16 v[28:31], v[132:135], v[192:195], v[28:31]
	v_mfma_f32_16x16x32_bf16 v[16:19], v[136:139], v[180:183], v[16:19]
	v_mfma_f32_16x16x32_bf16 v[12:15], v[136:139], v[184:187], v[12:15]
	v_mfma_f32_16x16x32_bf16 v[4:7], v[136:139], v[188:191], v[4:7]
	v_mfma_f32_16x16x32_bf16 v[8:11], v[136:139], v[192:195], v[8:11]
	v_mfma_f32_16x16x32_bf16 v[32:35], v[140:143], v[180:183], v[32:35]
	v_mfma_f32_16x16x32_bf16 v[24:27], v[140:143], v[184:187], v[24:27]
	v_mfma_f32_16x16x32_bf16 v[20:23], v[140:143], v[188:191], v[20:23]
	v_mfma_f32_16x16x32_bf16 v[0:3], v[140:143], v[192:195], v[0:3]
	ds_read_b128 v[124:127], v253 offset:0
	ds_read_b128 v[180:183], v255 offset:32768
	ds_read_b128 v[184:187], v255 offset:34816
	ds_read_b128 v[188:191], v255 offset:36864
	ds_read_b128 v[192:195], v255 offset:38912
	ds_read_b128 v[132:135], v253 offset:2048
	ds_read_b128 v[136:139], v253 offset:4096
	ds_read_b128 v[140:143], v253 offset:6144
	s_waitcnt lgkmcnt(14)
	v_mfma_f32_16x16x32_bf16 v[60:63], v[80:83], v[144:147], v[60:63]
	s_waitcnt lgkmcnt(13)
	v_mfma_f32_16x16x32_bf16 v[56:59], v[80:83], v[148:151], v[56:59]
	s_waitcnt lgkmcnt(12)
	v_mfma_f32_16x16x32_bf16 v[52:55], v[80:83], v[152:155], v[52:55]
	s_waitcnt lgkmcnt(11)
	v_mfma_f32_16x16x32_bf16 v[48:51], v[80:83], v[156:159], v[48:51]
	s_waitcnt lgkmcnt(10)
	v_mfma_f32_16x16x32_bf16 v[44:47], v[84:87], v[144:147], v[44:47]
	v_mfma_f32_16x16x32_bf16 v[40:43], v[84:87], v[148:151], v[40:43]
	v_mfma_f32_16x16x32_bf16 v[36:39], v[84:87], v[152:155], v[36:39]
	v_mfma_f32_16x16x32_bf16 v[28:31], v[84:87], v[156:159], v[28:31]
	s_waitcnt lgkmcnt(0)
	s_barrier
	s_add_u32 m0, s7, 0x0
	v_mfma_f32_16x16x32_bf16 v[16:19], v[88:91], v[144:147], v[16:19]
	global_load_lds_dwordx4 v248, s[8:9]
	s_add_u32 m0, s7, 0x400
	v_mfma_f32_16x16x32_bf16 v[12:15], v[88:91], v[148:151], v[12:15]
	global_load_lds_dwordx4 v249, s[8:9]
	s_add_u32 m0, s7, 0x800
	v_mfma_f32_16x16x32_bf16 v[4:7], v[88:91], v[152:155], v[4:7]
	global_load_lds_dwordx4 v250, s[8:9]
	s_add_u32 m0, s7, 0xc00
	v_mfma_f32_16x16x32_bf16 v[8:11], v[88:91], v[156:159], v[8:11]
	global_load_lds_dwordx4 v251, s[8:9]
	s_add_u32 m0, s7, 0x8000
	v_mfma_f32_16x16x32_bf16 v[32:35], v[92:95], v[144:147], v[32:35]
	global_load_lds_dwordx4 v248, s[64:65] sc1
	s_add_u32 m0, s7, 0x8400
	v_mfma_f32_16x16x32_bf16 v[24:27], v[92:95], v[148:151], v[24:27]
	global_load_lds_dwordx4 v249, s[64:65] sc1
	s_add_u32 m0, s7, 0x8800
	v_mfma_f32_16x16x32_bf16 v[20:23], v[92:95], v[152:155], v[20:23]
	global_load_lds_dwordx4 v250, s[64:65] sc1
	s_add_u32 m0, s7, 0x8c00
	v_mfma_f32_16x16x32_bf16 v[0:3], v[92:95], v[156:159], v[0:3]
	global_load_lds_dwordx4 v251, s[64:65] sc1
	s_add_u32 s8, s8, 0x80
	s_addc_u32 s9, s9, 0
	s_add_u32 s64, s64, 0x80
	s_addc_u32 s65, s65, 0
	s_waitcnt vmcnt(8)
	s_barrier
	ds_read_b128 v[80:83], v252 offset:16384
	ds_read_b128 v[144:147], v254 offset:49152
	ds_read_b128 v[148:151], v254 offset:51200
	ds_read_b128 v[152:155], v254 offset:53248
	ds_read_b128 v[156:159], v254 offset:55296
	ds_read_b128 v[84:87], v252 offset:18432
	ds_read_b128 v[88:91], v252 offset:20480
	ds_read_b128 v[92:95], v252 offset:22528
	v_mfma_f32_16x16x32_bf16 v[60:63], v[124:127], v[180:183], v[60:63]
	v_mfma_f32_16x16x32_bf16 v[56:59], v[124:127], v[184:187], v[56:59]
	v_mfma_f32_16x16x32_bf16 v[52:55], v[124:127], v[188:191], v[52:55]
	v_mfma_f32_16x16x32_bf16 v[48:51], v[124:127], v[192:195], v[48:51]
	v_mfma_f32_16x16x32_bf16 v[44:47], v[132:135], v[180:183], v[44:47]
	v_mfma_f32_16x16x32_bf16 v[40:43], v[132:135], v[184:187], v[40:43]
	v_mfma_f32_16x16x32_bf16 v[36:39], v[132:135], v[188:191], v[36:39]
	v_mfma_f32_16x16x32_bf16 v[28:31], v[132:135], v[192:195], v[28:31]
	v_mfma_f32_16x16x32_bf16 v[16:19], v[136:139], v[180:183], v[16:19]
	v_mfma_f32_16x16x32_bf16 v[12:15], v[136:139], v[184:187], v[12:15]
	v_mfma_f32_16x16x32_bf16 v[4:7], v[136:139], v[188:191], v[4:7]
	v_mfma_f32_16x16x32_bf16 v[8:11], v[136:139], v[192:195], v[8:11]
	v_mfma_f32_16x16x32_bf16 v[32:35], v[140:143], v[180:183], v[32:35]
	v_mfma_f32_16x16x32_bf16 v[24:27], v[140:143], v[184:187], v[24:27]
	v_mfma_f32_16x16x32_bf16 v[20:23], v[140:143], v[188:191], v[20:23]
	v_mfma_f32_16x16x32_bf16 v[0:3], v[140:143], v[192:195], v[0:3]
	ds_read_b128 v[124:127], v253 offset:16384
	ds_read_b128 v[180:183], v255 offset:49152
	ds_read_b128 v[184:187], v255 offset:51200
	ds_read_b128 v[188:191], v255 offset:53248
	ds_read_b128 v[192:195], v255 offset:55296
	ds_read_b128 v[132:135], v253 offset:18432
	ds_read_b128 v[136:139], v253 offset:20480
	ds_read_b128 v[140:143], v253 offset:22528
	s_waitcnt lgkmcnt(14)
	v_mfma_f32_16x16x32_bf16 v[60:63], v[80:83], v[144:147], v[60:63]
	s_waitcnt lgkmcnt(13)
	v_mfma_f32_16x16x32_bf16 v[56:59], v[80:83], v[148:151], v[56:59]
	s_waitcnt lgkmcnt(12)
	v_mfma_f32_16x16x32_bf16 v[52:55], v[80:83], v[152:155], v[52:55]
	s_waitcnt lgkmcnt(11)
	v_mfma_f32_16x16x32_bf16 v[48:51], v[80:83], v[156:159], v[48:51]
	s_waitcnt lgkmcnt(10)
	v_mfma_f32_16x16x32_bf16 v[44:47], v[84:87], v[144:147], v[44:47]
	v_mfma_f32_16x16x32_bf16 v[40:43], v[84:87], v[148:151], v[40:43]
	v_mfma_f32_16x16x32_bf16 v[36:39], v[84:87], v[152:155], v[36:39]
	v_mfma_f32_16x16x32_bf16 v[28:31], v[84:87], v[156:159], v[28:31]
	s_waitcnt lgkmcnt(0)
	s_barrier
	s_add_u32 m0, s7, 0x4000
	v_mfma_f32_16x16x32_bf16 v[16:19], v[88:91], v[144:147], v[16:19]
	global_load_lds_dwordx4 v248, s[8:9]
	s_add_u32 m0, s7, 0x4400
	v_mfma_f32_16x16x32_bf16 v[12:15], v[88:91], v[148:151], v[12:15]
	global_load_lds_dwordx4 v249, s[8:9]
	s_add_u32 m0, s7, 0x4800
	v_mfma_f32_16x16x32_bf16 v[4:7], v[88:91], v[152:155], v[4:7]
	global_load_lds_dwordx4 v250, s[8:9]
	s_add_u32 m0, s7, 0x4c00
	v_mfma_f32_16x16x32_bf16 v[8:11], v[88:91], v[156:159], v[8:11]
	global_load_lds_dwordx4 v251, s[8:9]
	s_add_u32 m0, s7, 0xc000
	v_mfma_f32_16x16x32_bf16 v[32:35], v[92:95], v[144:147], v[32:35]
	global_load_lds_dwordx4 v248, s[64:65] sc1
	s_add_u32 m0, s7, 0xc400
	v_mfma_f32_16x16x32_bf16 v[24:27], v[92:95], v[148:151], v[24:27]
	global_load_lds_dwordx4 v249, s[64:65] sc1
	s_add_u32 m0, s7, 0xc800
	v_mfma_f32_16x16x32_bf16 v[20:23], v[92:95], v[152:155], v[20:23]
	global_load_lds_dwordx4 v250, s[64:65] sc1
	s_add_u32 m0, s7, 0xcc00
	v_mfma_f32_16x16x32_bf16 v[0:3], v[92:95], v[156:159], v[0:3]
	global_load_lds_dwordx4 v251, s[64:65] sc1
	s_add_u32 s8, s8, 0x80
	s_addc_u32 s9, s9, 0
	s_add_u32 s64, s64, 0x80
	s_addc_u32 s65, s65, 0
	s_sub_u32 s32, s32, 1
	s_cmp_lg_u32 s32, 0
	s_cbranch_scc1 .Lg18_loop
	s_waitcnt vmcnt(8)
	s_barrier
	ds_read_b128 v[80:83], v252 offset:0
	ds_read_b128 v[144:147], v254 offset:32768
	ds_read_b128 v[148:151], v254 offset:34816
	ds_read_b128 v[152:155], v254 offset:36864
	ds_read_b128 v[156:159], v254 offset:38912
	ds_read_b128 v[84:87], v252 offset:2048
	ds_read_b128 v[88:91], v252 offset:4096
	ds_read_b128 v[92:95], v252 offset:6144
	v_mfma_f32_16x16x32_bf16 v[60:63], v[124:127], v[180:183], v[60:63]
	v_mfma_f32_16x16x32_bf16 v[56:59], v[124:127], v[184:187], v[56:59]
	v_mfma_f32_16x16x32_bf16 v[52:55], v[124:127], v[188:191], v[52:55]
	v_mfma_f32_16x16x32_bf16 v[48:51], v[124:127], v[192:195], v[48:51]
	v_mfma_f32_16x16x32_bf16 v[44:47], v[132:135], v[180:183], v[44:47]
	v_mfma_f32_16x16x32_bf16 v[40:43], v[132:135], v[184:187], v[40:43]
	v_mfma_f32_16x16x32_bf16 v[36:39], v[132:135], v[188:191], v[36:39]
	v_mfma_f32_16x16x32_bf16 v[28:31], v[132:135], v[192:195], v[28:31]
	v_mfma_f32_16x16x32_bf16 v[16:19], v[136:139], v[180:183], v[16:19]
	v_mfma_f32_16x16x32_bf16 v[12:15], v[136:139], v[184:187], v[12:15]
	v_mfma_f32_16x16x32_bf16 v[4:7], v[136:139], v[188:191], v[4:7]
	v_mfma_f32_16x16x32_bf16 v[8:11], v[136:139], v[192:195], v[8:11]
	v_mfma_f32_16x16x32_bf16 v[32:35], v[140:143], v[180:183], v[32:35]
	v_mfma_f32_16x16x32_bf16 v[24:27], v[140:143], v[184:187], v[24:27]
	v_mfma_f32_16x16x32_bf16 v[20:23], v[140:143], v[188:191], v[20:23]
	v_mfma_f32_16x16x32_bf16 v[0:3], v[140:143], v[192:195], v[0:3]
	ds_read_b128 v[124:127], v253 offset:0
	ds_read_b128 v[180:183], v255 offset:32768
	ds_read_b128 v[184:187], v255 offset:34816
	ds_read_b128 v[188:191], v255 offset:36864
	ds_read_b128 v[192:195], v255 offset:38912
	ds_read_b128 v[132:135], v253 offset:2048
	ds_read_b128 v[136:139], v253 offset:4096
	ds_read_b128 v[140:143], v253 offset:6144
	s_waitcnt lgkmcnt(14)
	v_mfma_f32_16x16x32_bf16 v[60:63], v[80:83], v[144:147], v[60:63]
	s_waitcnt lgkmcnt(13)
	v_mfma_f32_16x16x32_bf16 v[56:59], v[80:83], v[148:151], v[56:59]
	s_waitcnt lgkmcnt(12)
	v_mfma_f32_16x16x32_bf16 v[52:55], v[80:83], v[152:155], v[52:55]
	s_waitcnt lgkmcnt(11)
	v_mfma_f32_16x16x32_bf16 v[48:51], v[80:83], v[156:159], v[48:51]
	s_waitcnt lgkmcnt(10)
	v_mfma_f32_16x16x32_bf16 v[44:47], v[84:87], v[144:147], v[44:47]
	v_mfma_f32_16x16x32_bf16 v[40:43], v[84:87], v[148:151], v[40:43]
	v_mfma_f32_16x16x32_bf16 v[36:39], v[84:87], v[152:155], v[36:39]
	v_mfma_f32_16x16x32_bf16 v[28:31], v[84:87], v[156:159], v[28:31]
	s_waitcnt lgkmcnt(0)
	s_barrier
	v_mfma_f32_16x16x32_bf16 v[16:19], v[88:91], v[144:147], v[16:19]
	v_mfma_f32_16x16x32_bf16 v[12:15], v[88:91], v[148:151], v[12:15]
	v_mfma_f32_16x16x32_bf16 v[4:7], v[88:91], v[152:155], v[4:7]
	v_mfma_f32_16x16x32_bf16 v[8:11], v[88:91], v[156:159], v[8:11]
	v_mfma_f32_16x16x32_bf16 v[32:35], v[92:95], v[144:147], v[32:35]
	v_mfma_f32_16x16x32_bf16 v[24:27], v[92:95], v[148:151], v[24:27]
	v_mfma_f32_16x16x32_bf16 v[20:23], v[92:95], v[152:155], v[20:23]
	v_mfma_f32_16x16x32_bf16 v[0:3], v[92:95], v[156:159], v[0:3]
	s_waitcnt vmcnt(0)
	s_barrier
	ds_read_b128 v[80:83], v252 offset:16384
	ds_read_b128 v[144:147], v254 offset:49152
	ds_read_b128 v[148:151], v254 offset:51200
	ds_read_b128 v[152:155], v254 offset:53248
	ds_read_b128 v[156:159], v254 offset:55296
	ds_read_b128 v[84:87], v252 offset:18432
	ds_read_b128 v[88:91], v252 offset:20480
	ds_read_b128 v[92:95], v252 offset:22528
	v_mfma_f32_16x16x32_bf16 v[60:63], v[124:127], v[180:183], v[60:63]
	v_mfma_f32_16x16x32_bf16 v[56:59], v[124:127], v[184:187], v[56:59]
	v_mfma_f32_16x16x32_bf16 v[52:55], v[124:127], v[188:191], v[52:55]
	v_mfma_f32_16x16x32_bf16 v[48:51], v[124:127], v[192:195], v[48:51]
	v_mfma_f32_16x16x32_bf16 v[44:47], v[132:135], v[180:183], v[44:47]
	v_mfma_f32_16x16x32_bf16 v[40:43], v[132:135], v[184:187], v[40:43]
	v_mfma_f32_16x16x32_bf16 v[36:39], v[132:135], v[188:191], v[36:39]
	v_mfma_f32_16x16x32_bf16 v[28:31], v[132:135], v[192:195], v[28:31]
	v_mfma_f32_16x16x32_bf16 v[16:19], v[136:139], v[180:183], v[16:19]
	v_mfma_f32_16x16x32_bf16 v[12:15], v[136:139], v[184:187], v[12:15]
	v_mfma_f32_16x16x32_bf16 v[4:7], v[136:139], v[188:191], v[4:7]
	v_mfma_f32_16x16x32_bf16 v[8:11], v[136:139], v[192:195], v[8:11]
	v_mfma_f32_16x16x32_bf16 v[32:35], v[140:143], v[180:183], v[32:35]
	v_mfma_f32_16x16x32_bf16 v[24:27], v[140:143], v[184:187], v[24:27]
	v_mfma_f32_16x16x32_bf16 v[20:23], v[140:143], v[188:191], v[20:23]
	v_mfma_f32_16x16x32_bf16 v[0:3], v[140:143], v[192:195], v[0:3]
	ds_read_b128 v[124:127], v253 offset:16384
	ds_read_b128 v[180:183], v255 offset:49152
	ds_read_b128 v[184:187], v255 offset:51200
	ds_read_b128 v[188:191], v255 offset:53248
	ds_read_b128 v[192:195], v255 offset:55296
	ds_read_b128 v[132:135], v253 offset:18432
	ds_read_b128 v[136:139], v253 offset:20480
	ds_read_b128 v[140:143], v253 offset:22528
	s_waitcnt lgkmcnt(14)
	v_mfma_f32_16x16x32_bf16 v[60:63], v[80:83], v[144:147], v[60:63]
	s_waitcnt lgkmcnt(13)
	v_mfma_f32_16x16x32_bf16 v[56:59], v[80:83], v[148:151], v[56:59]
	s_waitcnt lgkmcnt(12)
	v_mfma_f32_16x16x32_bf16 v[52:55], v[80:83], v[152:155], v[52:55]
	s_waitcnt lgkmcnt(11)
	v_mfma_f32_16x16x32_bf16 v[48:51], v[80:83], v[156:159], v[48:51]
	s_waitcnt lgkmcnt(10)
	v_mfma_f32_16x16x32_bf16 v[44:47], v[84:87], v[144:147], v[44:47]
	v_mfma_f32_16x16x32_bf16 v[40:43], v[84:87], v[148:151], v[40:43]
	v_mfma_f32_16x16x32_bf16 v[36:39], v[84:87], v[152:155], v[36:39]
	v_mfma_f32_16x16x32_bf16 v[28:31], v[84:87], v[156:159], v[28:31]
	s_waitcnt lgkmcnt(0)
	s_barrier
	v_mfma_f32_16x16x32_bf16 v[16:19], v[88:91], v[144:147], v[16:19]
	v_mfma_f32_16x16x32_bf16 v[12:15], v[88:91], v[148:151], v[12:15]
	v_mfma_f32_16x16x32_bf16 v[4:7], v[88:91], v[152:155], v[4:7]
	v_mfma_f32_16x16x32_bf16 v[8:11], v[88:91], v[156:159], v[8:11]
	v_mfma_f32_16x16x32_bf16 v[32:35], v[92:95], v[144:147], v[32:35]
	v_mfma_f32_16x16x32_bf16 v[24:27], v[92:95], v[148:151], v[24:27]
	v_mfma_f32_16x16x32_bf16 v[20:23], v[92:95], v[152:155], v[20:23]
	v_mfma_f32_16x16x32_bf16 v[0:3], v[92:95], v[156:159], v[0:3]
	v_mfma_f32_16x16x32_bf16 v[60:63], v[124:127], v[180:183], v[60:63]
	v_mfma_f32_16x16x32_bf16 v[56:59], v[124:127], v[184:187], v[56:59]
	v_mfma_f32_16x16x32_bf16 v[52:55], v[124:127], v[188:191], v[52:55]
	v_mfma_f32_16x16x32_bf16 v[48:51], v[124:127], v[192:195], v[48:51]
	v_mfma_f32_16x16x32_bf16 v[44:47], v[132:135], v[180:183], v[44:47]
	v_mfma_f32_16x16x32_bf16 v[40:43], v[132:135], v[184:187], v[40:43]
	v_mfma_f32_16x16x32_bf16 v[36:39], v[132:135], v[188:191], v[36:39]
	v_mfma_f32_16x16x32_bf16 v[28:31], v[132:135], v[192:195], v[28:31]
	v_mfma_f32_16x16x32_bf16 v[16:19], v[136:139], v[180:183], v[16:19]
	v_mfma_f32_16x16x32_bf16 v[12:15], v[136:139], v[184:187], v[12:15]
	v_mfma_f32_16x16x32_bf16 v[4:7], v[136:139], v[188:191], v[4:7]
	v_mfma_f32_16x16x32_bf16 v[8:11], v[136:139], v[192:195], v[8:11]
	v_mfma_f32_16x16x32_bf16 v[32:35], v[140:143], v[180:183], v[32:35]
	v_mfma_f32_16x16x32_bf16 v[24:27], v[140:143], v[184:187], v[24:27]
	v_mfma_f32_16x16x32_bf16 v[20:23], v[140:143], v[188:191], v[20:23]
	v_mfma_f32_16x16x32_bf16 v[0:3], v[140:143], v[192:195], v[0:3]
	s_nop 7
	s_nop 1
	v_add_u32_e32 v80, s12, v174
	v_or_b32_e32 v64, s6, v175
	s_cmpk_gt_i32 s6, 0x3ff
	s_mov_b64 s[6:7], -1
	s_cbranch_scc0 .LBB0_1789
	s_cmpk_gt_u32 s13, 0xbff
	s_cbranch_scc0 .LBB0_1786
	s_cmpk_gt_u32 s13, 0x13ff
	s_cbranch_scc0 .LBB0_1609
	s_cmpk_gt_u32 s13, 0x17ff
	s_cbranch_scc0 .LBB0_1590
	s_and_saveexec_b64 s[6:7], s[4:5]
	s_cbranch_execz .LBB0_1589
	v_lshlrev_b32_e32 v98, 7, v80
	v_lshl_add_u64 v[66:67], v[104:105], 0, v[98:99]
	global_store_dword v[66:67], v60, off
	global_store_dword v[66:67], v61, off offset:128
	global_store_dword v[66:67], v62, off offset:256
	global_store_dword v[66:67], v63, off offset:384
	global_store_dword v[66:67], v56, off offset:64
	global_store_dword v[66:67], v57, off offset:192
	global_store_dword v[66:67], v58, off offset:320
	global_store_dword v[66:67], v59, off offset:448
	global_store_dword v[66:67], v44, off offset:2048
	global_store_dword v[66:67], v45, off offset:2176
	global_store_dword v[66:67], v46, off offset:2304
	global_store_dword v[66:67], v47, off offset:2432
	global_store_dword v[66:67], v40, off offset:2112
	global_store_dword v[66:67], v41, off offset:2240
	global_store_dword v[66:67], v42, off offset:2368
	global_store_dword v[66:67], v43, off offset:2496
	v_or_b32_e32 v66, 0x1000, v98
	v_mov_b32_e32 v67, v99
	v_lshl_add_u64 v[68:69], v[104:105], 0, v[66:67]
	global_store_dword v[68:69], v16, off
	v_or_b32_e32 v68, 0x1080, v98
	v_mov_b32_e32 v69, v99
	v_lshl_add_u64 v[70:71], v[104:105], 0, v[68:69]
	global_store_dword v[70:71], v17, off
	v_or_b32_e32 v70, 0x1100, v98
	v_mov_b32_e32 v71, v99
	v_lshl_add_u64 v[66:67], v[106:107], 0, v[66:67]
	v_lshl_add_u64 v[72:73], v[104:105], 0, v[70:71]
	global_store_dword v[66:67], v12, off
	v_lshl_add_u64 v[66:67], v[106:107], 0, v[68:69]
	global_store_dword v[72:73], v18, off
	v_or_b32_e32 v72, 0x1180, v98
	v_mov_b32_e32 v73, v99
	global_store_dword v[66:67], v13, off
	v_lshl_add_u64 v[66:67], v[106:107], 0, v[70:71]
	global_store_dword v[66:67], v14, off
	v_lshl_add_u64 v[66:67], v[106:107], 0, v[72:73]
	global_store_dword v[66:67], v15, off
	v_or_b32_e32 v66, 0x1800, v98
	v_mov_b32_e32 v67, v99
	v_lshl_add_u64 v[68:69], v[104:105], 0, v[66:67]
	global_store_dword v[68:69], v32, off
	v_or_b32_e32 v68, 0x1880, v98
	v_mov_b32_e32 v69, v99
	v_lshl_add_u64 v[70:71], v[104:105], 0, v[68:69]
	v_lshl_add_u64 v[66:67], v[106:107], 0, v[66:67]
	global_store_dword v[70:71], v33, off
	v_or_b32_e32 v70, 0x1900, v98
	v_mov_b32_e32 v71, v99
	global_store_dword v[66:67], v24, off
	v_lshl_add_u64 v[66:67], v[106:107], 0, v[68:69]
	v_lshl_add_u64 v[74:75], v[104:105], 0, v[72:73]
	v_lshl_add_u64 v[72:73], v[104:105], 0, v[70:71]
	v_or_b32_e32 v98, 0x1980, v98
	global_store_dword v[66:67], v25, off
	v_lshl_add_u64 v[66:67], v[106:107], 0, v[70:71]
	global_store_dword v[72:73], v34, off
	v_lshl_add_u64 v[72:73], v[104:105], 0, v[98:99]
	global_store_dword v[66:67], v26, off
	v_lshl_add_u64 v[66:67], v[106:107], 0, v[98:99]
	global_store_dword v[74:75], v19, off
	global_store_dword v[72:73], v35, off
	global_store_dword v[66:67], v27, off

.Lr22_tile:
	s_cmp_lt_u32 s15, 0x200
	s_cbranch_scc0 .Lr22_end
	s_and_b32 s2, s15, 63
	s_lshr_b32 s3, s15, 6
	s_mul_i32 s14, s2, 0x80000
	s_add_u32 s8, s26, s14
	s_addc_u32 s9, s27, 0
	s_mul_i32 s14, s3, 0x80000
	s_add_u32 s10, s28, s14
	s_addc_u32 s11, s29, 0
	s_lshl_b32 s14, s2, 19
	s_lshl_b32 s6, s3, 9
	s_add_u32 s14, s14, s6
	s_add_u32 s20, s4, 0x6b7a100
	s_addc_u32 s21, s5, 0
	s_add_u32 s20, s20, s14
	s_addc_u32 s21, s21, 0
	s_sub_u32 s7, s2, 32
	s_lshr_b32 s7, s7, 3
	s_add_u32 s7, s7, 1
	s_cmp_lt_u32 s2, 32
	s_cselect_b32 s7, 0, s7
	s_mul_i32 s7, s7, 0x6000
	s_add_u32 s7, s7, s6
	s_add_u32 s22, s4, 0x6b40000
	s_addc_u32 s23, s5, 0
	s_add_u32 s22, s22, s7
	s_addc_u32 s23, s23, 0
	v_readfirstlane_b32 s12, v247
	s_lshl_b32 s12, s12, 12
	s_add_u32 m0, s12, 0x0
	v_mov_b32_e32 v0, 0
	global_load_lds_dwordx4 v248, s[8:9]
	v_mov_b32_e32 v1, 0
	s_add_u32 m0, s12, 0x400
	v_mov_b32_e32 v2, 0
	global_load_lds_dwordx4 v249, s[8:9]
	v_mov_b32_e32 v3, 0
	s_add_u32 m0, s12, 0x800
	v_mov_b32_e32 v4, 0
	global_load_lds_dwordx4 v250, s[8:9]
	v_mov_b32_e32 v5, 0
	s_add_u32 m0, s12, 0xc00
	v_mov_b32_e32 v6, 0
	global_load_lds_dwordx4 v251, s[8:9]
	v_mov_b32_e32 v7, 0
	s_add_u32 m0, s12, 0x8000
	v_mov_b32_e32 v8, 0
	global_load_lds_dwordx4 v248, s[10:11] sc1
	v_mov_b32_e32 v9, 0
	s_add_u32 m0, s12, 0x8400
	v_mov_b32_e32 v10, 0
	global_load_lds_dwordx4 v249, s[10:11] sc1
	v_mov_b32_e32 v11, 0
	s_add_u32 m0, s12, 0x8800
	v_mov_b32_e32 v12, 0
	global_load_lds_dwordx4 v250, s[10:11] sc1
	v_mov_b32_e32 v13, 0
	s_add_u32 m0, s12, 0x8c00
	v_mov_b32_e32 v14, 0
	global_load_lds_dwordx4 v251, s[10:11] sc1
	v_mov_b32_e32 v15, 0
	s_add_u32 s8, s8, 0x80
	s_addc_u32 s9, s9, 0
	s_add_u32 s10, s10, 0x80
	s_addc_u32 s11, s11, 0
	s_add_u32 m0, s12, 0x4000
	v_mov_b32_e32 v16, 0
	global_load_lds_dwordx4 v248, s[8:9]
	v_mov_b32_e32 v17, 0
	s_add_u32 m0, s12, 0x4400
	v_mov_b32_e32 v18, 0
	global_load_lds_dwordx4 v249, s[8:9]
	v_mov_b32_e32 v19, 0
	s_add_u32 m0, s12, 0x4800
	v_mov_b32_e32 v20, 0
	global_load_lds_dwordx4 v250, s[8:9]
	v_mov_b32_e32 v21, 0
	s_add_u32 m0, s12, 0x4c00
	v_mov_b32_e32 v22, 0
	global_load_lds_dwordx4 v251, s[8:9]
	v_mov_b32_e32 v23, 0
	s_add_u32 m0, s12, 0xc000
	v_mov_b32_e32 v24, 0
	global_load_lds_dwordx4 v248, s[10:11] sc1
	v_mov_b32_e32 v25, 0
	s_add_u32 m0, s12, 0xc400
	v_mov_b32_e32 v26, 0
	global_load_lds_dwordx4 v249, s[10:11] sc1
	v_mov_b32_e32 v27, 0
	s_add_u32 m0, s12, 0xc800
	v_mov_b32_e32 v28, 0
	global_load_lds_dwordx4 v250, s[10:11] sc1
	v_mov_b32_e32 v29, 0
	s_add_u32 m0, s12, 0xcc00
	v_mov_b32_e32 v30, 0
	global_load_lds_dwordx4 v251, s[10:11] sc1
	v_mov_b32_e32 v31, 0
	s_add_u32 s8, s8, 0x80
	s_addc_u32 s9, s9, 0
	s_add_u32 s10, s10, 0x80
	s_addc_u32 s11, s11, 0
	v_mov_b32_e32 v32, 0
	v_mov_b32_e32 v33, 0
	v_mov_b32_e32 v34, 0
	v_mov_b32_e32 v35, 0
	v_mov_b32_e32 v36, 0
	v_mov_b32_e32 v37, 0
	v_mov_b32_e32 v38, 0
	v_mov_b32_e32 v39, 0
	v_mov_b32_e32 v40, 0
	v_mov_b32_e32 v41, 0
	v_mov_b32_e32 v42, 0
	v_mov_b32_e32 v43, 0
	v_mov_b32_e32 v44, 0
	v_mov_b32_e32 v45, 0
	v_mov_b32_e32 v46, 0
	v_mov_b32_e32 v47, 0
	v_mov_b32_e32 v48, 0
	v_mov_b32_e32 v49, 0
	v_mov_b32_e32 v50, 0
	v_mov_b32_e32 v51, 0
	v_mov_b32_e32 v52, 0
	v_mov_b32_e32 v53, 0
	v_mov_b32_e32 v54, 0
	v_mov_b32_e32 v55, 0
	v_mov_b32_e32 v56, 0
	v_mov_b32_e32 v57, 0
	v_mov_b32_e32 v58, 0
	v_mov_b32_e32 v59, 0
	v_mov_b32_e32 v60, 0
	v_mov_b32_e32 v61, 0
	v_mov_b32_e32 v62, 0
	v_mov_b32_e32 v63, 0
	global_load_dword v201, v245, s[22:23] offset:0
	global_load_dword v202, v245, s[22:23] offset:64
	global_load_dword v203, v245, s[22:23] offset:128
	global_load_dword v204, v245, s[22:23] offset:192
	s_mov_b64 s[18:19], s[20:21]
	global_load_dword v129, v246, s[18:19] offset:0
	global_load_dword v130, v246, s[18:19] offset:64
	global_load_dword v131, v246, s[18:19] offset:128
	global_load_dword v132, v246, s[18:19] offset:192
	s_add_u32 s18, s18, 0x1000
	s_addc_u32 s19, s19, 0
	global_load_dword v133, v246, s[18:19] offset:0
	global_load_dword v134, v246, s[18:19] offset:64
	global_load_dword v135, v246, s[18:19] offset:128
	global_load_dword v136, v246, s[18:19] offset:192
	s_add_u32 s18, s18, 0x1000
	s_addc_u32 s19, s19, 0
	global_load_dword v137, v246, s[18:19] offset:0
	global_load_dword v138, v246, s[18:19] offset:64
	global_load_dword v139, v246, s[18:19] offset:128
	global_load_dword v140, v246, s[18:19] offset:192
	s_add_u32 s18, s18, 0x1000
	s_addc_u32 s19, s19, 0
	global_load_dword v141, v246, s[18:19] offset:0
	global_load_dword v142, v246, s[18:19] offset:64
	global_load_dword v143, v246, s[18:19] offset:128
	global_load_dword v144, v246, s[18:19] offset:192
	s_add_u32 s18, s18, 0xd000
	s_addc_u32 s19, s19, 0
	global_load_dword v145, v246, s[18:19] offset:0
	global_load_dword v146, v246, s[18:19] offset:64
	global_load_dword v147, v246, s[18:19] offset:128
	global_load_dword v148, v246, s[18:19] offset:192
	s_add_u32 s18, s18, 0x1000
	s_addc_u32 s19, s19, 0
	global_load_dword v149, v246, s[18:19] offset:0
	global_load_dword v150, v246, s[18:19] offset:64
	global_load_dword v151, v246, s[18:19] offset:128
	global_load_dword v152, v246, s[18:19] offset:192
	s_add_u32 s18, s18, 0x1000
	s_addc_u32 s19, s19, 0
	global_load_dword v153, v246, s[18:19] offset:0
	global_load_dword v154, v246, s[18:19] offset:64
	global_load_dword v155, v246, s[18:19] offset:128
	global_load_dword v156, v246, s[18:19] offset:192
	s_add_u32 s18, s18, 0x1000
	s_addc_u32 s19, s19, 0
	global_load_dword v157, v246, s[18:19] offset:0
	global_load_dword v158, v246, s[18:19] offset:64
	global_load_dword v159, v246, s[18:19] offset:128
	global_load_dword v160, v246, s[18:19] offset:192
	s_add_u32 s18, s18, 0xd000
	s_addc_u32 s19, s19, 0
	global_load_dword v161, v246, s[18:19] offset:0
	global_load_dword v170, v246, s[18:19] offset:64
	global_load_dword v171, v246, s[18:19] offset:128
	global_load_dword v172, v246, s[18:19] offset:192
	s_add_u32 s18, s18, 0x1000
	s_addc_u32 s19, s19, 0
	global_load_dword v173, v246, s[18:19] offset:0
	global_load_dword v174, v246, s[18:19] offset:64
	global_load_dword v175, v246, s[18:19] offset:128
	global_load_dword v176, v246, s[18:19] offset:192
	s_add_u32 s18, s18, 0x1000
	s_addc_u32 s19, s19, 0
	global_load_dword v177, v246, s[18:19] offset:0
	global_load_dword v178, v246, s[18:19] offset:64
	global_load_dword v179, v246, s[18:19] offset:128
	global_load_dword v180, v246, s[18:19] offset:192
	s_add_u32 s18, s18, 0x1000
	s_addc_u32 s19, s19, 0
	global_load_dword v181, v246, s[18:19] offset:0
	global_load_dword v182, v246, s[18:19] offset:64
	global_load_dword v183, v246, s[18:19] offset:128
	global_load_dword v184, v246, s[18:19] offset:192
	s_add_u32 s18, s18, 0xd000
	s_addc_u32 s19, s19, 0
	global_load_dword v185, v246, s[18:19] offset:0
	global_load_dword v186, v246, s[18:19] offset:64
	global_load_dword v187, v246, s[18:19] offset:128
	global_load_dword v188, v246, s[18:19] offset:192
	s_add_u32 s18, s18, 0x1000
	s_addc_u32 s19, s19, 0
	global_load_dword v189, v246, s[18:19] offset:0
	global_load_dword v190, v246, s[18:19] offset:64
	global_load_dword v191, v246, s[18:19] offset:128
	global_load_dword v192, v246, s[18:19] offset:192
	s_add_u32 s18, s18, 0x1000
	s_addc_u32 s19, s19, 0
	global_load_dword v193, v246, s[18:19] offset:0
	global_load_dword v194, v246, s[18:19] offset:64
	global_load_dword v195, v246, s[18:19] offset:128
	global_load_dword v196, v246, s[18:19] offset:192
	s_add_u32 s18, s18, 0x1000
	s_addc_u32 s19, s19, 0
	global_load_dword v197, v246, s[18:19] offset:0
	global_load_dword v198, v246, s[18:19] offset:64
	global_load_dword v199, v246, s[18:19] offset:128
	global_load_dword v200, v246, s[18:19] offset:192
	s_waitcnt vmcnt(63)
	s_barrier
	ds_read_b128 v[64:67], v252 offset:0
	ds_read_b128 v[96:99], v254 offset:32768
	ds_read_b128 v[100:103], v254 offset:34816
	ds_read_b128 v[104:107], v254 offset:36864
	ds_read_b128 v[108:111], v254 offset:38912
	ds_read_b128 v[68:71], v252 offset:2048
	ds_read_b128 v[72:75], v252 offset:4096
	ds_read_b128 v[76:79], v252 offset:6144
	ds_read_b128 v[80:83], v253 offset:0
	ds_read_b128 v[112:115], v255 offset:32768
	ds_read_b128 v[116:119], v255 offset:34816
	ds_read_b128 v[120:123], v255 offset:36864
	ds_read_b128 v[124:127], v255 offset:38912
	s_waitcnt lgkmcnt(11)
	v_mfma_f32_16x16x32_bf16 v[0:3], v[64:67], v[96:99], v[0:3]
	s_waitcnt lgkmcnt(10)
	v_mfma_f32_16x16x32_bf16 v[4:7], v[64:67], v[100:103], v[4:7]
	s_waitcnt lgkmcnt(9)
	v_mfma_f32_16x16x32_bf16 v[8:11], v[64:67], v[104:107], v[8:11]
	s_waitcnt lgkmcnt(8)
	v_mfma_f32_16x16x32_bf16 v[12:15], v[64:67], v[108:111], v[12:15]
	ds_read_b128 v[84:87], v253 offset:2048
	ds_read_b128 v[88:91], v253 offset:4096
	ds_read_b128 v[92:95], v253 offset:6144
	s_waitcnt lgkmcnt(10)
	v_mfma_f32_16x16x32_bf16 v[16:19], v[68:71], v[96:99], v[16:19]
	v_mfma_f32_16x16x32_bf16 v[20:23], v[68:71], v[100:103], v[20:23]
	v_mfma_f32_16x16x32_bf16 v[24:27], v[68:71], v[104:107], v[24:27]
	v_mfma_f32_16x16x32_bf16 v[28:31], v[68:71], v[108:111], v[28:31]
	s_waitcnt lgkmcnt(0)
	s_barrier
	s_add_u32 m0, s12, 0x0
	v_mfma_f32_16x16x32_bf16 v[32:35], v[72:75], v[96:99], v[32:35]
	global_load_lds_dwordx4 v248, s[8:9]
	s_add_u32 m0, s12, 0x400
	v_mfma_f32_16x16x32_bf16 v[36:39], v[72:75], v[100:103], v[36:39]
	global_load_lds_dwordx4 v249, s[8:9]
	s_add_u32 m0, s12, 0x800
	v_mfma_f32_16x16x32_bf16 v[40:43], v[72:75], v[104:107], v[40:43]
	global_load_lds_dwordx4 v250, s[8:9]
	s_add_u32 m0, s12, 0xc00
	v_mfma_f32_16x16x32_bf16 v[44:47], v[72:75], v[108:111], v[44:47]
	global_load_lds_dwordx4 v251, s[8:9]
	s_add_u32 m0, s12, 0x8000
	v_mfma_f32_16x16x32_bf16 v[48:51], v[76:79], v[96:99], v[48:51]
	global_load_lds_dwordx4 v248, s[10:11] sc1
	s_add_u32 m0, s12, 0x8400
	v_mfma_f32_16x16x32_bf16 v[52:55], v[76:79], v[100:103], v[52:55]
	global_load_lds_dwordx4 v249, s[10:11] sc1
	s_add_u32 m0, s12, 0x8800
	v_mfma_f32_16x16x32_bf16 v[56:59], v[76:79], v[104:107], v[56:59]
	global_load_lds_dwordx4 v250, s[10:11] sc1
	s_add_u32 m0, s12, 0x8c00
	v_mfma_f32_16x16x32_bf16 v[60:63], v[76:79], v[108:111], v[60:63]
	global_load_lds_dwordx4 v251, s[10:11] sc1
	s_add_u32 s8, s8, 0x80
	s_addc_u32 s9, s9, 0
	s_add_u32 s10, s10, 0x80
	s_addc_u32 s11, s11, 0
	s_waitcnt vmcnt(63)
	s_barrier
	ds_read_b128 v[64:67], v252 offset:16384
	ds_read_b128 v[96:99], v254 offset:49152
	ds_read_b128 v[100:103], v254 offset:51200
	ds_read_b128 v[104:107], v254 offset:53248
	ds_read_b128 v[108:111], v254 offset:55296
	ds_read_b128 v[68:71], v252 offset:18432
	ds_read_b128 v[72:75], v252 offset:20480
	ds_read_b128 v[76:79], v252 offset:22528
	v_mfma_f32_16x16x32_bf16 v[0:3], v[80:83], v[112:115], v[0:3]
	v_mfma_f32_16x16x32_bf16 v[4:7], v[80:83], v[116:119], v[4:7]
	v_mfma_f32_16x16x32_bf16 v[8:11], v[80:83], v[120:123], v[8:11]
	v_mfma_f32_16x16x32_bf16 v[12:15], v[80:83], v[124:127], v[12:15]
	v_mfma_f32_16x16x32_bf16 v[16:19], v[84:87], v[112:115], v[16:19]
	v_mfma_f32_16x16x32_bf16 v[20:23], v[84:87], v[116:119], v[20:23]
	v_mfma_f32_16x16x32_bf16 v[24:27], v[84:87], v[120:123], v[24:27]
	v_mfma_f32_16x16x32_bf16 v[28:31], v[84:87], v[124:127], v[28:31]
	v_mfma_f32_16x16x32_bf16 v[32:35], v[88:91], v[112:115], v[32:35]
	v_mfma_f32_16x16x32_bf16 v[36:39], v[88:91], v[116:119], v[36:39]
	v_mfma_f32_16x16x32_bf16 v[40:43], v[88:91], v[120:123], v[40:43]
	v_mfma_f32_16x16x32_bf16 v[44:47], v[88:91], v[124:127], v[44:47]
	v_mfma_f32_16x16x32_bf16 v[48:51], v[92:95], v[112:115], v[48:51]
	v_mfma_f32_16x16x32_bf16 v[52:55], v[92:95], v[116:119], v[52:55]
	v_mfma_f32_16x16x32_bf16 v[56:59], v[92:95], v[120:123], v[56:59]
	v_mfma_f32_16x16x32_bf16 v[60:63], v[92:95], v[124:127], v[60:63]
	ds_read_b128 v[80:83], v253 offset:16384
	ds_read_b128 v[112:115], v255 offset:49152
	ds_read_b128 v[116:119], v255 offset:51200
	ds_read_b128 v[120:123], v255 offset:53248
	ds_read_b128 v[124:127], v255 offset:55296
	ds_read_b128 v[84:87], v253 offset:18432
	ds_read_b128 v[88:91], v253 offset:20480
	ds_read_b128 v[92:95], v253 offset:22528
	s_waitcnt lgkmcnt(14)
	v_mfma_f32_16x16x32_bf16 v[0:3], v[64:67], v[96:99], v[0:3]
	s_waitcnt lgkmcnt(13)
	v_mfma_f32_16x16x32_bf16 v[4:7], v[64:67], v[100:103], v[4:7]
	s_waitcnt lgkmcnt(12)
	v_mfma_f32_16x16x32_bf16 v[8:11], v[64:67], v[104:107], v[8:11]
	s_waitcnt lgkmcnt(11)
	v_mfma_f32_16x16x32_bf16 v[12:15], v[64:67], v[108:111], v[12:15]
	s_waitcnt lgkmcnt(10)
	v_mfma_f32_16x16x32_bf16 v[16:19], v[68:71], v[96:99], v[16:19]
	v_mfma_f32_16x16x32_bf16 v[20:23], v[68:71], v[100:103], v[20:23]
	v_mfma_f32_16x16x32_bf16 v[24:27], v[68:71], v[104:107], v[24:27]
	v_mfma_f32_16x16x32_bf16 v[28:31], v[68:71], v[108:111], v[28:31]
	s_waitcnt lgkmcnt(0)
	s_barrier
	s_add_u32 m0, s12, 0x4000
	v_mfma_f32_16x16x32_bf16 v[32:35], v[72:75], v[96:99], v[32:35]
	global_load_lds_dwordx4 v248, s[8:9]
	s_add_u32 m0, s12, 0x4400
	v_mfma_f32_16x16x32_bf16 v[36:39], v[72:75], v[100:103], v[36:39]
	global_load_lds_dwordx4 v249, s[8:9]
	s_add_u32 m0, s12, 0x4800
	v_mfma_f32_16x16x32_bf16 v[40:43], v[72:75], v[104:107], v[40:43]
	global_load_lds_dwordx4 v250, s[8:9]
	s_add_u32 m0, s12, 0x4c00
	v_mfma_f32_16x16x32_bf16 v[44:47], v[72:75], v[108:111], v[44:47]
	global_load_lds_dwordx4 v251, s[8:9]
	s_add_u32 m0, s12, 0xc000
	v_mfma_f32_16x16x32_bf16 v[48:51], v[76:79], v[96:99], v[48:51]
	global_load_lds_dwordx4 v248, s[10:11] sc1
	s_add_u32 m0, s12, 0xc400
	v_mfma_f32_16x16x32_bf16 v[52:55], v[76:79], v[100:103], v[52:55]
	global_load_lds_dwordx4 v249, s[10:11] sc1
	s_add_u32 m0, s12, 0xc800
	v_mfma_f32_16x16x32_bf16 v[56:59], v[76:79], v[104:107], v[56:59]
	global_load_lds_dwordx4 v250, s[10:11] sc1
	s_add_u32 m0, s12, 0xcc00
	v_mfma_f32_16x16x32_bf16 v[60:63], v[76:79], v[108:111], v[60:63]
	global_load_lds_dwordx4 v251, s[10:11] sc1
	s_add_u32 s8, s8, 0x80
	s_addc_u32 s9, s9, 0
	s_add_u32 s10, s10, 0x80
	s_addc_u32 s11, s11, 0
	s_mov_b32 s13, 14

.Lr25_tile:
	s_cmp_lt_u32 s15, 0x200
	s_cbranch_scc0 .Lr25_end
	s_and_b32 s2, s15, 63
	s_lshr_b32 s3, s15, 6
	s_mul_i32 s14, s2, 0xb0000
	s_add_u32 s8, s26, s14
	s_addc_u32 s9, s27, 0
	s_mul_i32 s14, s3, 0xb0000
	s_add_u32 s10, s28, s14
	s_addc_u32 s11, s29, 0
	s_lshl_b32 s14, s2, 19
	s_lshl_b32 s6, s3, 9
	s_add_u32 s14, s14, s6
	s_add_u32 s20, s4, 0x6b7a100
	s_addc_u32 s21, s5, 0
	s_add_u32 s20, s20, s14
	s_addc_u32 s21, s21, 0
	s_sub_u32 s7, s2, 32
	s_lshr_b32 s7, s7, 3
	s_add_u32 s7, s7, 1
	s_cmp_lt_u32 s2, 32
	s_cselect_b32 s7, 0, s7
	s_mul_i32 s7, s7, 0x6000
	s_add_u32 s7, s7, s6
	s_add_u32 s22, s4, 0x6b43000
	s_addc_u32 s23, s5, 0
	s_add_u32 s22, s22, s7
	s_addc_u32 s23, s23, 0
	v_readfirstlane_b32 s12, v247
	s_lshl_b32 s12, s12, 12
	s_add_u32 m0, s12, 0x0
	v_mov_b32_e32 v0, 0
	global_load_lds_dwordx4 v248, s[8:9]
	v_mov_b32_e32 v1, 0
	s_add_u32 m0, s12, 0x400
	v_mov_b32_e32 v2, 0
	global_load_lds_dwordx4 v249, s[8:9]
	v_mov_b32_e32 v3, 0
	s_add_u32 m0, s12, 0x800
	v_mov_b32_e32 v4, 0
	global_load_lds_dwordx4 v250, s[8:9]
	v_mov_b32_e32 v5, 0
	s_add_u32 m0, s12, 0xc00
	v_mov_b32_e32 v6, 0
	global_load_lds_dwordx4 v251, s[8:9]
	v_mov_b32_e32 v7, 0
	s_add_u32 m0, s12, 0x8000
	v_mov_b32_e32 v8, 0
	global_load_lds_dwordx4 v248, s[10:11] sc1
	v_mov_b32_e32 v9, 0
	s_add_u32 m0, s12, 0x8400
	v_mov_b32_e32 v10, 0
	global_load_lds_dwordx4 v249, s[10:11] sc1
	v_mov_b32_e32 v11, 0
	s_add_u32 m0, s12, 0x8800
	v_mov_b32_e32 v12, 0
	global_load_lds_dwordx4 v250, s[10:11] sc1
	v_mov_b32_e32 v13, 0
	s_add_u32 m0, s12, 0x8c00
	v_mov_b32_e32 v14, 0
	global_load_lds_dwordx4 v251, s[10:11] sc1
	v_mov_b32_e32 v15, 0
	s_add_u32 s8, s8, 0x80
	s_addc_u32 s9, s9, 0
	s_add_u32 s10, s10, 0x80
	s_addc_u32 s11, s11, 0
	s_add_u32 m0, s12, 0x4000
	v_mov_b32_e32 v16, 0
	global_load_lds_dwordx4 v248, s[8:9]
	v_mov_b32_e32 v17, 0
	s_add_u32 m0, s12, 0x4400
	v_mov_b32_e32 v18, 0
	global_load_lds_dwordx4 v249, s[8:9]
	v_mov_b32_e32 v19, 0
	s_add_u32 m0, s12, 0x4800
	v_mov_b32_e32 v20, 0
	global_load_lds_dwordx4 v250, s[8:9]
	v_mov_b32_e32 v21, 0
	s_add_u32 m0, s12, 0x4c00
	v_mov_b32_e32 v22, 0
	global_load_lds_dwordx4 v251, s[8:9]
	v_mov_b32_e32 v23, 0
	s_add_u32 m0, s12, 0xc000
	v_mov_b32_e32 v24, 0
	global_load_lds_dwordx4 v248, s[10:11] sc1
	v_mov_b32_e32 v25, 0
	s_add_u32 m0, s12, 0xc400
	v_mov_b32_e32 v26, 0
	global_load_lds_dwordx4 v249, s[10:11] sc1
	v_mov_b32_e32 v27, 0
	s_add_u32 m0, s12, 0xc800
	v_mov_b32_e32 v28, 0
	global_load_lds_dwordx4 v250, s[10:11] sc1
	v_mov_b32_e32 v29, 0
	s_add_u32 m0, s12, 0xcc00
	v_mov_b32_e32 v30, 0
	global_load_lds_dwordx4 v251, s[10:11] sc1
	v_mov_b32_e32 v31, 0
	s_add_u32 s8, s8, 0x80
	s_addc_u32 s9, s9, 0
	s_add_u32 s10, s10, 0x80
	s_addc_u32 s11, s11, 0
	v_mov_b32_e32 v32, 0
	v_mov_b32_e32 v33, 0
	v_mov_b32_e32 v34, 0
	v_mov_b32_e32 v35, 0
	v_mov_b32_e32 v36, 0
	v_mov_b32_e32 v37, 0
	v_mov_b32_e32 v38, 0
	v_mov_b32_e32 v39, 0
	v_mov_b32_e32 v40, 0
	v_mov_b32_e32 v41, 0
	v_mov_b32_e32 v42, 0
	v_mov_b32_e32 v43, 0
	v_mov_b32_e32 v44, 0
	v_mov_b32_e32 v45, 0
	v_mov_b32_e32 v46, 0
	v_mov_b32_e32 v47, 0
	v_mov_b32_e32 v48, 0
	v_mov_b32_e32 v49, 0
	v_mov_b32_e32 v50, 0
	v_mov_b32_e32 v51, 0
	v_mov_b32_e32 v52, 0
	v_mov_b32_e32 v53, 0
	v_mov_b32_e32 v54, 0
	v_mov_b32_e32 v55, 0
	v_mov_b32_e32 v56, 0
	v_mov_b32_e32 v57, 0
	v_mov_b32_e32 v58, 0
	v_mov_b32_e32 v59, 0
	v_mov_b32_e32 v60, 0
	v_mov_b32_e32 v61, 0
	v_mov_b32_e32 v62, 0
	v_mov_b32_e32 v63, 0
	global_load_dword v201, v245, s[22:23] offset:0
	global_load_dword v202, v245, s[22:23] offset:64
	global_load_dword v203, v245, s[22:23] offset:128
	global_load_dword v204, v245, s[22:23] offset:192
	s_mov_b64 s[18:19], s[20:21]
	global_load_dword v129, v246, s[18:19] offset:0
	global_load_dword v130, v246, s[18:19] offset:64
	global_load_dword v131, v246, s[18:19] offset:128
	global_load_dword v132, v246, s[18:19] offset:192
	s_add_u32 s18, s18, 0x1000
	s_addc_u32 s19, s19, 0
	global_load_dword v133, v246, s[18:19] offset:0
	global_load_dword v134, v246, s[18:19] offset:64
	global_load_dword v135, v246, s[18:19] offset:128
	global_load_dword v136, v246, s[18:19] offset:192
	s_add_u32 s18, s18, 0x1000
	s_addc_u32 s19, s19, 0
	global_load_dword v137, v246, s[18:19] offset:0
	global_load_dword v138, v246, s[18:19] offset:64
	global_load_dword v139, v246, s[18:19] offset:128
	global_load_dword v140, v246, s[18:19] offset:192
	s_add_u32 s18, s18, 0x1000
	s_addc_u32 s19, s19, 0
	global_load_dword v141, v246, s[18:19] offset:0
	global_load_dword v142, v246, s[18:19] offset:64
	global_load_dword v143, v246, s[18:19] offset:128
	global_load_dword v144, v246, s[18:19] offset:192
	s_add_u32 s18, s18, 0xd000
	s_addc_u32 s19, s19, 0
	global_load_dword v145, v246, s[18:19] offset:0
	global_load_dword v146, v246, s[18:19] offset:64
	global_load_dword v147, v246, s[18:19] offset:128
	global_load_dword v148, v246, s[18:19] offset:192
	s_add_u32 s18, s18, 0x1000
	s_addc_u32 s19, s19, 0
	global_load_dword v149, v246, s[18:19] offset:0
	global_load_dword v150, v246, s[18:19] offset:64
	global_load_dword v151, v246, s[18:19] offset:128
	global_load_dword v152, v246, s[18:19] offset:192
	s_add_u32 s18, s18, 0x1000
	s_addc_u32 s19, s19, 0
	global_load_dword v153, v246, s[18:19] offset:0
	global_load_dword v154, v246, s[18:19] offset:64
	global_load_dword v155, v246, s[18:19] offset:128
	global_load_dword v156, v246, s[18:19] offset:192
	s_add_u32 s18, s18, 0x1000
	s_addc_u32 s19, s19, 0
	global_load_dword v157, v246, s[18:19] offset:0
	global_load_dword v158, v246, s[18:19] offset:64
	global_load_dword v159, v246, s[18:19] offset:128
	global_load_dword v160, v246, s[18:19] offset:192
	s_add_u32 s18, s18, 0xd000
	s_addc_u32 s19, s19, 0
	global_load_dword v161, v246, s[18:19] offset:0
	global_load_dword v170, v246, s[18:19] offset:64
	global_load_dword v171, v246, s[18:19] offset:128
	global_load_dword v172, v246, s[18:19] offset:192
	s_add_u32 s18, s18, 0x1000
	s_addc_u32 s19, s19, 0
	global_load_dword v173, v246, s[18:19] offset:0
	global_load_dword v174, v246, s[18:19] offset:64
	global_load_dword v175, v246, s[18:19] offset:128
	global_load_dword v176, v246, s[18:19] offset:192
	s_add_u32 s18, s18, 0x1000
	s_addc_u32 s19, s19, 0
	global_load_dword v177, v246, s[18:19] offset:0
	global_load_dword v178, v246, s[18:19] offset:64
	global_load_dword v179, v246, s[18:19] offset:128
	global_load_dword v180, v246, s[18:19] offset:192
	s_add_u32 s18, s18, 0x1000
	s_addc_u32 s19, s19, 0
	global_load_dword v181, v246, s[18:19] offset:0
	global_load_dword v182, v246, s[18:19] offset:64
	global_load_dword v183, v246, s[18:19] offset:128
	global_load_dword v184, v246, s[18:19] offset:192
	s_add_u32 s18, s18, 0xd000
	s_addc_u32 s19, s19, 0
	global_load_dword v185, v246, s[18:19] offset:0
	global_load_dword v186, v246, s[18:19] offset:64
	global_load_dword v187, v246, s[18:19] offset:128
	global_load_dword v188, v246, s[18:19] offset:192
	s_add_u32 s18, s18, 0x1000
	s_addc_u32 s19, s19, 0
	global_load_dword v189, v246, s[18:19] offset:0
	global_load_dword v190, v246, s[18:19] offset:64
	global_load_dword v191, v246, s[18:19] offset:128
	global_load_dword v192, v246, s[18:19] offset:192
	s_add_u32 s18, s18, 0x1000
	s_addc_u32 s19, s19, 0
	global_load_dword v193, v246, s[18:19] offset:0
	global_load_dword v194, v246, s[18:19] offset:64
	global_load_dword v195, v246, s[18:19] offset:128
	global_load_dword v196, v246, s[18:19] offset:192
	s_add_u32 s18, s18, 0x1000
	s_addc_u32 s19, s19, 0
	global_load_dword v197, v246, s[18:19] offset:0
	global_load_dword v198, v246, s[18:19] offset:64
	global_load_dword v199, v246, s[18:19] offset:128
	global_load_dword v200, v246, s[18:19] offset:192
	s_waitcnt vmcnt(63)
	s_barrier
	ds_read_b128 v[64:67], v252 offset:0
	ds_read_b128 v[96:99], v254 offset:32768
	ds_read_b128 v[100:103], v254 offset:34816
	ds_read_b128 v[104:107], v254 offset:36864
	ds_read_b128 v[108:111], v254 offset:38912
	ds_read_b128 v[68:71], v252 offset:2048
	ds_read_b128 v[72:75], v252 offset:4096
	ds_read_b128 v[76:79], v252 offset:6144
	ds_read_b128 v[80:83], v253 offset:0
	ds_read_b128 v[112:115], v255 offset:32768
	ds_read_b128 v[116:119], v255 offset:34816
	ds_read_b128 v[120:123], v255 offset:36864
	ds_read_b128 v[124:127], v255 offset:38912
	s_waitcnt lgkmcnt(11)
	v_mfma_f32_16x16x32_bf16 v[0:3], v[64:67], v[96:99], v[0:3]
	s_waitcnt lgkmcnt(10)
	v_mfma_f32_16x16x32_bf16 v[4:7], v[64:67], v[100:103], v[4:7]
	s_waitcnt lgkmcnt(9)
	v_mfma_f32_16x16x32_bf16 v[8:11], v[64:67], v[104:107], v[8:11]
	s_waitcnt lgkmcnt(8)
	v_mfma_f32_16x16x32_bf16 v[12:15], v[64:67], v[108:111], v[12:15]
	ds_read_b128 v[84:87], v253 offset:2048
	ds_read_b128 v[88:91], v253 offset:4096
	ds_read_b128 v[92:95], v253 offset:6144
	s_waitcnt lgkmcnt(10)
	v_mfma_f32_16x16x32_bf16 v[16:19], v[68:71], v[96:99], v[16:19]
	v_mfma_f32_16x16x32_bf16 v[20:23], v[68:71], v[100:103], v[20:23]
	v_mfma_f32_16x16x32_bf16 v[24:27], v[68:71], v[104:107], v[24:27]
	v_mfma_f32_16x16x32_bf16 v[28:31], v[68:71], v[108:111], v[28:31]
	s_waitcnt lgkmcnt(0)
	s_barrier
	s_add_u32 m0, s12, 0x0
	v_mfma_f32_16x16x32_bf16 v[32:35], v[72:75], v[96:99], v[32:35]
	global_load_lds_dwordx4 v248, s[8:9]
	s_add_u32 m0, s12, 0x400
	v_mfma_f32_16x16x32_bf16 v[36:39], v[72:75], v[100:103], v[36:39]
	global_load_lds_dwordx4 v249, s[8:9]
	s_add_u32 m0, s12, 0x800
	v_mfma_f32_16x16x32_bf16 v[40:43], v[72:75], v[104:107], v[40:43]
	global_load_lds_dwordx4 v250, s[8:9]
	s_add_u32 m0, s12, 0xc00
	v_mfma_f32_16x16x32_bf16 v[44:47], v[72:75], v[108:111], v[44:47]
	global_load_lds_dwordx4 v251, s[8:9]
	s_add_u32 m0, s12, 0x8000
	v_mfma_f32_16x16x32_bf16 v[48:51], v[76:79], v[96:99], v[48:51]
	global_load_lds_dwordx4 v248, s[10:11] sc1
	s_add_u32 m0, s12, 0x8400
	v_mfma_f32_16x16x32_bf16 v[52:55], v[76:79], v[100:103], v[52:55]
	global_load_lds_dwordx4 v249, s[10:11] sc1
	s_add_u32 m0, s12, 0x8800
	v_mfma_f32_16x16x32_bf16 v[56:59], v[76:79], v[104:107], v[56:59]
	global_load_lds_dwordx4 v250, s[10:11] sc1
	s_add_u32 m0, s12, 0x8c00
	v_mfma_f32_16x16x32_bf16 v[60:63], v[76:79], v[108:111], v[60:63]
	global_load_lds_dwordx4 v251, s[10:11] sc1
	s_add_u32 s8, s8, 0x80
	s_addc_u32 s9, s9, 0
	s_add_u32 s10, s10, 0x80
	s_addc_u32 s11, s11, 0
	s_waitcnt vmcnt(63)
	s_barrier
	ds_read_b128 v[64:67], v252 offset:16384
	ds_read_b128 v[96:99], v254 offset:49152
	ds_read_b128 v[100:103], v254 offset:51200
	ds_read_b128 v[104:107], v254 offset:53248
	ds_read_b128 v[108:111], v254 offset:55296
	ds_read_b128 v[68:71], v252 offset:18432
	ds_read_b128 v[72:75], v252 offset:20480
	ds_read_b128 v[76:79], v252 offset:22528
	v_mfma_f32_16x16x32_bf16 v[0:3], v[80:83], v[112:115], v[0:3]
	v_mfma_f32_16x16x32_bf16 v[4:7], v[80:83], v[116:119], v[4:7]
	v_mfma_f32_16x16x32_bf16 v[8:11], v[80:83], v[120:123], v[8:11]
	v_mfma_f32_16x16x32_bf16 v[12:15], v[80:83], v[124:127], v[12:15]
	v_mfma_f32_16x16x32_bf16 v[16:19], v[84:87], v[112:115], v[16:19]
	v_mfma_f32_16x16x32_bf16 v[20:23], v[84:87], v[116:119], v[20:23]
	v_mfma_f32_16x16x32_bf16 v[24:27], v[84:87], v[120:123], v[24:27]
	v_mfma_f32_16x16x32_bf16 v[28:31], v[84:87], v[124:127], v[28:31]
	v_mfma_f32_16x16x32_bf16 v[32:35], v[88:91], v[112:115], v[32:35]
	v_mfma_f32_16x16x32_bf16 v[36:39], v[88:91], v[116:119], v[36:39]
	v_mfma_f32_16x16x32_bf16 v[40:43], v[88:91], v[120:123], v[40:43]
	v_mfma_f32_16x16x32_bf16 v[44:47], v[88:91], v[124:127], v[44:47]
	v_mfma_f32_16x16x32_bf16 v[48:51], v[92:95], v[112:115], v[48:51]
	v_mfma_f32_16x16x32_bf16 v[52:55], v[92:95], v[116:119], v[52:55]
	v_mfma_f32_16x16x32_bf16 v[56:59], v[92:95], v[120:123], v[56:59]
	v_mfma_f32_16x16x32_bf16 v[60:63], v[92:95], v[124:127], v[60:63]
	ds_read_b128 v[80:83], v253 offset:16384
	ds_read_b128 v[112:115], v255 offset:49152
	ds_read_b128 v[116:119], v255 offset:51200
	ds_read_b128 v[120:123], v255 offset:53248
	ds_read_b128 v[124:127], v255 offset:55296
	ds_read_b128 v[84:87], v253 offset:18432
	ds_read_b128 v[88:91], v253 offset:20480
	ds_read_b128 v[92:95], v253 offset:22528
	s_waitcnt lgkmcnt(14)
	v_mfma_f32_16x16x32_bf16 v[0:3], v[64:67], v[96:99], v[0:3]
	s_waitcnt lgkmcnt(13)
	v_mfma_f32_16x16x32_bf16 v[4:7], v[64:67], v[100:103], v[4:7]
	s_waitcnt lgkmcnt(12)
	v_mfma_f32_16x16x32_bf16 v[8:11], v[64:67], v[104:107], v[8:11]
	s_waitcnt lgkmcnt(11)
	v_mfma_f32_16x16x32_bf16 v[12:15], v[64:67], v[108:111], v[12:15]
	s_waitcnt lgkmcnt(10)
	v_mfma_f32_16x16x32_bf16 v[16:19], v[68:71], v[96:99], v[16:19]
	v_mfma_f32_16x16x32_bf16 v[20:23], v[68:71], v[100:103], v[20:23]
	v_mfma_f32_16x16x32_bf16 v[24:27], v[68:71], v[104:107], v[24:27]
	v_mfma_f32_16x16x32_bf16 v[28:31], v[68:71], v[108:111], v[28:31]
	s_waitcnt lgkmcnt(0)
	s_barrier
	s_add_u32 m0, s12, 0x4000
	v_mfma_f32_16x16x32_bf16 v[32:35], v[72:75], v[96:99], v[32:35]
	global_load_lds_dwordx4 v248, s[8:9]
	s_add_u32 m0, s12, 0x4400
	v_mfma_f32_16x16x32_bf16 v[36:39], v[72:75], v[100:103], v[36:39]
	global_load_lds_dwordx4 v249, s[8:9]
	s_add_u32 m0, s12, 0x4800
	v_mfma_f32_16x16x32_bf16 v[40:43], v[72:75], v[104:107], v[40:43]
	global_load_lds_dwordx4 v250, s[8:9]
	s_add_u32 m0, s12, 0x4c00
	v_mfma_f32_16x16x32_bf16 v[44:47], v[72:75], v[108:111], v[44:47]
	global_load_lds_dwordx4 v251, s[8:9]
	s_add_u32 m0, s12, 0xc000
	v_mfma_f32_16x16x32_bf16 v[48:51], v[76:79], v[96:99], v[48:51]
	global_load_lds_dwordx4 v248, s[10:11] sc1
	s_add_u32 m0, s12, 0xc400
	v_mfma_f32_16x16x32_bf16 v[52:55], v[76:79], v[100:103], v[52:55]
	global_load_lds_dwordx4 v249, s[10:11] sc1
	s_add_u32 m0, s12, 0xc800
	v_mfma_f32_16x16x32_bf16 v[56:59], v[76:79], v[104:107], v[56:59]
	global_load_lds_dwordx4 v250, s[10:11] sc1
	s_add_u32 m0, s12, 0xcc00
	v_mfma_f32_16x16x32_bf16 v[60:63], v[76:79], v[108:111], v[60:63]
	global_load_lds_dwordx4 v251, s[10:11] sc1
	s_add_u32 s8, s8, 0x80
	s_addc_u32 s9, s9, 0
	s_add_u32 s10, s10, 0x80
	s_addc_u32 s11, s11, 0
	s_mov_b32 s13, 20

.Lr29_tile:
	s_cmp_lt_u32 s15, 0x200
	s_cbranch_scc0 .Lr29_end
	s_and_b32 s2, s15, 63
	s_lshr_b32 s3, s15, 6
	s_mul_i32 s14, s2, 0x40000
	s_add_u32 s8, s26, s14
	s_addc_u32 s9, s27, 0
	s_mul_i32 s14, s3, 0x40000
	s_add_u32 s10, s28, s14
	s_addc_u32 s11, s29, 0
	s_lshl_b32 s14, s2, 19
	s_lshl_b32 s6, s3, 9
	s_add_u32 s14, s14, s6
	s_add_u32 s20, s4, 0x6b7a100
	s_addc_u32 s21, s5, 0
	s_add_u32 s20, s20, s14
	s_addc_u32 s21, s21, 0
	s_sub_u32 s7, s2, 32
	s_lshr_b32 s7, s7, 3
	s_add_u32 s7, s7, 1
	s_cmp_lt_u32 s2, 32
	s_cselect_b32 s7, 0, s7
	s_mul_i32 s7, s7, 0x6000
	s_add_u32 s7, s7, s6
	s_add_u32 s22, s4, 0x6b5e000
	s_addc_u32 s23, s5, 0
	s_add_u32 s22, s22, s7
	s_addc_u32 s23, s23, 0
	s_add_u32 s30, s24, 0x1000
	s_addc_u32 s31, s25, 0
	s_add_u32 s30, s30, s6
	s_addc_u32 s31, s31, 0
	v_readfirstlane_b32 s12, v247
	s_lshl_b32 s12, s12, 12
	s_add_u32 m0, s12, 0x0
	v_mov_b32_e32 v0, 0
	global_load_lds_dwordx4 v248, s[8:9]
	v_mov_b32_e32 v1, 0
	s_add_u32 m0, s12, 0x400
	v_mov_b32_e32 v2, 0
	global_load_lds_dwordx4 v249, s[8:9]
	v_mov_b32_e32 v3, 0
	s_add_u32 m0, s12, 0x800
	v_mov_b32_e32 v4, 0
	global_load_lds_dwordx4 v250, s[8:9]
	v_mov_b32_e32 v5, 0
	s_add_u32 m0, s12, 0xc00
	v_mov_b32_e32 v6, 0
	global_load_lds_dwordx4 v251, s[8:9]
	v_mov_b32_e32 v7, 0
	s_add_u32 m0, s12, 0x8000
	v_mov_b32_e32 v8, 0
	global_load_lds_dwordx4 v248, s[10:11] sc1
	v_mov_b32_e32 v9, 0
	s_add_u32 m0, s12, 0x8400
	v_mov_b32_e32 v10, 0
	global_load_lds_dwordx4 v249, s[10:11] sc1
	v_mov_b32_e32 v11, 0
	s_add_u32 m0, s12, 0x8800
	v_mov_b32_e32 v12, 0
	global_load_lds_dwordx4 v250, s[10:11] sc1
	v_mov_b32_e32 v13, 0
	s_add_u32 m0, s12, 0x8c00
	v_mov_b32_e32 v14, 0
	global_load_lds_dwordx4 v251, s[10:11] sc1
	v_mov_b32_e32 v15, 0
	s_add_u32 s8, s8, 0x80
	s_addc_u32 s9, s9, 0
	s_add_u32 s10, s10, 0x80
	s_addc_u32 s11, s11, 0
	s_add_u32 m0, s12, 0x4000
	v_mov_b32_e32 v16, 0
	global_load_lds_dwordx4 v248, s[8:9]
	v_mov_b32_e32 v17, 0
	s_add_u32 m0, s12, 0x4400
	v_mov_b32_e32 v18, 0
	global_load_lds_dwordx4 v249, s[8:9]
	v_mov_b32_e32 v19, 0
	s_add_u32 m0, s12, 0x4800
	v_mov_b32_e32 v20, 0
	global_load_lds_dwordx4 v250, s[8:9]
	v_mov_b32_e32 v21, 0
	s_add_u32 m0, s12, 0x4c00
	v_mov_b32_e32 v22, 0
	global_load_lds_dwordx4 v251, s[8:9]
	v_mov_b32_e32 v23, 0
	s_add_u32 m0, s12, 0xc000
	v_mov_b32_e32 v24, 0
	global_load_lds_dwordx4 v248, s[10:11] sc1
	v_mov_b32_e32 v25, 0
	s_add_u32 m0, s12, 0xc400
	v_mov_b32_e32 v26, 0
	global_load_lds_dwordx4 v249, s[10:11] sc1
	v_mov_b32_e32 v27, 0
	s_add_u32 m0, s12, 0xc800
	v_mov_b32_e32 v28, 0
	global_load_lds_dwordx4 v250, s[10:11] sc1
	v_mov_b32_e32 v29, 0
	s_add_u32 m0, s12, 0xcc00
	v_mov_b32_e32 v30, 0
	global_load_lds_dwordx4 v251, s[10:11] sc1
	v_mov_b32_e32 v31, 0
	s_add_u32 s8, s8, 0x80
	s_addc_u32 s9, s9, 0
	s_add_u32 s10, s10, 0x80
	s_addc_u32 s11, s11, 0
	v_mov_b32_e32 v32, 0
	v_mov_b32_e32 v33, 0
	v_mov_b32_e32 v34, 0
	v_mov_b32_e32 v35, 0
	v_mov_b32_e32 v36, 0
	v_mov_b32_e32 v37, 0
	v_mov_b32_e32 v38, 0
	v_mov_b32_e32 v39, 0
	v_mov_b32_e32 v40, 0
	v_mov_b32_e32 v41, 0
	v_mov_b32_e32 v42, 0
	v_mov_b32_e32 v43, 0
	v_mov_b32_e32 v44, 0
	v_mov_b32_e32 v45, 0
	v_mov_b32_e32 v46, 0
	v_mov_b32_e32 v47, 0
	v_mov_b32_e32 v48, 0
	v_mov_b32_e32 v49, 0
	v_mov_b32_e32 v50, 0
	v_mov_b32_e32 v51, 0
	v_mov_b32_e32 v52, 0
	v_mov_b32_e32 v53, 0
	v_mov_b32_e32 v54, 0
	v_mov_b32_e32 v55, 0
	v_mov_b32_e32 v56, 0
	v_mov_b32_e32 v57, 0
	v_mov_b32_e32 v58, 0
	v_mov_b32_e32 v59, 0
	v_mov_b32_e32 v60, 0
	v_mov_b32_e32 v61, 0
	v_mov_b32_e32 v62, 0
	v_mov_b32_e32 v63, 0
	global_load_dword v201, v245, s[22:23] offset:0
	global_load_dword v202, v245, s[22:23] offset:64
	global_load_dword v203, v245, s[22:23] offset:128
	global_load_dword v204, v245, s[22:23] offset:192
	global_load_dword v205, v245, s[30:31] offset:0
	global_load_dword v206, v245, s[30:31] offset:64
	global_load_dword v207, v245, s[30:31] offset:128
	global_load_dword v208, v245, s[30:31] offset:192
	s_mov_b64 s[18:19], s[20:21]
	global_load_dword v129, v246, s[18:19] offset:0
	global_load_dword v130, v246, s[18:19] offset:64
	global_load_dword v131, v246, s[18:19] offset:128
	global_load_dword v132, v246, s[18:19] offset:192
	s_add_u32 s18, s18, 0x1000
	s_addc_u32 s19, s19, 0
	global_load_dword v133, v246, s[18:19] offset:0
	global_load_dword v134, v246, s[18:19] offset:64
	global_load_dword v135, v246, s[18:19] offset:128
	global_load_dword v136, v246, s[18:19] offset:192
	s_add_u32 s18, s18, 0x1000
	s_addc_u32 s19, s19, 0
	global_load_dword v137, v246, s[18:19] offset:0
	global_load_dword v138, v246, s[18:19] offset:64
	global_load_dword v139, v246, s[18:19] offset:128
	global_load_dword v140, v246, s[18:19] offset:192
	s_add_u32 s18, s18, 0x1000
	s_addc_u32 s19, s19, 0
	global_load_dword v141, v246, s[18:19] offset:0
	global_load_dword v142, v246, s[18:19] offset:64
	global_load_dword v143, v246, s[18:19] offset:128
	global_load_dword v144, v246, s[18:19] offset:192
	s_add_u32 s18, s18, 0xd000
	s_addc_u32 s19, s19, 0
	global_load_dword v145, v246, s[18:19] offset:0
	global_load_dword v146, v246, s[18:19] offset:64
	global_load_dword v147, v246, s[18:19] offset:128
	global_load_dword v148, v246, s[18:19] offset:192
	s_add_u32 s18, s18, 0x1000
	s_addc_u32 s19, s19, 0
	global_load_dword v149, v246, s[18:19] offset:0
	global_load_dword v150, v246, s[18:19] offset:64
	global_load_dword v151, v246, s[18:19] offset:128
	global_load_dword v152, v246, s[18:19] offset:192
	s_add_u32 s18, s18, 0x1000
	s_addc_u32 s19, s19, 0
	global_load_dword v153, v246, s[18:19] offset:0
	global_load_dword v154, v246, s[18:19] offset:64
	global_load_dword v155, v246, s[18:19] offset:128
	global_load_dword v156, v246, s[18:19] offset:192
	s_add_u32 s18, s18, 0x1000
	s_addc_u32 s19, s19, 0
	global_load_dword v157, v246, s[18:19] offset:0
	global_load_dword v158, v246, s[18:19] offset:64
	global_load_dword v159, v246, s[18:19] offset:128
	global_load_dword v160, v246, s[18:19] offset:192
	s_add_u32 s18, s18, 0xd000
	s_addc_u32 s19, s19, 0
	global_load_dword v161, v246, s[18:19] offset:0
	global_load_dword v170, v246, s[18:19] offset:64
	global_load_dword v171, v246, s[18:19] offset:128
	global_load_dword v172, v246, s[18:19] offset:192
	s_add_u32 s18, s18, 0x1000
	s_addc_u32 s19, s19, 0
	global_load_dword v173, v246, s[18:19] offset:0
	global_load_dword v174, v246, s[18:19] offset:64
	global_load_dword v175, v246, s[18:19] offset:128
	global_load_dword v176, v246, s[18:19] offset:192
	s_add_u32 s18, s18, 0x1000
	s_addc_u32 s19, s19, 0
	global_load_dword v177, v246, s[18:19] offset:0
	global_load_dword v178, v246, s[18:19] offset:64
	global_load_dword v179, v246, s[18:19] offset:128
	global_load_dword v180, v246, s[18:19] offset:192
	s_add_u32 s18, s18, 0x1000
	s_addc_u32 s19, s19, 0
	global_load_dword v181, v246, s[18:19] offset:0
	global_load_dword v182, v246, s[18:19] offset:64
	global_load_dword v183, v246, s[18:19] offset:128
	global_load_dword v184, v246, s[18:19] offset:192
	s_add_u32 s18, s18, 0xd000
	s_addc_u32 s19, s19, 0
	global_load_dword v185, v246, s[18:19] offset:0
	global_load_dword v186, v246, s[18:19] offset:64
	global_load_dword v187, v246, s[18:19] offset:128
	global_load_dword v188, v246, s[18:19] offset:192
	s_add_u32 s18, s18, 0x1000
	s_addc_u32 s19, s19, 0
	global_load_dword v189, v246, s[18:19] offset:0
	global_load_dword v190, v246, s[18:19] offset:64
	global_load_dword v191, v246, s[18:19] offset:128
	global_load_dword v192, v246, s[18:19] offset:192
	s_add_u32 s18, s18, 0x1000
	s_addc_u32 s19, s19, 0
	global_load_dword v193, v246, s[18:19] offset:0
	global_load_dword v194, v246, s[18:19] offset:64
	global_load_dword v195, v246, s[18:19] offset:128
	global_load_dword v196, v246, s[18:19] offset:192
	s_add_u32 s18, s18, 0x1000
	s_addc_u32 s19, s19, 0
	global_load_dword v197, v246, s[18:19] offset:0
	global_load_dword v198, v246, s[18:19] offset:64
	global_load_dword v199, v246, s[18:19] offset:128
	global_load_dword v200, v246, s[18:19] offset:192
	s_waitcnt vmcnt(63)
	s_barrier
	ds_read_b128 v[64:67], v252 offset:0
	ds_read_b128 v[96:99], v254 offset:32768
	ds_read_b128 v[100:103], v254 offset:34816
	ds_read_b128 v[104:107], v254 offset:36864
	ds_read_b128 v[108:111], v254 offset:38912
	ds_read_b128 v[68:71], v252 offset:2048
	ds_read_b128 v[72:75], v252 offset:4096
	ds_read_b128 v[76:79], v252 offset:6144
	ds_read_b128 v[80:83], v253 offset:0
	ds_read_b128 v[112:115], v255 offset:32768
	ds_read_b128 v[116:119], v255 offset:34816
	ds_read_b128 v[120:123], v255 offset:36864
	ds_read_b128 v[124:127], v255 offset:38912
	s_waitcnt lgkmcnt(11)
	v_mfma_f32_16x16x32_bf16 v[0:3], v[64:67], v[96:99], v[0:3]
	s_waitcnt lgkmcnt(10)
	v_mfma_f32_16x16x32_bf16 v[4:7], v[64:67], v[100:103], v[4:7]
	s_waitcnt lgkmcnt(9)
	v_mfma_f32_16x16x32_bf16 v[8:11], v[64:67], v[104:107], v[8:11]
	s_waitcnt lgkmcnt(8)
	v_mfma_f32_16x16x32_bf16 v[12:15], v[64:67], v[108:111], v[12:15]
	ds_read_b128 v[84:87], v253 offset:2048
	ds_read_b128 v[88:91], v253 offset:4096
	ds_read_b128 v[92:95], v253 offset:6144
	s_waitcnt lgkmcnt(10)
	v_mfma_f32_16x16x32_bf16 v[16:19], v[68:71], v[96:99], v[16:19]
	v_mfma_f32_16x16x32_bf16 v[20:23], v[68:71], v[100:103], v[20:23]
	v_mfma_f32_16x16x32_bf16 v[24:27], v[68:71], v[104:107], v[24:27]
	v_mfma_f32_16x16x32_bf16 v[28:31], v[68:71], v[108:111], v[28:31]
	s_waitcnt lgkmcnt(0)
	s_barrier
	s_add_u32 m0, s12, 0x0
	v_mfma_f32_16x16x32_bf16 v[32:35], v[72:75], v[96:99], v[32:35]
	global_load_lds_dwordx4 v248, s[8:9]
	s_add_u32 m0, s12, 0x400
	v_mfma_f32_16x16x32_bf16 v[36:39], v[72:75], v[100:103], v[36:39]
	global_load_lds_dwordx4 v249, s[8:9]
	s_add_u32 m0, s12, 0x800
	v_mfma_f32_16x16x32_bf16 v[40:43], v[72:75], v[104:107], v[40:43]
	global_load_lds_dwordx4 v250, s[8:9]
	s_add_u32 m0, s12, 0xc00
	v_mfma_f32_16x16x32_bf16 v[44:47], v[72:75], v[108:111], v[44:47]
	global_load_lds_dwordx4 v251, s[8:9]
	s_add_u32 m0, s12, 0x8000
	v_mfma_f32_16x16x32_bf16 v[48:51], v[76:79], v[96:99], v[48:51]
	global_load_lds_dwordx4 v248, s[10:11] sc1
	s_add_u32 m0, s12, 0x8400
	v_mfma_f32_16x16x32_bf16 v[52:55], v[76:79], v[100:103], v[52:55]
	global_load_lds_dwordx4 v249, s[10:11] sc1
	s_add_u32 m0, s12, 0x8800
	v_mfma_f32_16x16x32_bf16 v[56:59], v[76:79], v[104:107], v[56:59]
	global_load_lds_dwordx4 v250, s[10:11] sc1
	s_add_u32 m0, s12, 0x8c00
	v_mfma_f32_16x16x32_bf16 v[60:63], v[76:79], v[108:111], v[60:63]
	global_load_lds_dwordx4 v251, s[10:11] sc1
	s_add_u32 s8, s8, 0x80
	s_addc_u32 s9, s9, 0
	s_add_u32 s10, s10, 0x80
	s_addc_u32 s11, s11, 0
	s_waitcnt vmcnt(63)
	s_barrier
	ds_read_b128 v[64:67], v252 offset:16384
	ds_read_b128 v[96:99], v254 offset:49152
	ds_read_b128 v[100:103], v254 offset:51200
	ds_read_b128 v[104:107], v254 offset:53248
	ds_read_b128 v[108:111], v254 offset:55296
	ds_read_b128 v[68:71], v252 offset:18432
	ds_read_b128 v[72:75], v252 offset:20480
	ds_read_b128 v[76:79], v252 offset:22528
	v_mfma_f32_16x16x32_bf16 v[0:3], v[80:83], v[112:115], v[0:3]
	v_mfma_f32_16x16x32_bf16 v[4:7], v[80:83], v[116:119], v[4:7]
	v_mfma_f32_16x16x32_bf16 v[8:11], v[80:83], v[120:123], v[8:11]
	v_mfma_f32_16x16x32_bf16 v[12:15], v[80:83], v[124:127], v[12:15]
	v_mfma_f32_16x16x32_bf16 v[16:19], v[84:87], v[112:115], v[16:19]
	v_mfma_f32_16x16x32_bf16 v[20:23], v[84:87], v[116:119], v[20:23]
	v_mfma_f32_16x16x32_bf16 v[24:27], v[84:87], v[120:123], v[24:27]
	v_mfma_f32_16x16x32_bf16 v[28:31], v[84:87], v[124:127], v[28:31]
	v_mfma_f32_16x16x32_bf16 v[32:35], v[88:91], v[112:115], v[32:35]
	v_mfma_f32_16x16x32_bf16 v[36:39], v[88:91], v[116:119], v[36:39]
	v_mfma_f32_16x16x32_bf16 v[40:43], v[88:91], v[120:123], v[40:43]
	v_mfma_f32_16x16x32_bf16 v[44:47], v[88:91], v[124:127], v[44:47]
	v_mfma_f32_16x16x32_bf16 v[48:51], v[92:95], v[112:115], v[48:51]
	v_mfma_f32_16x16x32_bf16 v[52:55], v[92:95], v[116:119], v[52:55]
	v_mfma_f32_16x16x32_bf16 v[56:59], v[92:95], v[120:123], v[56:59]
	v_mfma_f32_16x16x32_bf16 v[60:63], v[92:95], v[124:127], v[60:63]
	ds_read_b128 v[80:83], v253 offset:16384
	ds_read_b128 v[112:115], v255 offset:49152
	ds_read_b128 v[116:119], v255 offset:51200
	ds_read_b128 v[120:123], v255 offset:53248
	ds_read_b128 v[124:127], v255 offset:55296
	ds_read_b128 v[84:87], v253 offset:18432
	ds_read_b128 v[88:91], v253 offset:20480
	ds_read_b128 v[92:95], v253 offset:22528
	s_waitcnt lgkmcnt(14)
	v_mfma_f32_16x16x32_bf16 v[0:3], v[64:67], v[96:99], v[0:3]
	s_waitcnt lgkmcnt(13)
	v_mfma_f32_16x16x32_bf16 v[4:7], v[64:67], v[100:103], v[4:7]
	s_waitcnt lgkmcnt(12)
	v_mfma_f32_16x16x32_bf16 v[8:11], v[64:67], v[104:107], v[8:11]
	s_waitcnt lgkmcnt(11)
	v_mfma_f32_16x16x32_bf16 v[12:15], v[64:67], v[108:111], v[12:15]
	s_waitcnt lgkmcnt(10)
	v_mfma_f32_16x16x32_bf16 v[16:19], v[68:71], v[96:99], v[16:19]
	v_mfma_f32_16x16x32_bf16 v[20:23], v[68:71], v[100:103], v[20:23]
	v_mfma_f32_16x16x32_bf16 v[24:27], v[68:71], v[104:107], v[24:27]
	v_mfma_f32_16x16x32_bf16 v[28:31], v[68:71], v[108:111], v[28:31]
	s_waitcnt lgkmcnt(0)
	s_barrier
	s_add_u32 m0, s12, 0x4000
	v_mfma_f32_16x16x32_bf16 v[32:35], v[72:75], v[96:99], v[32:35]
	global_load_lds_dwordx4 v248, s[8:9]
	s_add_u32 m0, s12, 0x4400
	v_mfma_f32_16x16x32_bf16 v[36:39], v[72:75], v[100:103], v[36:39]
	global_load_lds_dwordx4 v249, s[8:9]
	s_add_u32 m0, s12, 0x4800
	v_mfma_f32_16x16x32_bf16 v[40:43], v[72:75], v[104:107], v[40:43]
	global_load_lds_dwordx4 v250, s[8:9]
	s_add_u32 m0, s12, 0x4c00
	v_mfma_f32_16x16x32_bf16 v[44:47], v[72:75], v[108:111], v[44:47]
	global_load_lds_dwordx4 v251, s[8:9]
	s_add_u32 m0, s12, 0xc000
	v_mfma_f32_16x16x32_bf16 v[48:51], v[76:79], v[96:99], v[48:51]
	global_load_lds_dwordx4 v248, s[10:11] sc1
	s_add_u32 m0, s12, 0xc400
	v_mfma_f32_16x16x32_bf16 v[52:55], v[76:79], v[100:103], v[52:55]
	global_load_lds_dwordx4 v249, s[10:11] sc1
	s_add_u32 m0, s12, 0xc800
	v_mfma_f32_16x16x32_bf16 v[56:59], v[76:79], v[104:107], v[56:59]
	global_load_lds_dwordx4 v250, s[10:11] sc1
	s_add_u32 m0, s12, 0xcc00
	v_mfma_f32_16x16x32_bf16 v[60:63], v[76:79], v[108:111], v[60:63]
	global_load_lds_dwordx4 v251, s[10:11] sc1
	s_add_u32 s8, s8, 0x80
	s_addc_u32 s9, s9, 0
	s_add_u32 s10, s10, 0x80
	s_addc_u32 s11, s11, 0
	s_mov_b32 s13, 6

.Lr32_tile:
	s_cmp_lt_u32 s15, 0x200
	s_cbranch_scc0 .Lr32_end
	s_and_b32 s2, s15, 63
	s_lshr_b32 s3, s15, 6
	s_mul_i32 s14, s2, 0xb0000
	s_add_u32 s8, s26, s14
	s_addc_u32 s9, s27, 0
	s_mul_i32 s14, s3, 0xb0000
	s_add_u32 s10, s28, s14
	s_addc_u32 s11, s29, 0
	s_lshl_b32 s14, s2, 19
	s_lshl_b32 s6, s3, 9
	s_add_u32 s14, s14, s6
	s_add_u32 s20, s4, 0x6b7a100
	s_addc_u32 s21, s5, 0
	s_add_u32 s20, s20, s14
	s_addc_u32 s21, s21, 0
	s_sub_u32 s7, s2, 32
	s_lshr_b32 s7, s7, 3
	s_add_u32 s7, s7, 1
	s_cmp_lt_u32 s2, 32
	s_cselect_b32 s7, 0, s7
	s_mul_i32 s7, s7, 0x6000
	s_add_u32 s7, s7, s6
	s_add_u32 s22, s4, 0x6b61000
	s_addc_u32 s23, s5, 0
	s_add_u32 s22, s22, s7
	s_addc_u32 s23, s23, 0
	v_readfirstlane_b32 s12, v247
	s_lshl_b32 s12, s12, 12
	s_add_u32 m0, s12, 0x0
	v_mov_b32_e32 v0, 0
	global_load_lds_dwordx4 v248, s[8:9]
	v_mov_b32_e32 v1, 0
	s_add_u32 m0, s12, 0x400
	v_mov_b32_e32 v2, 0
	global_load_lds_dwordx4 v249, s[8:9]
	v_mov_b32_e32 v3, 0
	s_add_u32 m0, s12, 0x800
	v_mov_b32_e32 v4, 0
	global_load_lds_dwordx4 v250, s[8:9]
	v_mov_b32_e32 v5, 0
	s_add_u32 m0, s12, 0xc00
	v_mov_b32_e32 v6, 0
	global_load_lds_dwordx4 v251, s[8:9]
	v_mov_b32_e32 v7, 0
	s_add_u32 m0, s12, 0x8000
	v_mov_b32_e32 v8, 0
	global_load_lds_dwordx4 v248, s[10:11] sc1
	v_mov_b32_e32 v9, 0
	s_add_u32 m0, s12, 0x8400
	v_mov_b32_e32 v10, 0
	global_load_lds_dwordx4 v249, s[10:11] sc1
	v_mov_b32_e32 v11, 0
	s_add_u32 m0, s12, 0x8800
	v_mov_b32_e32 v12, 0
	global_load_lds_dwordx4 v250, s[10:11] sc1
	v_mov_b32_e32 v13, 0
	s_add_u32 m0, s12, 0x8c00
	v_mov_b32_e32 v14, 0
	global_load_lds_dwordx4 v251, s[10:11] sc1
	v_mov_b32_e32 v15, 0
	s_add_u32 s8, s8, 0x80
	s_addc_u32 s9, s9, 0
	s_add_u32 s10, s10, 0x80
	s_addc_u32 s11, s11, 0
	s_add_u32 m0, s12, 0x4000
	v_mov_b32_e32 v16, 0
	global_load_lds_dwordx4 v248, s[8:9]
	v_mov_b32_e32 v17, 0
	s_add_u32 m0, s12, 0x4400
	v_mov_b32_e32 v18, 0
	global_load_lds_dwordx4 v249, s[8:9]
	v_mov_b32_e32 v19, 0
	s_add_u32 m0, s12, 0x4800
	v_mov_b32_e32 v20, 0
	global_load_lds_dwordx4 v250, s[8:9]
	v_mov_b32_e32 v21, 0
	s_add_u32 m0, s12, 0x4c00
	v_mov_b32_e32 v22, 0
	global_load_lds_dwordx4 v251, s[8:9]
	v_mov_b32_e32 v23, 0
	s_add_u32 m0, s12, 0xc000
	v_mov_b32_e32 v24, 0
	global_load_lds_dwordx4 v248, s[10:11] sc1
	v_mov_b32_e32 v25, 0
	s_add_u32 m0, s12, 0xc400
	v_mov_b32_e32 v26, 0
	global_load_lds_dwordx4 v249, s[10:11] sc1
	v_mov_b32_e32 v27, 0
	s_add_u32 m0, s12, 0xc800
	v_mov_b32_e32 v28, 0
	global_load_lds_dwordx4 v250, s[10:11] sc1
	v_mov_b32_e32 v29, 0
	s_add_u32 m0, s12, 0xcc00
	v_mov_b32_e32 v30, 0
	global_load_lds_dwordx4 v251, s[10:11] sc1
	v_mov_b32_e32 v31, 0
	s_add_u32 s8, s8, 0x80
	s_addc_u32 s9, s9, 0
	s_add_u32 s10, s10, 0x80
	s_addc_u32 s11, s11, 0
	v_mov_b32_e32 v32, 0
	v_mov_b32_e32 v33, 0
	v_mov_b32_e32 v34, 0
	v_mov_b32_e32 v35, 0
	v_mov_b32_e32 v36, 0
	v_mov_b32_e32 v37, 0
	v_mov_b32_e32 v38, 0
	v_mov_b32_e32 v39, 0
	v_mov_b32_e32 v40, 0
	v_mov_b32_e32 v41, 0
	v_mov_b32_e32 v42, 0
	v_mov_b32_e32 v43, 0
	v_mov_b32_e32 v44, 0
	v_mov_b32_e32 v45, 0
	v_mov_b32_e32 v46, 0
	v_mov_b32_e32 v47, 0
	v_mov_b32_e32 v48, 0
	v_mov_b32_e32 v49, 0
	v_mov_b32_e32 v50, 0
	v_mov_b32_e32 v51, 0
	v_mov_b32_e32 v52, 0
	v_mov_b32_e32 v53, 0
	v_mov_b32_e32 v54, 0
	v_mov_b32_e32 v55, 0
	v_mov_b32_e32 v56, 0
	v_mov_b32_e32 v57, 0
	v_mov_b32_e32 v58, 0
	v_mov_b32_e32 v59, 0
	v_mov_b32_e32 v60, 0
	v_mov_b32_e32 v61, 0
	v_mov_b32_e32 v62, 0
	v_mov_b32_e32 v63, 0
	global_load_dword v201, v245, s[22:23] offset:0
	global_load_dword v202, v245, s[22:23] offset:64
	global_load_dword v203, v245, s[22:23] offset:128
	global_load_dword v204, v245, s[22:23] offset:192
	s_mov_b64 s[18:19], s[20:21]
	global_load_dword v129, v246, s[18:19] offset:0
	global_load_dword v130, v246, s[18:19] offset:64
	global_load_dword v131, v246, s[18:19] offset:128
	global_load_dword v132, v246, s[18:19] offset:192
	s_add_u32 s18, s18, 0x1000
	s_addc_u32 s19, s19, 0
	global_load_dword v133, v246, s[18:19] offset:0
	global_load_dword v134, v246, s[18:19] offset:64
	global_load_dword v135, v246, s[18:19] offset:128
	global_load_dword v136, v246, s[18:19] offset:192
	s_add_u32 s18, s18, 0x1000
	s_addc_u32 s19, s19, 0
	global_load_dword v137, v246, s[18:19] offset:0
	global_load_dword v138, v246, s[18:19] offset:64
	global_load_dword v139, v246, s[18:19] offset:128
	global_load_dword v140, v246, s[18:19] offset:192
	s_add_u32 s18, s18, 0x1000
	s_addc_u32 s19, s19, 0
	global_load_dword v141, v246, s[18:19] offset:0
	global_load_dword v142, v246, s[18:19] offset:64
	global_load_dword v143, v246, s[18:19] offset:128
	global_load_dword v144, v246, s[18:19] offset:192
	s_add_u32 s18, s18, 0xd000
	s_addc_u32 s19, s19, 0
	global_load_dword v145, v246, s[18:19] offset:0
	global_load_dword v146, v246, s[18:19] offset:64
	global_load_dword v147, v246, s[18:19] offset:128
	global_load_dword v148, v246, s[18:19] offset:192
	s_add_u32 s18, s18, 0x1000
	s_addc_u32 s19, s19, 0
	global_load_dword v149, v246, s[18:19] offset:0
	global_load_dword v150, v246, s[18:19] offset:64
	global_load_dword v151, v246, s[18:19] offset:128
	global_load_dword v152, v246, s[18:19] offset:192
	s_add_u32 s18, s18, 0x1000
	s_addc_u32 s19, s19, 0
	global_load_dword v153, v246, s[18:19] offset:0
	global_load_dword v154, v246, s[18:19] offset:64
	global_load_dword v155, v246, s[18:19] offset:128
	global_load_dword v156, v246, s[18:19] offset:192
	s_add_u32 s18, s18, 0x1000
	s_addc_u32 s19, s19, 0
	global_load_dword v157, v246, s[18:19] offset:0
	global_load_dword v158, v246, s[18:19] offset:64
	global_load_dword v159, v246, s[18:19] offset:128
	global_load_dword v160, v246, s[18:19] offset:192
	s_add_u32 s18, s18, 0xd000
	s_addc_u32 s19, s19, 0
	global_load_dword v161, v246, s[18:19] offset:0
	global_load_dword v170, v246, s[18:19] offset:64
	global_load_dword v171, v246, s[18:19] offset:128
	global_load_dword v172, v246, s[18:19] offset:192
	s_add_u32 s18, s18, 0x1000
	s_addc_u32 s19, s19, 0
	global_load_dword v173, v246, s[18:19] offset:0
	global_load_dword v174, v246, s[18:19] offset:64
	global_load_dword v175, v246, s[18:19] offset:128
	global_load_dword v176, v246, s[18:19] offset:192
	s_add_u32 s18, s18, 0x1000
	s_addc_u32 s19, s19, 0
	global_load_dword v177, v246, s[18:19] offset:0
	global_load_dword v178, v246, s[18:19] offset:64
	global_load_dword v179, v246, s[18:19] offset:128
	global_load_dword v180, v246, s[18:19] offset:192
	s_add_u32 s18, s18, 0x1000
	s_addc_u32 s19, s19, 0
	global_load_dword v181, v246, s[18:19] offset:0
	global_load_dword v182, v246, s[18:19] offset:64
	global_load_dword v183, v246, s[18:19] offset:128
	global_load_dword v184, v246, s[18:19] offset:192
	s_add_u32 s18, s18, 0xd000
	s_addc_u32 s19, s19, 0
	global_load_dword v185, v246, s[18:19] offset:0
	global_load_dword v186, v246, s[18:19] offset:64
	global_load_dword v187, v246, s[18:19] offset:128
	global_load_dword v188, v246, s[18:19] offset:192
	s_add_u32 s18, s18, 0x1000
	s_addc_u32 s19, s19, 0
	global_load_dword v189, v246, s[18:19] offset:0
	global_load_dword v190, v246, s[18:19] offset:64
	global_load_dword v191, v246, s[18:19] offset:128
	global_load_dword v192, v246, s[18:19] offset:192
	s_add_u32 s18, s18, 0x1000
	s_addc_u32 s19, s19, 0
	global_load_dword v193, v246, s[18:19] offset:0
	global_load_dword v194, v246, s[18:19] offset:64
	global_load_dword v195, v246, s[18:19] offset:128
	global_load_dword v196, v246, s[18:19] offset:192
	s_add_u32 s18, s18, 0x1000
	s_addc_u32 s19, s19, 0
	global_load_dword v197, v246, s[18:19] offset:0
	global_load_dword v198, v246, s[18:19] offset:64
	global_load_dword v199, v246, s[18:19] offset:128
	global_load_dword v200, v246, s[18:19] offset:192
	s_waitcnt vmcnt(63)
	s_barrier
	ds_read_b128 v[64:67], v252 offset:0
	ds_read_b128 v[96:99], v254 offset:32768
	ds_read_b128 v[100:103], v254 offset:34816
	ds_read_b128 v[104:107], v254 offset:36864
	ds_read_b128 v[108:111], v254 offset:38912
	ds_read_b128 v[68:71], v252 offset:2048
	ds_read_b128 v[72:75], v252 offset:4096
	ds_read_b128 v[76:79], v252 offset:6144
	ds_read_b128 v[80:83], v253 offset:0
	ds_read_b128 v[112:115], v255 offset:32768
	ds_read_b128 v[116:119], v255 offset:34816
	ds_read_b128 v[120:123], v255 offset:36864
	ds_read_b128 v[124:127], v255 offset:38912
	s_waitcnt lgkmcnt(11)
	v_mfma_f32_16x16x32_bf16 v[0:3], v[64:67], v[96:99], v[0:3]
	s_waitcnt lgkmcnt(10)
	v_mfma_f32_16x16x32_bf16 v[4:7], v[64:67], v[100:103], v[4:7]
	s_waitcnt lgkmcnt(9)
	v_mfma_f32_16x16x32_bf16 v[8:11], v[64:67], v[104:107], v[8:11]
	s_waitcnt lgkmcnt(8)
	v_mfma_f32_16x16x32_bf16 v[12:15], v[64:67], v[108:111], v[12:15]
	ds_read_b128 v[84:87], v253 offset:2048
	ds_read_b128 v[88:91], v253 offset:4096
	ds_read_b128 v[92:95], v253 offset:6144
	s_waitcnt lgkmcnt(10)
	v_mfma_f32_16x16x32_bf16 v[16:19], v[68:71], v[96:99], v[16:19]
	v_mfma_f32_16x16x32_bf16 v[20:23], v[68:71], v[100:103], v[20:23]
	v_mfma_f32_16x16x32_bf16 v[24:27], v[68:71], v[104:107], v[24:27]
	v_mfma_f32_16x16x32_bf16 v[28:31], v[68:71], v[108:111], v[28:31]
	s_waitcnt lgkmcnt(0)
	s_barrier
	s_add_u32 m0, s12, 0x0
	v_mfma_f32_16x16x32_bf16 v[32:35], v[72:75], v[96:99], v[32:35]
	global_load_lds_dwordx4 v248, s[8:9]
	s_add_u32 m0, s12, 0x400
	v_mfma_f32_16x16x32_bf16 v[36:39], v[72:75], v[100:103], v[36:39]
	global_load_lds_dwordx4 v249, s[8:9]
	s_add_u32 m0, s12, 0x800
	v_mfma_f32_16x16x32_bf16 v[40:43], v[72:75], v[104:107], v[40:43]
	global_load_lds_dwordx4 v250, s[8:9]
	s_add_u32 m0, s12, 0xc00
	v_mfma_f32_16x16x32_bf16 v[44:47], v[72:75], v[108:111], v[44:47]
	global_load_lds_dwordx4 v251, s[8:9]
	s_add_u32 m0, s12, 0x8000
	v_mfma_f32_16x16x32_bf16 v[48:51], v[76:79], v[96:99], v[48:51]
	global_load_lds_dwordx4 v248, s[10:11] sc1
	s_add_u32 m0, s12, 0x8400
	v_mfma_f32_16x16x32_bf16 v[52:55], v[76:79], v[100:103], v[52:55]
	global_load_lds_dwordx4 v249, s[10:11] sc1
	s_add_u32 m0, s12, 0x8800
	v_mfma_f32_16x16x32_bf16 v[56:59], v[76:79], v[104:107], v[56:59]
	global_load_lds_dwordx4 v250, s[10:11] sc1
	s_add_u32 m0, s12, 0x8c00
	v_mfma_f32_16x16x32_bf16 v[60:63], v[76:79], v[108:111], v[60:63]
	global_load_lds_dwordx4 v251, s[10:11] sc1
	s_add_u32 s8, s8, 0x80
	s_addc_u32 s9, s9, 0
	s_add_u32 s10, s10, 0x80
	s_addc_u32 s11, s11, 0
	s_waitcnt vmcnt(63)
	s_barrier
	ds_read_b128 v[64:67], v252 offset:16384
	ds_read_b128 v[96:99], v254 offset:49152
	ds_read_b128 v[100:103], v254 offset:51200
	ds_read_b128 v[104:107], v254 offset:53248
	ds_read_b128 v[108:111], v254 offset:55296
	ds_read_b128 v[68:71], v252 offset:18432
	ds_read_b128 v[72:75], v252 offset:20480
	ds_read_b128 v[76:79], v252 offset:22528
	v_mfma_f32_16x16x32_bf16 v[0:3], v[80:83], v[112:115], v[0:3]
	v_mfma_f32_16x16x32_bf16 v[4:7], v[80:83], v[116:119], v[4:7]
	v_mfma_f32_16x16x32_bf16 v[8:11], v[80:83], v[120:123], v[8:11]
	v_mfma_f32_16x16x32_bf16 v[12:15], v[80:83], v[124:127], v[12:15]
	v_mfma_f32_16x16x32_bf16 v[16:19], v[84:87], v[112:115], v[16:19]
	v_mfma_f32_16x16x32_bf16 v[20:23], v[84:87], v[116:119], v[20:23]
	v_mfma_f32_16x16x32_bf16 v[24:27], v[84:87], v[120:123], v[24:27]
	v_mfma_f32_16x16x32_bf16 v[28:31], v[84:87], v[124:127], v[28:31]
	v_mfma_f32_16x16x32_bf16 v[32:35], v[88:91], v[112:115], v[32:35]
	v_mfma_f32_16x16x32_bf16 v[36:39], v[88:91], v[116:119], v[36:39]
	v_mfma_f32_16x16x32_bf16 v[40:43], v[88:91], v[120:123], v[40:43]
	v_mfma_f32_16x16x32_bf16 v[44:47], v[88:91], v[124:127], v[44:47]
	v_mfma_f32_16x16x32_bf16 v[48:51], v[92:95], v[112:115], v[48:51]
	v_mfma_f32_16x16x32_bf16 v[52:55], v[92:95], v[116:119], v[52:55]
	v_mfma_f32_16x16x32_bf16 v[56:59], v[92:95], v[120:123], v[56:59]
	v_mfma_f32_16x16x32_bf16 v[60:63], v[92:95], v[124:127], v[60:63]
	ds_read_b128 v[80:83], v253 offset:16384
	ds_read_b128 v[112:115], v255 offset:49152
	ds_read_b128 v[116:119], v255 offset:51200
	ds_read_b128 v[120:123], v255 offset:53248
	ds_read_b128 v[124:127], v255 offset:55296
	ds_read_b128 v[84:87], v253 offset:18432
	ds_read_b128 v[88:91], v253 offset:20480
	ds_read_b128 v[92:95], v253 offset:22528
	s_waitcnt lgkmcnt(14)
	v_mfma_f32_16x16x32_bf16 v[0:3], v[64:67], v[96:99], v[0:3]
	s_waitcnt lgkmcnt(13)
	v_mfma_f32_16x16x32_bf16 v[4:7], v[64:67], v[100:103], v[4:7]
	s_waitcnt lgkmcnt(12)
	v_mfma_f32_16x16x32_bf16 v[8:11], v[64:67], v[104:107], v[8:11]
	s_waitcnt lgkmcnt(11)
	v_mfma_f32_16x16x32_bf16 v[12:15], v[64:67], v[108:111], v[12:15]
	s_waitcnt lgkmcnt(10)
	v_mfma_f32_16x16x32_bf16 v[16:19], v[68:71], v[96:99], v[16:19]
	v_mfma_f32_16x16x32_bf16 v[20:23], v[68:71], v[100:103], v[20:23]
	v_mfma_f32_16x16x32_bf16 v[24:27], v[68:71], v[104:107], v[24:27]
	v_mfma_f32_16x16x32_bf16 v[28:31], v[68:71], v[108:111], v[28:31]
	s_waitcnt lgkmcnt(0)
	s_barrier
	s_add_u32 m0, s12, 0x4000
	v_mfma_f32_16x16x32_bf16 v[32:35], v[72:75], v[96:99], v[32:35]
	global_load_lds_dwordx4 v248, s[8:9]
	s_add_u32 m0, s12, 0x4400
	v_mfma_f32_16x16x32_bf16 v[36:39], v[72:75], v[100:103], v[36:39]
	global_load_lds_dwordx4 v249, s[8:9]
	s_add_u32 m0, s12, 0x4800
	v_mfma_f32_16x16x32_bf16 v[40:43], v[72:75], v[104:107], v[40:43]
	global_load_lds_dwordx4 v250, s[8:9]
	s_add_u32 m0, s12, 0x4c00
	v_mfma_f32_16x16x32_bf16 v[44:47], v[72:75], v[108:111], v[44:47]
	global_load_lds_dwordx4 v251, s[8:9]
	s_add_u32 m0, s12, 0xc000
	v_mfma_f32_16x16x32_bf16 v[48:51], v[76:79], v[96:99], v[48:51]
	global_load_lds_dwordx4 v248, s[10:11] sc1
	s_add_u32 m0, s12, 0xc400
	v_mfma_f32_16x16x32_bf16 v[52:55], v[76:79], v[100:103], v[52:55]
	global_load_lds_dwordx4 v249, s[10:11] sc1
	s_add_u32 m0, s12, 0xc800
	v_mfma_f32_16x16x32_bf16 v[56:59], v[76:79], v[104:107], v[56:59]
	global_load_lds_dwordx4 v250, s[10:11] sc1
	s_add_u32 m0, s12, 0xcc00
	v_mfma_f32_16x16x32_bf16 v[60:63], v[76:79], v[108:111], v[60:63]
	global_load_lds_dwordx4 v251, s[10:11] sc1
	s_add_u32 s8, s8, 0x80
	s_addc_u32 s9, s9, 0
	s_add_u32 s10, s10, 0x80
	s_addc_u32 s11, s11, 0
	s_mov_b32 s13, 20
